# prep1: kdT 2-byte scattered stores packed in registers into 16-byte stores (8 steps per store), v218-226 parked in LDS during the loop
# speedup vs baseline: 1.0255x; 1.0095x over previous
.LBB0_760:
	v_mov_b64_e32 v[146:147], s[34:35]
	v_mad_i64_i32 v[146:147], s[14:15], v4, s27, v[146:147]
	v_lshl_add_u64 v[146:147], v[146:147], 0, v[2:3]
	v_add_co_u32_e32 v146, vcc, 0x1000, v146
	v_add_u32_e32 v6, 0x100, v6
	s_nop 0
	v_addc_co_u32_e32 v147, vcc, 0, v147, vcc
	global_load_ushort v7, v[146:147], off offset:2048
	s_movk_i32 s2, 0x6ff
	v_cmp_lt_u32_e32 vcc, s2, v6
	v_add_u32_e32 v4, 8, v4
	s_or_b64 s[0:1], vcc, s[0:1]
	s_waitcnt vmcnt(0)
	v_lshlrev_b32_e32 v7, 16, v7
	ds_write_b32 v5, v7
	v_add_u32_e32 v5, 0x400, v5
	s_andn2_b64 exec, exec, s[0:1]
	s_cbranch_execnz .LBB0_760
	s_or_b64 exec, exec, s[0:1]
	v_and_b32_e32 v143, 3, v1
	v_or_b32_e32 v4, v142, v13
	v_mov_b64_e32 v[146:147], s[34:35]
	v_mad_i64_i32 v[4:5], s[0:1], v4, s27, v[146:147]
	v_lshlrev_b32_e32 v154, 8, v143
	v_mov_b32_e32 v155, v3
	v_lshl_add_u64 v[4:5], v[4:5], 0, v[154:155]
	v_mov_b32_e32 v141, v3
	v_lshl_add_u64 v[156:157], v[4:5], 0, v[140:141]
	global_load_dwordx4 v[4:7], v[156:157], off
	v_lshlrev_b32_e32 v173, 7, v143
	v_add_u32_e32 v1, s3, v1
	s_waitcnt vmcnt(0)
	ds_write_b128 v15, v[4:7]
	global_load_dwordx4 v[4:7], v[156:157], off offset:1024
	s_waitcnt vmcnt(0)
	ds_write_b128 v17, v[4:7]
	v_or_b32_e32 v4, v142, v19
	v_mad_i64_i32 v[4:5], s[0:1], v4, s27, v[146:147]
	v_lshl_add_u64 v[4:5], v[4:5], 0, v[154:155]
	v_lshl_add_u64 v[156:157], v[4:5], 0, v[140:141]
	global_load_dwordx4 v[4:7], v[156:157], off
	s_waitcnt vmcnt(0)
	ds_write_b128 v21, v[4:7]
	global_load_dwordx4 v[4:7], v[156:157], off offset:1024
	s_waitcnt vmcnt(0)
	ds_write_b128 v23, v[4:7]
	v_or_b32_e32 v4, v142, v25
	v_mad_i64_i32 v[4:5], s[0:1], v4, s27, v[146:147]
	v_lshl_add_u64 v[4:5], v[4:5], 0, v[154:155]
	v_lshl_add_u64 v[156:157], v[4:5], 0, v[140:141]
	global_load_dwordx4 v[4:7], v[156:157], off
	s_waitcnt vmcnt(0)
	ds_write_b128 v27, v[4:7]
	global_load_dwordx4 v[4:7], v[156:157], off offset:1024
	s_waitcnt vmcnt(0)
	ds_write_b128 v29, v[4:7]
	v_or_b32_e32 v4, v142, v31
	v_mad_i64_i32 v[4:5], s[0:1], v4, s27, v[146:147]
	v_lshl_add_u64 v[4:5], v[4:5], 0, v[154:155]
	v_lshl_add_u64 v[146:147], v[4:5], 0, v[140:141]
	global_load_dwordx4 v[4:7], v[146:147], off
	s_movk_i32 s0, 0x1000
	v_or_b32_e32 v141, v173, v39
	v_lshlrev_b32_e32 v141, 2, v141
	s_waitcnt vmcnt(0)
	ds_write_b128 v33, v[4:7]
	global_load_dwordx4 v[4:7], v[146:147], off offset:1024
	s_waitcnt vmcnt(0)
	ds_write_b128 v35, v[4:7]
	v_or_b32_e32 v4, v173, v37
	v_lshlrev_b32_e32 v6, 2, v4
	v_mov_b32_e32 v7, v3
	v_lshl_add_u64 v[158:159], s[8:9], 0, v[6:7]
	v_add_co_u32_e32 v146, vcc, s0, v158
	s_movk_i32 s0, 0x2000
	s_nop 0
	v_addc_co_u32_e32 v147, vcc, 0, v159, vcc
	v_add_co_u32_e32 v154, vcc, s0, v158
	s_movk_i32 s0, 0x3000
	s_nop 0
	v_addc_co_u32_e32 v155, vcc, 0, v159, vcc
	s_waitcnt lgkmcnt(0)
	s_barrier
	global_load_dword v4, v6, s[8:9]
	global_load_dword v5, v6, s[8:9] offset:2048
	s_nop 0
	global_load_dword v6, v[154:155], off offset:-4096
	global_load_dword v7, v[146:147], off offset:2048
	global_load_dword v228, v[154:155], off
	s_nop 0
	global_load_dword v154, v[154:155], off offset:2048
	v_add_co_u32_e32 v146, vcc, s0, v158
	s_movk_i32 s0, 0x5000
	s_nop 0
	v_addc_co_u32_e32 v147, vcc, 0, v159, vcc
	v_add_co_u32_e32 v160, vcc, s17, v158
	s_nop 1
	v_addc_co_u32_e32 v161, vcc, 0, v159, vcc
	global_load_dword v155, v[160:161], off offset:-4096
	global_load_dword v156, v[146:147], off offset:2048
	s_nop 0
	global_load_dword v146, v[160:161], off
	global_load_dword v252, v[160:161], off offset:2048
	v_add_co_u32_e32 v160, vcc, s0, v158
	s_movk_i32 s0, 0x7000
	s_nop 0
	v_addc_co_u32_e32 v161, vcc, 0, v159, vcc
	v_add_co_u32_e32 v174, vcc, s62, v158
	s_nop 1
	v_addc_co_u32_e32 v175, vcc, 0, v159, vcc
	v_add_co_u32_e32 v158, vcc, s0, v158
	global_load_dword v253, v[174:175], off offset:-4096
	global_load_dword v227, v[160:161], off offset:2048
	global_load_dword v145, v[174:175], off
	global_load_dword v147, v[174:175], off offset:2048
	v_addc_co_u32_e32 v159, vcc, 0, v159, vcc
	global_load_dword v230, v[158:159], off
	global_load_dword v231, v[158:159], off offset:2048
	global_load_dword v157, v141, s[10:11]
	ds_read_b128 v[174:177], v9
	ds_read_b128 v[178:181], v9 offset:16
	ds_read_b128 v[182:185], v9 offset:32
	ds_read_b128 v[186:189], v9 offset:48
	ds_read_b128 v[212:215], v9 offset:4480
	ds_read_b128 v[234:237], v9 offset:4992
	s_waitcnt vmcnt(15) lgkmcnt(5)
	v_mul_f32_e32 v141, v5, v175
	v_fmac_f32_e32 v141, v4, v174
	s_waitcnt vmcnt(11) lgkmcnt(4)
	v_mul_f32_e32 v158, v154, v179
	v_fmac_f32_e32 v141, v6, v176
	v_fmac_f32_e32 v158, v228, v178
	v_fmac_f32_e32 v141, v7, v177
	ds_read_b128 v[174:177], v9 offset:128
	s_waitcnt vmcnt(10)
	v_fmac_f32_e32 v158, v155, v180
	s_waitcnt vmcnt(9)
	v_fmac_f32_e32 v158, v156, v181
	s_waitcnt vmcnt(0)
	v_add_f32_e32 v141, v157, v141
	v_add_f32_e32 v141, v141, v158
	s_waitcnt lgkmcnt(4)
	v_mul_f32_e32 v158, v252, v183
	v_fmac_f32_e32 v158, v146, v182
	v_fmac_f32_e32 v158, v253, v184
	v_fmac_f32_e32 v158, v227, v185
	v_add_f32_e32 v141, v141, v158
	s_waitcnt lgkmcnt(3)
	v_mul_f32_e32 v158, v147, v187
	v_fmac_f32_e32 v158, v145, v186
	v_fmac_f32_e32 v158, v230, v188
	v_fmac_f32_e32 v158, v231, v189
	v_add_f32_e32 v141, v141, v158
	v_min_f32_e32 v158, 0, v141
	v_mul_f32_e64 v141, |v141|, s18
	v_exp_f32_e32 v141, v141
	s_nop 0
	v_add_f32_e32 v141, 1.0, v141
	v_cmp_gt_f32_e32 vcc, s71, v141
	s_nop 1
	v_cndmask_b32_e64 v159, 0, 32, vcc
	v_ldexp_f32 v141, v141, v159
	v_log_f32_e32 v141, v141
	s_nop 0
	v_mul_f32_e32 v159, 0x3f317217, v141
	v_fma_f32 v159, v141, s48, -v159
	v_fmac_f32_e32 v159, 0x3377d1cf, v141
	v_fmac_f32_e32 v159, 0x3f317217, v141
	v_cmp_lt_f32_e64 s[0:1], |v141|, s49
	s_nop 1
	v_cndmask_b32_e64 v141, v141, v159, s[0:1]
	v_cndmask_b32_e32 v159, 0, v233, vcc
	v_sub_f32_e32 v141, v141, v159
	v_sub_f32_e32 v141, v158, v141
	s_waitcnt lgkmcnt(0)
	v_mul_f32_e32 v158, v5, v175
	v_fmac_f32_e32 v158, v4, v174
	v_fmac_f32_e32 v158, v6, v176
	v_fmac_f32_e32 v158, v7, v177
	ds_read_b128 v[174:177], v9 offset:144
	v_add_f32_e32 v158, v157, v158
	s_mov_b32 s0, 0x3d800000
	v_mul_f32_e32 v173, 0x3d800000, v141
	v_fma_f32 v141, v141, s0, 0
	s_waitcnt lgkmcnt(0)
	v_mul_f32_e32 v159, v154, v175
	v_fmac_f32_e32 v159, v228, v174
	v_fmac_f32_e32 v159, v155, v176
	v_fmac_f32_e32 v159, v156, v177
	ds_read_b128 v[174:177], v9 offset:160
	v_add_f32_e32 v158, v158, v159
	s_waitcnt lgkmcnt(0)
	v_mul_f32_e32 v159, v252, v175
	v_fmac_f32_e32 v159, v146, v174
	v_fmac_f32_e32 v159, v253, v176
	v_fmac_f32_e32 v159, v227, v177
	ds_read_b128 v[174:177], v9 offset:176
	v_add_f32_e32 v158, v158, v159
	s_waitcnt lgkmcnt(0)
	v_mul_f32_e32 v159, v147, v175
	v_fmac_f32_e32 v159, v145, v174
	v_fmac_f32_e32 v159, v230, v176
	v_fmac_f32_e32 v159, v231, v177
	v_add_f32_e32 v158, v158, v159
	v_min_f32_e32 v159, 0, v158
	v_mul_f32_e64 v158, |v158|, s18
	v_exp_f32_e32 v158, v158
	ds_read_b128 v[176:179], v9 offset:256
	v_add_f32_e32 v158, 1.0, v158
	v_cmp_gt_f32_e32 vcc, s71, v158
	s_nop 1
	v_cndmask_b32_e64 v160, 0, 32, vcc
	v_ldexp_f32 v158, v158, v160
	v_log_f32_e32 v158, v158
	s_nop 0
	v_mul_f32_e32 v160, 0x3f317217, v158
	v_fma_f32 v160, v158, s48, -v160
	v_fmac_f32_e32 v160, 0x3377d1cf, v158
	v_fmac_f32_e32 v160, 0x3f317217, v158
	v_cmp_lt_f32_e64 s[0:1], |v158|, s49
	s_nop 1
	v_cndmask_b32_e64 v158, v158, v160, s[0:1]
	v_cndmask_b32_e32 v160, 0, v233, vcc
	v_sub_f32_e32 v158, v158, v160
	v_sub_f32_e32 v158, v159, v158
	v_mul_f32_e32 v174, 0x3d800000, v158
	v_fmac_f32_e32 v141, 0x3d800000, v158
	s_waitcnt lgkmcnt(0)
	v_mul_f32_e32 v158, v5, v177
	v_fmac_f32_e32 v158, v4, v176
	v_fmac_f32_e32 v158, v6, v178
	v_fmac_f32_e32 v158, v7, v179
	ds_read_b128 v[176:179], v9 offset:272
	v_add_f32_e32 v158, v157, v158
	s_waitcnt lgkmcnt(0)
	v_mul_f32_e32 v159, v154, v177
	v_fmac_f32_e32 v159, v228, v176
	v_fmac_f32_e32 v159, v155, v178
	v_fmac_f32_e32 v159, v156, v179
	ds_read_b128 v[176:179], v9 offset:288
	v_add_f32_e32 v158, v158, v159
	s_waitcnt lgkmcnt(0)
	v_mul_f32_e32 v159, v252, v177
	v_fmac_f32_e32 v159, v146, v176
	v_fmac_f32_e32 v159, v253, v178
	v_fmac_f32_e32 v159, v227, v179
	ds_read_b128 v[176:179], v9 offset:304
	v_add_f32_e32 v158, v158, v159
	s_waitcnt lgkmcnt(0)
	v_mul_f32_e32 v159, v147, v177
	v_fmac_f32_e32 v159, v145, v176
	v_fmac_f32_e32 v159, v230, v178
	v_fmac_f32_e32 v159, v231, v179
	v_add_f32_e32 v158, v158, v159
	v_min_f32_e32 v159, 0, v158
	v_mul_f32_e64 v158, |v158|, s18
	v_exp_f32_e32 v158, v158
	ds_read_b128 v[176:179], v9 offset:384
	v_add_f32_e32 v158, 1.0, v158
	v_cmp_gt_f32_e32 vcc, s71, v158
	s_nop 1
	v_cndmask_b32_e64 v160, 0, 32, vcc
	v_ldexp_f32 v158, v158, v160
	v_log_f32_e32 v158, v158
	s_nop 0
	v_mul_f32_e32 v160, 0x3f317217, v158
	v_fma_f32 v160, v158, s48, -v160
	v_fmac_f32_e32 v160, 0x3377d1cf, v158
	v_fmac_f32_e32 v160, 0x3f317217, v158
	v_cmp_lt_f32_e64 s[0:1], |v158|, s49
	s_nop 1
	v_cndmask_b32_e64 v158, v158, v160, s[0:1]
	v_cndmask_b32_e32 v160, 0, v233, vcc
	v_sub_f32_e32 v158, v158, v160
	v_sub_f32_e32 v158, v159, v158
	v_mul_f32_e32 v175, 0x3d800000, v158
	v_fmac_f32_e32 v141, 0x3d800000, v158
	s_waitcnt lgkmcnt(0)
	v_mul_f32_e32 v158, v5, v177
	v_fmac_f32_e32 v158, v4, v176
	v_fmac_f32_e32 v158, v6, v178
	v_fmac_f32_e32 v158, v7, v179
	ds_read_b128 v[176:179], v9 offset:400
	v_add_f32_e32 v158, v157, v158
	s_waitcnt lgkmcnt(0)
	v_mul_f32_e32 v159, v154, v177
	v_fmac_f32_e32 v159, v228, v176
	v_fmac_f32_e32 v159, v155, v178
	v_fmac_f32_e32 v159, v156, v179
	ds_read_b128 v[176:179], v9 offset:416
	v_add_f32_e32 v158, v158, v159
	s_waitcnt lgkmcnt(0)
	v_mul_f32_e32 v159, v252, v177
	v_fmac_f32_e32 v159, v146, v176
	v_fmac_f32_e32 v159, v253, v178
	v_fmac_f32_e32 v159, v227, v179
	ds_read_b128 v[176:179], v9 offset:432
	v_add_f32_e32 v158, v158, v159
	s_waitcnt lgkmcnt(0)
	v_mul_f32_e32 v159, v147, v177
	v_fmac_f32_e32 v159, v145, v176
	v_fmac_f32_e32 v159, v230, v178
	v_fmac_f32_e32 v159, v231, v179
	v_add_f32_e32 v158, v158, v159
	v_min_f32_e32 v159, 0, v158
	v_mul_f32_e64 v158, |v158|, s18
	v_exp_f32_e32 v158, v158
	ds_read_b128 v[178:181], v9 offset:512
	v_add_f32_e32 v158, 1.0, v158
	v_cmp_gt_f32_e32 vcc, s71, v158
	s_nop 1
	v_cndmask_b32_e64 v160, 0, 32, vcc
	v_ldexp_f32 v158, v158, v160
	v_log_f32_e32 v158, v158
	s_nop 0
	v_mul_f32_e32 v160, 0x3f317217, v158
	v_fma_f32 v160, v158, s48, -v160
	v_fmac_f32_e32 v160, 0x3377d1cf, v158
	v_fmac_f32_e32 v160, 0x3f317217, v158
	v_cmp_lt_f32_e64 s[0:1], |v158|, s49
	s_nop 1
	v_cndmask_b32_e64 v158, v158, v160, s[0:1]
	v_cndmask_b32_e32 v160, 0, v233, vcc
	v_sub_f32_e32 v158, v158, v160
	v_sub_f32_e32 v158, v159, v158
	v_mul_f32_e32 v176, 0x3d800000, v158
	v_fmac_f32_e32 v141, 0x3d800000, v158
	s_waitcnt lgkmcnt(0)
	v_mul_f32_e32 v158, v5, v179
	v_fmac_f32_e32 v158, v4, v178
	v_fmac_f32_e32 v158, v6, v180
	v_fmac_f32_e32 v158, v7, v181
	ds_read_b128 v[178:181], v9 offset:528
	v_add_f32_e32 v158, v157, v158
	s_waitcnt lgkmcnt(0)
	v_mul_f32_e32 v159, v154, v179
	v_fmac_f32_e32 v159, v228, v178
	v_fmac_f32_e32 v159, v155, v180
	v_fmac_f32_e32 v159, v156, v181
	ds_read_b128 v[178:181], v9 offset:544
	v_add_f32_e32 v158, v158, v159
	s_waitcnt lgkmcnt(0)
	v_mul_f32_e32 v159, v252, v179
	v_fmac_f32_e32 v159, v146, v178
	v_fmac_f32_e32 v159, v253, v180
	v_fmac_f32_e32 v159, v227, v181
	ds_read_b128 v[178:181], v9 offset:560
	v_add_f32_e32 v158, v158, v159
	s_waitcnt lgkmcnt(0)
	v_mul_f32_e32 v159, v147, v179
	v_fmac_f32_e32 v159, v145, v178
	v_fmac_f32_e32 v159, v230, v180
	v_fmac_f32_e32 v159, v231, v181
	v_add_f32_e32 v158, v158, v159
	v_min_f32_e32 v159, 0, v158
	v_mul_f32_e64 v158, |v158|, s18
	v_exp_f32_e32 v158, v158
	ds_read_b128 v[178:181], v9 offset:640
	v_add_f32_e32 v158, 1.0, v158
	v_cmp_gt_f32_e32 vcc, s71, v158
	s_nop 1
	v_cndmask_b32_e64 v160, 0, 32, vcc
	v_ldexp_f32 v158, v158, v160
	v_log_f32_e32 v158, v158
	s_nop 0
	v_mul_f32_e32 v160, 0x3f317217, v158
	v_fma_f32 v160, v158, s48, -v160
	v_fmac_f32_e32 v160, 0x3377d1cf, v158
	v_fmac_f32_e32 v160, 0x3f317217, v158
	v_cmp_lt_f32_e64 s[0:1], |v158|, s49
	s_nop 1
	v_cndmask_b32_e64 v158, v158, v160, s[0:1]
	v_cndmask_b32_e32 v160, 0, v233, vcc
	v_sub_f32_e32 v158, v158, v160
	v_sub_f32_e32 v158, v159, v158
	v_mul_f32_e32 v177, 0x3d800000, v158
	v_fmac_f32_e32 v141, 0x3d800000, v158
	s_waitcnt lgkmcnt(0)
	v_mul_f32_e32 v158, v5, v179
	v_fmac_f32_e32 v158, v4, v178
	v_fmac_f32_e32 v158, v6, v180
	v_fmac_f32_e32 v158, v7, v181
	ds_read_b128 v[178:181], v9 offset:656
	v_add_f32_e32 v158, v157, v158
	s_waitcnt lgkmcnt(0)
	v_mul_f32_e32 v159, v154, v179
	v_fmac_f32_e32 v159, v228, v178
	v_fmac_f32_e32 v159, v155, v180
	v_fmac_f32_e32 v159, v156, v181
	ds_read_b128 v[178:181], v9 offset:672
	v_add_f32_e32 v158, v158, v159
	s_waitcnt lgkmcnt(0)
	v_mul_f32_e32 v159, v252, v179
	v_fmac_f32_e32 v159, v146, v178
	v_fmac_f32_e32 v159, v253, v180
	v_fmac_f32_e32 v159, v227, v181
	ds_read_b128 v[178:181], v9 offset:688
	v_add_f32_e32 v158, v158, v159
	s_waitcnt lgkmcnt(0)
	v_mul_f32_e32 v159, v147, v179
	v_fmac_f32_e32 v159, v145, v178
	v_fmac_f32_e32 v159, v230, v180
	v_fmac_f32_e32 v159, v231, v181
	v_add_f32_e32 v158, v158, v159
	v_min_f32_e32 v159, 0, v158
	v_mul_f32_e64 v158, |v158|, s18
	v_exp_f32_e32 v158, v158
	ds_read_b128 v[180:183], v9 offset:768
	v_add_f32_e32 v158, 1.0, v158
	v_cmp_gt_f32_e32 vcc, s71, v158
	s_nop 1
	v_cndmask_b32_e64 v160, 0, 32, vcc
	v_ldexp_f32 v158, v158, v160
	v_log_f32_e32 v158, v158
	s_nop 0
	v_mul_f32_e32 v160, 0x3f317217, v158
	v_fma_f32 v160, v158, s48, -v160
	v_fmac_f32_e32 v160, 0x3377d1cf, v158
	v_fmac_f32_e32 v160, 0x3f317217, v158
	v_cmp_lt_f32_e64 s[0:1], |v158|, s49
	s_nop 1
	v_cndmask_b32_e64 v158, v158, v160, s[0:1]
	v_cndmask_b32_e32 v160, 0, v233, vcc
	v_sub_f32_e32 v158, v158, v160
	v_sub_f32_e32 v158, v159, v158
	v_mul_f32_e32 v178, 0x3d800000, v158
	v_fmac_f32_e32 v141, 0x3d800000, v158
	s_waitcnt lgkmcnt(0)
	v_mul_f32_e32 v158, v5, v181
	v_fmac_f32_e32 v158, v4, v180
	v_fmac_f32_e32 v158, v6, v182
	v_fmac_f32_e32 v158, v7, v183
	ds_read_b128 v[180:183], v9 offset:784
	v_add_f32_e32 v158, v157, v158
	s_waitcnt lgkmcnt(0)
	v_mul_f32_e32 v159, v154, v181
	v_fmac_f32_e32 v159, v228, v180
	v_fmac_f32_e32 v159, v155, v182
	v_fmac_f32_e32 v159, v156, v183
	ds_read_b128 v[180:183], v9 offset:800
	v_add_f32_e32 v158, v158, v159
	s_waitcnt lgkmcnt(0)
	v_mul_f32_e32 v159, v252, v181
	v_fmac_f32_e32 v159, v146, v180
	v_fmac_f32_e32 v159, v253, v182
	v_fmac_f32_e32 v159, v227, v183
	ds_read_b128 v[180:183], v9 offset:816
	v_add_f32_e32 v158, v158, v159
	s_waitcnt lgkmcnt(0)
	v_mul_f32_e32 v159, v147, v181
	v_fmac_f32_e32 v159, v145, v180
	v_fmac_f32_e32 v159, v230, v182
	v_fmac_f32_e32 v159, v231, v183
	v_add_f32_e32 v158, v158, v159
	v_min_f32_e32 v159, 0, v158
	v_mul_f32_e64 v158, |v158|, s18
	v_exp_f32_e32 v158, v158
	ds_read_b128 v[180:183], v9 offset:896
	v_add_f32_e32 v158, 1.0, v158
	v_cmp_gt_f32_e32 vcc, s71, v158
	s_nop 1
	v_cndmask_b32_e64 v160, 0, 32, vcc
	v_ldexp_f32 v158, v158, v160
	v_log_f32_e32 v158, v158
	s_nop 0
	v_mul_f32_e32 v160, 0x3f317217, v158
	v_fma_f32 v160, v158, s48, -v160
	v_fmac_f32_e32 v160, 0x3377d1cf, v158
	v_fmac_f32_e32 v160, 0x3f317217, v158
	v_cmp_lt_f32_e64 s[0:1], |v158|, s49
	s_nop 1
	v_cndmask_b32_e64 v158, v158, v160, s[0:1]
	v_cndmask_b32_e32 v160, 0, v233, vcc
	v_sub_f32_e32 v158, v158, v160
	v_sub_f32_e32 v158, v159, v158
	v_mul_f32_e32 v179, 0x3d800000, v158
	v_fmac_f32_e32 v141, 0x3d800000, v158
	s_waitcnt lgkmcnt(0)
	v_mul_f32_e32 v158, v5, v181
	v_fmac_f32_e32 v158, v4, v180
	v_fmac_f32_e32 v158, v6, v182
	v_fmac_f32_e32 v158, v7, v183
	ds_read_b128 v[180:183], v9 offset:912
	v_add_f32_e32 v158, v157, v158
	s_waitcnt lgkmcnt(0)
	v_mul_f32_e32 v159, v154, v181
	v_fmac_f32_e32 v159, v228, v180
	v_fmac_f32_e32 v159, v155, v182
	v_fmac_f32_e32 v159, v156, v183
	ds_read_b128 v[180:183], v9 offset:928
	v_add_f32_e32 v158, v158, v159
	s_waitcnt lgkmcnt(0)
	v_mul_f32_e32 v159, v252, v181
	v_fmac_f32_e32 v159, v146, v180
	v_fmac_f32_e32 v159, v253, v182
	v_fmac_f32_e32 v159, v227, v183
	ds_read_b128 v[180:183], v9 offset:944
	v_add_f32_e32 v158, v158, v159
	s_waitcnt lgkmcnt(0)
	v_mul_f32_e32 v159, v147, v181
	v_fmac_f32_e32 v159, v145, v180
	v_fmac_f32_e32 v159, v230, v182
	v_fmac_f32_e32 v159, v231, v183
	v_add_f32_e32 v158, v158, v159
	v_min_f32_e32 v159, 0, v158
	v_mul_f32_e64 v158, |v158|, s18
	v_exp_f32_e32 v158, v158
	ds_read_b128 v[182:185], v9 offset:1024
	v_add_f32_e32 v158, 1.0, v158
	v_cmp_gt_f32_e32 vcc, s71, v158
	s_nop 1
	v_cndmask_b32_e64 v160, 0, 32, vcc
	v_ldexp_f32 v158, v158, v160
	v_log_f32_e32 v158, v158
	s_nop 0
	v_mul_f32_e32 v160, 0x3f317217, v158
	v_fma_f32 v160, v158, s48, -v160
	v_fmac_f32_e32 v160, 0x3377d1cf, v158
	v_fmac_f32_e32 v160, 0x3f317217, v158
	v_cmp_lt_f32_e64 s[0:1], |v158|, s49
	s_nop 1
	v_cndmask_b32_e64 v158, v158, v160, s[0:1]
	v_cndmask_b32_e32 v160, 0, v233, vcc
	v_sub_f32_e32 v158, v158, v160
	v_sub_f32_e32 v158, v159, v158
	v_mul_f32_e32 v180, 0x3d800000, v158
	v_fmac_f32_e32 v141, 0x3d800000, v158
	s_waitcnt lgkmcnt(0)
	v_mul_f32_e32 v158, v5, v183
	v_fmac_f32_e32 v158, v4, v182
	v_fmac_f32_e32 v158, v6, v184
	v_fmac_f32_e32 v158, v7, v185
	ds_read_b128 v[182:185], v9 offset:1040
	v_add_f32_e32 v158, v157, v158
	s_waitcnt lgkmcnt(0)
	v_mul_f32_e32 v159, v154, v183
	v_fmac_f32_e32 v159, v228, v182
	v_fmac_f32_e32 v159, v155, v184
	v_fmac_f32_e32 v159, v156, v185
	ds_read_b128 v[182:185], v9 offset:1056
	v_add_f32_e32 v158, v158, v159
	s_waitcnt lgkmcnt(0)
	v_mul_f32_e32 v159, v252, v183
	v_fmac_f32_e32 v159, v146, v182
	v_fmac_f32_e32 v159, v253, v184
	v_fmac_f32_e32 v159, v227, v185
	ds_read_b128 v[182:185], v9 offset:1072
	v_add_f32_e32 v158, v158, v159
	s_waitcnt lgkmcnt(0)
	v_mul_f32_e32 v159, v147, v183
	v_fmac_f32_e32 v159, v145, v182
	v_fmac_f32_e32 v159, v230, v184
	v_fmac_f32_e32 v159, v231, v185
	v_add_f32_e32 v158, v158, v159
	v_min_f32_e32 v159, 0, v158
	v_mul_f32_e64 v158, |v158|, s18
	v_exp_f32_e32 v158, v158
	ds_read_b128 v[182:185], v9 offset:1152
	v_add_f32_e32 v158, 1.0, v158
	v_cmp_gt_f32_e32 vcc, s71, v158
	s_nop 1
	v_cndmask_b32_e64 v160, 0, 32, vcc
	v_ldexp_f32 v158, v158, v160
	v_log_f32_e32 v158, v158
	s_nop 0
	v_mul_f32_e32 v160, 0x3f317217, v158
	v_fma_f32 v160, v158, s48, -v160
	v_fmac_f32_e32 v160, 0x3377d1cf, v158
	v_fmac_f32_e32 v160, 0x3f317217, v158
	v_cmp_lt_f32_e64 s[0:1], |v158|, s49
	s_nop 1
	v_cndmask_b32_e64 v158, v158, v160, s[0:1]
	v_cndmask_b32_e32 v160, 0, v233, vcc
	v_sub_f32_e32 v158, v158, v160
	v_sub_f32_e32 v158, v159, v158
	v_mul_f32_e32 v181, 0x3d800000, v158
	v_fmac_f32_e32 v141, 0x3d800000, v158
	s_waitcnt lgkmcnt(0)
	v_mul_f32_e32 v158, v5, v183
	v_fmac_f32_e32 v158, v4, v182
	v_fmac_f32_e32 v158, v6, v184
	v_fmac_f32_e32 v158, v7, v185
	ds_read_b128 v[182:185], v9 offset:1168
	v_add_f32_e32 v158, v157, v158
	s_waitcnt lgkmcnt(0)
	v_mul_f32_e32 v159, v154, v183
	v_fmac_f32_e32 v159, v228, v182
	v_fmac_f32_e32 v159, v155, v184
	v_fmac_f32_e32 v159, v156, v185
	ds_read_b128 v[182:185], v9 offset:1184
	v_add_f32_e32 v158, v158, v159
	s_waitcnt lgkmcnt(0)
	v_mul_f32_e32 v159, v252, v183
	v_fmac_f32_e32 v159, v146, v182
	v_fmac_f32_e32 v159, v253, v184
	v_fmac_f32_e32 v159, v227, v185
	ds_read_b128 v[182:185], v9 offset:1200
	v_add_f32_e32 v158, v158, v159
	s_waitcnt lgkmcnt(0)
	v_mul_f32_e32 v159, v147, v183
	v_fmac_f32_e32 v159, v145, v182
	v_fmac_f32_e32 v159, v230, v184
	v_fmac_f32_e32 v159, v231, v185
	v_add_f32_e32 v158, v158, v159
	v_min_f32_e32 v159, 0, v158
	v_mul_f32_e64 v158, |v158|, s18
	v_exp_f32_e32 v158, v158
	ds_read_b128 v[184:187], v9 offset:1280
	v_add_f32_e32 v158, 1.0, v158
	v_cmp_gt_f32_e32 vcc, s71, v158
	s_nop 1
	v_cndmask_b32_e64 v160, 0, 32, vcc
	v_ldexp_f32 v158, v158, v160
	v_log_f32_e32 v158, v158
	s_nop 0
	v_mul_f32_e32 v160, 0x3f317217, v158
	v_fma_f32 v160, v158, s48, -v160
	v_fmac_f32_e32 v160, 0x3377d1cf, v158
	v_fmac_f32_e32 v160, 0x3f317217, v158
	v_cmp_lt_f32_e64 s[0:1], |v158|, s49
	s_nop 1
	v_cndmask_b32_e64 v158, v158, v160, s[0:1]
	v_cndmask_b32_e32 v160, 0, v233, vcc
	v_sub_f32_e32 v158, v158, v160
	v_sub_f32_e32 v158, v159, v158
	v_mul_f32_e32 v182, 0x3d800000, v158
	v_fmac_f32_e32 v141, 0x3d800000, v158
	s_waitcnt lgkmcnt(0)
	v_mul_f32_e32 v158, v5, v185
	v_fmac_f32_e32 v158, v4, v184
	v_fmac_f32_e32 v158, v6, v186
	v_fmac_f32_e32 v158, v7, v187
	ds_read_b128 v[184:187], v9 offset:1296
	v_add_f32_e32 v158, v157, v158
	s_waitcnt lgkmcnt(0)
	v_mul_f32_e32 v159, v154, v185
	v_fmac_f32_e32 v159, v228, v184
	v_fmac_f32_e32 v159, v155, v186
	v_fmac_f32_e32 v159, v156, v187
	ds_read_b128 v[184:187], v9 offset:1312
	v_add_f32_e32 v158, v158, v159
	s_waitcnt lgkmcnt(0)
	v_mul_f32_e32 v159, v252, v185
	v_fmac_f32_e32 v159, v146, v184
	v_fmac_f32_e32 v159, v253, v186
	v_fmac_f32_e32 v159, v227, v187
	ds_read_b128 v[184:187], v9 offset:1328
	v_add_f32_e32 v158, v158, v159
	s_waitcnt lgkmcnt(0)
	v_mul_f32_e32 v159, v147, v185
	v_fmac_f32_e32 v159, v145, v184
	v_fmac_f32_e32 v159, v230, v186
	v_fmac_f32_e32 v159, v231, v187
	v_add_f32_e32 v158, v158, v159
	v_min_f32_e32 v159, 0, v158
	v_mul_f32_e64 v158, |v158|, s18
	v_exp_f32_e32 v158, v158
	ds_read_b128 v[184:187], v9 offset:1408
	v_add_f32_e32 v158, 1.0, v158
	v_cmp_gt_f32_e32 vcc, s71, v158
	s_nop 1
	v_cndmask_b32_e64 v160, 0, 32, vcc
	v_ldexp_f32 v158, v158, v160
	v_log_f32_e32 v158, v158
	s_nop 0
	v_mul_f32_e32 v160, 0x3f317217, v158
	v_fma_f32 v160, v158, s48, -v160
	v_fmac_f32_e32 v160, 0x3377d1cf, v158
	v_fmac_f32_e32 v160, 0x3f317217, v158
	v_cmp_lt_f32_e64 s[0:1], |v158|, s49
	s_nop 1
	v_cndmask_b32_e64 v158, v158, v160, s[0:1]
	v_cndmask_b32_e32 v160, 0, v233, vcc
	v_sub_f32_e32 v158, v158, v160
	v_sub_f32_e32 v158, v159, v158
	v_mul_f32_e32 v183, 0x3d800000, v158
	v_fmac_f32_e32 v141, 0x3d800000, v158
	s_waitcnt lgkmcnt(0)
	v_mul_f32_e32 v158, v5, v185
	v_fmac_f32_e32 v158, v4, v184
	v_fmac_f32_e32 v158, v6, v186
	v_fmac_f32_e32 v158, v7, v187
	ds_read_b128 v[184:187], v9 offset:1424
	v_add_f32_e32 v158, v157, v158
	s_waitcnt lgkmcnt(0)
	v_mul_f32_e32 v159, v154, v185
	v_fmac_f32_e32 v159, v228, v184
	v_fmac_f32_e32 v159, v155, v186
	v_fmac_f32_e32 v159, v156, v187
	ds_read_b128 v[184:187], v9 offset:1440
	v_add_f32_e32 v158, v158, v159
	s_waitcnt lgkmcnt(0)
	v_mul_f32_e32 v159, v252, v185
	v_fmac_f32_e32 v159, v146, v184
	v_fmac_f32_e32 v159, v253, v186
	v_fmac_f32_e32 v159, v227, v187
	ds_read_b128 v[184:187], v9 offset:1456
	v_add_f32_e32 v158, v158, v159
	s_waitcnt lgkmcnt(0)
	v_mul_f32_e32 v159, v147, v185
	v_fmac_f32_e32 v159, v145, v184
	v_fmac_f32_e32 v159, v230, v186
	v_fmac_f32_e32 v159, v231, v187
	v_add_f32_e32 v158, v158, v159
	v_min_f32_e32 v159, 0, v158
	v_mul_f32_e64 v158, |v158|, s18
	v_exp_f32_e32 v158, v158
	ds_read_b128 v[186:189], v9 offset:1536
	v_add_f32_e32 v158, 1.0, v158
	v_cmp_gt_f32_e32 vcc, s71, v158
	s_nop 1
	v_cndmask_b32_e64 v160, 0, 32, vcc
	v_ldexp_f32 v158, v158, v160
	v_log_f32_e32 v158, v158
	s_nop 0
	v_mul_f32_e32 v160, 0x3f317217, v158
	v_fma_f32 v160, v158, s48, -v160
	v_fmac_f32_e32 v160, 0x3377d1cf, v158
	v_fmac_f32_e32 v160, 0x3f317217, v158
	v_cmp_lt_f32_e64 s[0:1], |v158|, s49
	s_nop 1
	v_cndmask_b32_e64 v158, v158, v160, s[0:1]
	v_cndmask_b32_e32 v160, 0, v233, vcc
	v_sub_f32_e32 v158, v158, v160
	v_sub_f32_e32 v158, v159, v158
	v_mul_f32_e32 v184, 0x3d800000, v158
	v_fmac_f32_e32 v141, 0x3d800000, v158
	s_waitcnt lgkmcnt(0)
	v_mul_f32_e32 v158, v5, v187
	v_fmac_f32_e32 v158, v4, v186
	v_fmac_f32_e32 v158, v6, v188
	v_fmac_f32_e32 v158, v7, v189
	ds_read_b128 v[186:189], v9 offset:1552
	v_add_f32_e32 v158, v157, v158
	s_waitcnt lgkmcnt(0)
	v_mul_f32_e32 v159, v154, v187
	v_fmac_f32_e32 v159, v228, v186
	v_fmac_f32_e32 v159, v155, v188
	v_fmac_f32_e32 v159, v156, v189
	ds_read_b128 v[186:189], v9 offset:1568
	v_add_f32_e32 v158, v158, v159
	s_waitcnt lgkmcnt(0)
	v_mul_f32_e32 v159, v252, v187
	v_fmac_f32_e32 v159, v146, v186
	v_fmac_f32_e32 v159, v253, v188
	v_fmac_f32_e32 v159, v227, v189
	ds_read_b128 v[186:189], v9 offset:1584
	v_add_f32_e32 v158, v158, v159
	s_waitcnt lgkmcnt(0)
	v_mul_f32_e32 v159, v147, v187
	v_fmac_f32_e32 v159, v145, v186
	v_fmac_f32_e32 v159, v230, v188
	v_fmac_f32_e32 v159, v231, v189
	v_add_f32_e32 v158, v158, v159
	v_min_f32_e32 v159, 0, v158
	v_mul_f32_e64 v158, |v158|, s18
	v_exp_f32_e32 v158, v158
	ds_read_b128 v[186:189], v9 offset:1664
	v_add_f32_e32 v158, 1.0, v158
	v_cmp_gt_f32_e32 vcc, s71, v158
	s_nop 1
	v_cndmask_b32_e64 v160, 0, 32, vcc
	v_ldexp_f32 v158, v158, v160
	v_log_f32_e32 v158, v158
	s_nop 0
	v_mul_f32_e32 v160, 0x3f317217, v158
	v_fma_f32 v160, v158, s48, -v160
	v_fmac_f32_e32 v160, 0x3377d1cf, v158
	v_fmac_f32_e32 v160, 0x3f317217, v158
	v_cmp_lt_f32_e64 s[0:1], |v158|, s49
	s_nop 1
	v_cndmask_b32_e64 v158, v158, v160, s[0:1]
	v_cndmask_b32_e32 v160, 0, v233, vcc
	v_sub_f32_e32 v158, v158, v160
	v_sub_f32_e32 v158, v159, v158
	v_mul_f32_e32 v185, 0x3d800000, v158
	v_fmac_f32_e32 v141, 0x3d800000, v158
	s_waitcnt lgkmcnt(0)
	v_mul_f32_e32 v158, v5, v187
	v_fmac_f32_e32 v158, v4, v186
	v_fmac_f32_e32 v158, v6, v188
	v_fmac_f32_e32 v158, v7, v189
	ds_read_b128 v[186:189], v9 offset:1680
	v_add_f32_e32 v158, v157, v158
	s_waitcnt lgkmcnt(0)
	v_mul_f32_e32 v159, v154, v187
	v_fmac_f32_e32 v159, v228, v186
	v_fmac_f32_e32 v159, v155, v188
	v_fmac_f32_e32 v159, v156, v189
	ds_read_b128 v[186:189], v9 offset:1696
	v_add_f32_e32 v158, v158, v159
	s_waitcnt lgkmcnt(0)
	v_mul_f32_e32 v159, v252, v187
	v_fmac_f32_e32 v159, v146, v186
	v_fmac_f32_e32 v159, v253, v188
	v_fmac_f32_e32 v159, v227, v189
	ds_read_b128 v[186:189], v9 offset:1712
	v_add_f32_e32 v158, v158, v159
	s_waitcnt lgkmcnt(0)
	v_mul_f32_e32 v159, v147, v187
	v_fmac_f32_e32 v159, v145, v186
	v_fmac_f32_e32 v159, v230, v188
	v_fmac_f32_e32 v159, v231, v189
	v_add_f32_e32 v158, v158, v159
	v_min_f32_e32 v159, 0, v158
	v_mul_f32_e64 v158, |v158|, s18
	v_exp_f32_e32 v158, v158
	ds_read_b128 v[188:191], v9 offset:1792
	v_add_f32_e32 v158, 1.0, v158
	v_cmp_gt_f32_e32 vcc, s71, v158
	s_nop 1
	v_cndmask_b32_e64 v160, 0, 32, vcc
	v_ldexp_f32 v158, v158, v160
	v_log_f32_e32 v158, v158
	s_nop 0
	v_mul_f32_e32 v160, 0x3f317217, v158
	v_fma_f32 v160, v158, s48, -v160
	v_fmac_f32_e32 v160, 0x3377d1cf, v158
	v_fmac_f32_e32 v160, 0x3f317217, v158
	v_cmp_lt_f32_e64 s[0:1], |v158|, s49
	s_nop 1
	v_cndmask_b32_e64 v158, v158, v160, s[0:1]
	v_cndmask_b32_e32 v160, 0, v233, vcc
	v_sub_f32_e32 v158, v158, v160
	v_sub_f32_e32 v158, v159, v158
	v_mul_f32_e32 v186, 0x3d800000, v158
	v_fmac_f32_e32 v141, 0x3d800000, v158
	s_waitcnt lgkmcnt(0)
	v_mul_f32_e32 v158, v5, v189
	v_fmac_f32_e32 v158, v4, v188
	v_fmac_f32_e32 v158, v6, v190
	v_fmac_f32_e32 v158, v7, v191
	ds_read_b128 v[188:191], v9 offset:1808
	v_add_f32_e32 v158, v157, v158
	s_waitcnt lgkmcnt(0)
	v_mul_f32_e32 v159, v154, v189
	v_fmac_f32_e32 v159, v228, v188
	v_fmac_f32_e32 v159, v155, v190
	v_fmac_f32_e32 v159, v156, v191
	ds_read_b128 v[188:191], v9 offset:1824
	v_add_f32_e32 v158, v158, v159
	s_waitcnt lgkmcnt(0)
	v_mul_f32_e32 v159, v252, v189
	v_fmac_f32_e32 v159, v146, v188
	v_fmac_f32_e32 v159, v253, v190
	v_fmac_f32_e32 v159, v227, v191
	ds_read_b128 v[188:191], v9 offset:1840
	v_add_f32_e32 v158, v158, v159
	s_waitcnt lgkmcnt(0)
	v_mul_f32_e32 v159, v147, v189
	v_fmac_f32_e32 v159, v145, v188
	v_fmac_f32_e32 v159, v230, v190
	v_fmac_f32_e32 v159, v231, v191
	v_add_f32_e32 v158, v158, v159
	v_min_f32_e32 v159, 0, v158
	v_mul_f32_e64 v158, |v158|, s18
	v_exp_f32_e32 v158, v158
	ds_read_b128 v[188:191], v9 offset:1920
	v_add_f32_e32 v158, 1.0, v158
	v_cmp_gt_f32_e32 vcc, s71, v158
	s_nop 1
	v_cndmask_b32_e64 v160, 0, 32, vcc
	v_ldexp_f32 v158, v158, v160
	v_log_f32_e32 v158, v158
	s_nop 0
	v_mul_f32_e32 v160, 0x3f317217, v158
	v_fma_f32 v160, v158, s48, -v160
	v_fmac_f32_e32 v160, 0x3377d1cf, v158
	v_fmac_f32_e32 v160, 0x3f317217, v158
	v_cmp_lt_f32_e64 s[0:1], |v158|, s49
	s_nop 1
	v_cndmask_b32_e64 v158, v158, v160, s[0:1]
	v_cndmask_b32_e32 v160, 0, v233, vcc
	v_sub_f32_e32 v158, v158, v160
	v_sub_f32_e32 v158, v159, v158
	v_mul_f32_e32 v187, 0x3d800000, v158
	v_fmac_f32_e32 v141, 0x3d800000, v158
	s_waitcnt lgkmcnt(0)
	v_mul_f32_e32 v158, v5, v189
	v_fmac_f32_e32 v158, v4, v188
	v_fmac_f32_e32 v158, v6, v190
	v_fmac_f32_e32 v158, v7, v191
	ds_read_b128 v[188:191], v9 offset:1936
	v_add_f32_e32 v158, v157, v158
	s_waitcnt lgkmcnt(0)
	v_mul_f32_e32 v159, v154, v189
	v_fmac_f32_e32 v159, v228, v188
	v_fmac_f32_e32 v159, v155, v190
	v_fmac_f32_e32 v159, v156, v191
	ds_read_b128 v[188:191], v9 offset:1952
	v_add_f32_e32 v158, v158, v159
	s_waitcnt lgkmcnt(0)
	v_mul_f32_e32 v159, v252, v189
	v_fmac_f32_e32 v159, v146, v188
	v_fmac_f32_e32 v159, v253, v190
	v_fmac_f32_e32 v159, v227, v191
	ds_read_b128 v[188:191], v9 offset:1968
	v_add_f32_e32 v158, v158, v159
	s_waitcnt lgkmcnt(0)
	v_mul_f32_e32 v159, v147, v189
	v_fmac_f32_e32 v159, v145, v188
	v_fmac_f32_e32 v159, v230, v190
	v_fmac_f32_e32 v159, v231, v191
	v_add_f32_e32 v158, v158, v159
	v_min_f32_e32 v159, 0, v158
	v_mul_f32_e64 v158, |v158|, s18
	v_exp_f32_e32 v158, v158
	ds_read_b128 v[190:193], v9 offset:2048
	v_add_f32_e32 v158, 1.0, v158
	v_cmp_gt_f32_e32 vcc, s71, v158
	s_nop 1
	v_cndmask_b32_e64 v160, 0, 32, vcc
	v_ldexp_f32 v158, v158, v160
	v_log_f32_e32 v158, v158
	s_nop 0
	v_mul_f32_e32 v160, 0x3f317217, v158
	v_fma_f32 v160, v158, s48, -v160
	v_fmac_f32_e32 v160, 0x3377d1cf, v158
	v_fmac_f32_e32 v160, 0x3f317217, v158
	v_cmp_lt_f32_e64 s[0:1], |v158|, s49
	s_nop 1
	v_cndmask_b32_e64 v158, v158, v160, s[0:1]
	v_cndmask_b32_e32 v160, 0, v233, vcc
	v_sub_f32_e32 v158, v158, v160
	v_sub_f32_e32 v158, v159, v158
	v_mul_f32_e32 v188, 0x3d800000, v158
	v_fmac_f32_e32 v141, 0x3d800000, v158
	s_waitcnt lgkmcnt(0)
	v_mul_f32_e32 v158, v5, v191
	v_fmac_f32_e32 v158, v4, v190
	v_fmac_f32_e32 v158, v6, v192
	v_fmac_f32_e32 v158, v7, v193
	ds_read_b128 v[190:193], v9 offset:2064
	v_add_f32_e32 v158, v157, v158
	s_waitcnt lgkmcnt(0)
	v_mul_f32_e32 v159, v154, v191
	v_fmac_f32_e32 v159, v228, v190
	v_fmac_f32_e32 v159, v155, v192
	v_fmac_f32_e32 v159, v156, v193
	ds_read_b128 v[190:193], v9 offset:2080
	v_add_f32_e32 v158, v158, v159
	s_waitcnt lgkmcnt(0)
	v_mul_f32_e32 v159, v252, v191
	v_fmac_f32_e32 v159, v146, v190
	v_fmac_f32_e32 v159, v253, v192
	v_fmac_f32_e32 v159, v227, v193
	ds_read_b128 v[190:193], v9 offset:2096
	v_add_f32_e32 v158, v158, v159
	s_waitcnt lgkmcnt(0)
	v_mul_f32_e32 v159, v147, v191
	v_fmac_f32_e32 v159, v145, v190
	v_fmac_f32_e32 v159, v230, v192
	v_fmac_f32_e32 v159, v231, v193
	v_add_f32_e32 v158, v158, v159
	v_min_f32_e32 v159, 0, v158
	v_mul_f32_e64 v158, |v158|, s18
	v_exp_f32_e32 v158, v158
	ds_read_b128 v[190:193], v9 offset:2176
	v_add_f32_e32 v158, 1.0, v158
	v_cmp_gt_f32_e32 vcc, s71, v158
	s_nop 1
	v_cndmask_b32_e64 v160, 0, 32, vcc
	v_ldexp_f32 v158, v158, v160
	v_log_f32_e32 v158, v158
	s_nop 0
	v_mul_f32_e32 v160, 0x3f317217, v158
	v_fma_f32 v160, v158, s48, -v160
	v_fmac_f32_e32 v160, 0x3377d1cf, v158
	v_fmac_f32_e32 v160, 0x3f317217, v158
	v_cmp_lt_f32_e64 s[0:1], |v158|, s49
	s_nop 1
	v_cndmask_b32_e64 v158, v158, v160, s[0:1]
	v_cndmask_b32_e32 v160, 0, v233, vcc
	v_sub_f32_e32 v158, v158, v160
	v_sub_f32_e32 v158, v159, v158
	v_mul_f32_e32 v189, 0x3d800000, v158
	v_fmac_f32_e32 v141, 0x3d800000, v158
	s_waitcnt lgkmcnt(0)
	v_mul_f32_e32 v158, v5, v191
	v_fmac_f32_e32 v158, v4, v190
	v_fmac_f32_e32 v158, v6, v192
	v_fmac_f32_e32 v158, v7, v193
	ds_read_b128 v[190:193], v9 offset:2192
	v_add_f32_e32 v158, v157, v158
	s_waitcnt lgkmcnt(0)
	v_mul_f32_e32 v159, v154, v191
	v_fmac_f32_e32 v159, v228, v190
	v_fmac_f32_e32 v159, v155, v192
	v_fmac_f32_e32 v159, v156, v193
	ds_read_b128 v[190:193], v9 offset:2208
	v_add_f32_e32 v158, v158, v159
	s_waitcnt lgkmcnt(0)
	v_mul_f32_e32 v159, v252, v191
	v_fmac_f32_e32 v159, v146, v190
	v_fmac_f32_e32 v159, v253, v192
	v_fmac_f32_e32 v159, v227, v193
	ds_read_b128 v[190:193], v9 offset:2224
	v_add_f32_e32 v158, v158, v159
	s_waitcnt lgkmcnt(0)
	v_mul_f32_e32 v159, v147, v191
	v_fmac_f32_e32 v159, v145, v190
	v_fmac_f32_e32 v159, v230, v192
	v_fmac_f32_e32 v159, v231, v193
	v_add_f32_e32 v158, v158, v159
	v_min_f32_e32 v159, 0, v158
	v_mul_f32_e64 v158, |v158|, s18
	v_exp_f32_e32 v158, v158
	ds_read_b128 v[192:195], v9 offset:2304
	v_add_f32_e32 v158, 1.0, v158
	v_cmp_gt_f32_e32 vcc, s71, v158
	s_nop 1
	v_cndmask_b32_e64 v160, 0, 32, vcc
	v_ldexp_f32 v158, v158, v160
	v_log_f32_e32 v158, v158
	s_nop 0
	v_mul_f32_e32 v160, 0x3f317217, v158
	v_fma_f32 v160, v158, s48, -v160
	v_fmac_f32_e32 v160, 0x3377d1cf, v158
	v_fmac_f32_e32 v160, 0x3f317217, v158
	v_cmp_lt_f32_e64 s[0:1], |v158|, s49
	s_nop 1
	v_cndmask_b32_e64 v158, v158, v160, s[0:1]
	v_cndmask_b32_e32 v160, 0, v233, vcc
	v_sub_f32_e32 v158, v158, v160
	v_sub_f32_e32 v158, v159, v158
	v_mul_f32_e32 v190, 0x3d800000, v158
	v_fmac_f32_e32 v141, 0x3d800000, v158
	s_waitcnt lgkmcnt(0)
	v_mul_f32_e32 v158, v5, v193
	v_fmac_f32_e32 v158, v4, v192
	v_fmac_f32_e32 v158, v6, v194
	v_fmac_f32_e32 v158, v7, v195
	ds_read_b128 v[192:195], v9 offset:2320
	v_add_f32_e32 v158, v157, v158
	s_waitcnt lgkmcnt(0)
	v_mul_f32_e32 v159, v154, v193
	v_fmac_f32_e32 v159, v228, v192
	v_fmac_f32_e32 v159, v155, v194
	v_fmac_f32_e32 v159, v156, v195
	ds_read_b128 v[192:195], v9 offset:2336
	v_add_f32_e32 v158, v158, v159
	s_waitcnt lgkmcnt(0)
	v_mul_f32_e32 v159, v252, v193
	v_fmac_f32_e32 v159, v146, v192
	v_fmac_f32_e32 v159, v253, v194
	v_fmac_f32_e32 v159, v227, v195
	ds_read_b128 v[192:195], v9 offset:2352
	v_add_f32_e32 v158, v158, v159
	s_waitcnt lgkmcnt(0)
	v_mul_f32_e32 v159, v147, v193
	v_fmac_f32_e32 v159, v145, v192
	v_fmac_f32_e32 v159, v230, v194
	v_fmac_f32_e32 v159, v231, v195
	v_add_f32_e32 v158, v158, v159
	v_min_f32_e32 v159, 0, v158
	v_mul_f32_e64 v158, |v158|, s18
	v_exp_f32_e32 v158, v158
	ds_read_b128 v[192:195], v9 offset:2432
	v_add_f32_e32 v158, 1.0, v158
	v_cmp_gt_f32_e32 vcc, s71, v158
	s_nop 1
	v_cndmask_b32_e64 v160, 0, 32, vcc
	v_ldexp_f32 v158, v158, v160
	v_log_f32_e32 v158, v158
	s_nop 0
	v_mul_f32_e32 v160, 0x3f317217, v158
	v_fma_f32 v160, v158, s48, -v160
	v_fmac_f32_e32 v160, 0x3377d1cf, v158
	v_fmac_f32_e32 v160, 0x3f317217, v158
	v_cmp_lt_f32_e64 s[0:1], |v158|, s49
	s_nop 1
	v_cndmask_b32_e64 v158, v158, v160, s[0:1]
	v_cndmask_b32_e32 v160, 0, v233, vcc
	v_sub_f32_e32 v158, v158, v160
	v_sub_f32_e32 v158, v159, v158
	v_mul_f32_e32 v191, 0x3d800000, v158
	v_fmac_f32_e32 v141, 0x3d800000, v158
	s_waitcnt lgkmcnt(0)
	v_mul_f32_e32 v158, v5, v193
	v_fmac_f32_e32 v158, v4, v192
	v_fmac_f32_e32 v158, v6, v194
	v_fmac_f32_e32 v158, v7, v195
	ds_read_b128 v[192:195], v9 offset:2448
	v_add_f32_e32 v158, v157, v158
	s_waitcnt lgkmcnt(0)
	v_mul_f32_e32 v159, v154, v193
	v_fmac_f32_e32 v159, v228, v192
	v_fmac_f32_e32 v159, v155, v194
	v_fmac_f32_e32 v159, v156, v195
	ds_read_b128 v[192:195], v9 offset:2464
	v_add_f32_e32 v158, v158, v159
	s_waitcnt lgkmcnt(0)
	v_mul_f32_e32 v159, v252, v193
	v_fmac_f32_e32 v159, v146, v192
	v_fmac_f32_e32 v159, v253, v194
	v_fmac_f32_e32 v159, v227, v195
	ds_read_b128 v[192:195], v9 offset:2480
	v_add_f32_e32 v158, v158, v159
	s_waitcnt lgkmcnt(0)
	v_mul_f32_e32 v159, v147, v193
	v_fmac_f32_e32 v159, v145, v192
	v_fmac_f32_e32 v159, v230, v194
	v_fmac_f32_e32 v159, v231, v195
	v_add_f32_e32 v158, v158, v159
	v_min_f32_e32 v159, 0, v158
	v_mul_f32_e64 v158, |v158|, s18
	v_exp_f32_e32 v158, v158
	ds_read_b128 v[194:197], v9 offset:2560
	v_add_f32_e32 v158, 1.0, v158
	v_cmp_gt_f32_e32 vcc, s71, v158
	s_nop 1
	v_cndmask_b32_e64 v160, 0, 32, vcc
	v_ldexp_f32 v158, v158, v160
	v_log_f32_e32 v158, v158
	s_nop 0
	v_mul_f32_e32 v160, 0x3f317217, v158
	v_fma_f32 v160, v158, s48, -v160
	v_fmac_f32_e32 v160, 0x3377d1cf, v158
	v_fmac_f32_e32 v160, 0x3f317217, v158
	v_cmp_lt_f32_e64 s[0:1], |v158|, s49
	s_nop 1
	v_cndmask_b32_e64 v158, v158, v160, s[0:1]
	v_cndmask_b32_e32 v160, 0, v233, vcc
	v_sub_f32_e32 v158, v158, v160
	v_sub_f32_e32 v158, v159, v158
	v_mul_f32_e32 v192, 0x3d800000, v158
	v_fmac_f32_e32 v141, 0x3d800000, v158
	s_waitcnt lgkmcnt(0)
	v_mul_f32_e32 v158, v5, v195
	v_fmac_f32_e32 v158, v4, v194
	v_fmac_f32_e32 v158, v6, v196
	v_fmac_f32_e32 v158, v7, v197
	ds_read_b128 v[194:197], v9 offset:2576
	v_add_f32_e32 v158, v157, v158
	s_waitcnt lgkmcnt(0)
	v_mul_f32_e32 v159, v154, v195
	v_fmac_f32_e32 v159, v228, v194
	v_fmac_f32_e32 v159, v155, v196
	v_fmac_f32_e32 v159, v156, v197
	ds_read_b128 v[194:197], v9 offset:2592
	v_add_f32_e32 v158, v158, v159
	s_waitcnt lgkmcnt(0)
	v_mul_f32_e32 v159, v252, v195
	v_fmac_f32_e32 v159, v146, v194
	v_fmac_f32_e32 v159, v253, v196
	v_fmac_f32_e32 v159, v227, v197
	ds_read_b128 v[194:197], v9 offset:2608
	v_add_f32_e32 v158, v158, v159
	s_waitcnt lgkmcnt(0)
	v_mul_f32_e32 v159, v147, v195
	v_fmac_f32_e32 v159, v145, v194
	v_fmac_f32_e32 v159, v230, v196
	v_fmac_f32_e32 v159, v231, v197
	v_add_f32_e32 v158, v158, v159
	v_min_f32_e32 v159, 0, v158
	v_mul_f32_e64 v158, |v158|, s18
	v_exp_f32_e32 v158, v158
	ds_read_b128 v[194:197], v9 offset:2688
	v_add_f32_e32 v158, 1.0, v158
	v_cmp_gt_f32_e32 vcc, s71, v158
	s_nop 1
	v_cndmask_b32_e64 v160, 0, 32, vcc
	v_ldexp_f32 v158, v158, v160
	v_log_f32_e32 v158, v158
	s_nop 0
	v_mul_f32_e32 v160, 0x3f317217, v158
	v_fma_f32 v160, v158, s48, -v160
	v_fmac_f32_e32 v160, 0x3377d1cf, v158
	v_fmac_f32_e32 v160, 0x3f317217, v158
	v_cmp_lt_f32_e64 s[0:1], |v158|, s49
	s_nop 1
	v_cndmask_b32_e64 v158, v158, v160, s[0:1]
	v_cndmask_b32_e32 v160, 0, v233, vcc
	v_sub_f32_e32 v158, v158, v160
	v_sub_f32_e32 v158, v159, v158
	v_mul_f32_e32 v193, 0x3d800000, v158
	v_fmac_f32_e32 v141, 0x3d800000, v158
	s_waitcnt lgkmcnt(0)
	v_mul_f32_e32 v158, v5, v195
	v_fmac_f32_e32 v158, v4, v194
	v_fmac_f32_e32 v158, v6, v196
	v_fmac_f32_e32 v158, v7, v197
	ds_read_b128 v[194:197], v9 offset:2704
	v_add_f32_e32 v158, v157, v158
	s_waitcnt lgkmcnt(0)
	v_mul_f32_e32 v159, v154, v195
	v_fmac_f32_e32 v159, v228, v194
	v_fmac_f32_e32 v159, v155, v196
	v_fmac_f32_e32 v159, v156, v197
	ds_read_b128 v[194:197], v9 offset:2720
	v_add_f32_e32 v158, v158, v159
	s_waitcnt lgkmcnt(0)
	v_mul_f32_e32 v159, v252, v195
	v_fmac_f32_e32 v159, v146, v194
	v_fmac_f32_e32 v159, v253, v196
	v_fmac_f32_e32 v159, v227, v197
	ds_read_b128 v[194:197], v9 offset:2736
	v_add_f32_e32 v158, v158, v159
	s_waitcnt lgkmcnt(0)
	v_mul_f32_e32 v159, v147, v195
	v_fmac_f32_e32 v159, v145, v194
	v_fmac_f32_e32 v159, v230, v196
	v_fmac_f32_e32 v159, v231, v197
	v_add_f32_e32 v158, v158, v159
	v_min_f32_e32 v159, 0, v158
	v_mul_f32_e64 v158, |v158|, s18
	v_exp_f32_e32 v158, v158
	ds_read_b128 v[196:199], v9 offset:2816
	v_add_f32_e32 v158, 1.0, v158
	v_cmp_gt_f32_e32 vcc, s71, v158
	s_nop 1
	v_cndmask_b32_e64 v160, 0, 32, vcc
	v_ldexp_f32 v158, v158, v160
	v_log_f32_e32 v158, v158
	s_nop 0
	v_mul_f32_e32 v160, 0x3f317217, v158
	v_fma_f32 v160, v158, s48, -v160
	v_fmac_f32_e32 v160, 0x3377d1cf, v158
	v_fmac_f32_e32 v160, 0x3f317217, v158
	v_cmp_lt_f32_e64 s[0:1], |v158|, s49
	s_nop 1
	v_cndmask_b32_e64 v158, v158, v160, s[0:1]
	v_cndmask_b32_e32 v160, 0, v233, vcc
	v_sub_f32_e32 v158, v158, v160
	v_sub_f32_e32 v158, v159, v158
	v_mul_f32_e32 v194, 0x3d800000, v158
	v_fmac_f32_e32 v141, 0x3d800000, v158
	s_waitcnt lgkmcnt(0)
	v_mul_f32_e32 v158, v5, v197
	v_fmac_f32_e32 v158, v4, v196
	v_fmac_f32_e32 v158, v6, v198
	v_fmac_f32_e32 v158, v7, v199
	ds_read_b128 v[196:199], v9 offset:2832
	v_add_f32_e32 v158, v157, v158
	s_waitcnt lgkmcnt(0)
	v_mul_f32_e32 v159, v154, v197
	v_fmac_f32_e32 v159, v228, v196
	v_fmac_f32_e32 v159, v155, v198
	v_fmac_f32_e32 v159, v156, v199
	ds_read_b128 v[196:199], v9 offset:2848
	v_add_f32_e32 v158, v158, v159
	s_waitcnt lgkmcnt(0)
	v_mul_f32_e32 v159, v252, v197
	v_fmac_f32_e32 v159, v146, v196
	v_fmac_f32_e32 v159, v253, v198
	v_fmac_f32_e32 v159, v227, v199
	ds_read_b128 v[196:199], v9 offset:2864
	v_add_f32_e32 v158, v158, v159
	s_waitcnt lgkmcnt(0)
	v_mul_f32_e32 v159, v147, v197
	v_fmac_f32_e32 v159, v145, v196
	v_fmac_f32_e32 v159, v230, v198
	v_fmac_f32_e32 v159, v231, v199
	v_add_f32_e32 v158, v158, v159
	v_min_f32_e32 v159, 0, v158
	v_mul_f32_e64 v158, |v158|, s18
	v_exp_f32_e32 v158, v158
	ds_read_b128 v[196:199], v9 offset:2944
	v_add_f32_e32 v158, 1.0, v158
	v_cmp_gt_f32_e32 vcc, s71, v158
	s_nop 1
	v_cndmask_b32_e64 v160, 0, 32, vcc
	v_ldexp_f32 v158, v158, v160
	v_log_f32_e32 v158, v158
	s_nop 0
	v_mul_f32_e32 v160, 0x3f317217, v158
	v_fma_f32 v160, v158, s48, -v160
	v_fmac_f32_e32 v160, 0x3377d1cf, v158
	v_fmac_f32_e32 v160, 0x3f317217, v158
	v_cmp_lt_f32_e64 s[0:1], |v158|, s49
	s_nop 1
	v_cndmask_b32_e64 v158, v158, v160, s[0:1]
	v_cndmask_b32_e32 v160, 0, v233, vcc
	v_sub_f32_e32 v158, v158, v160
	v_sub_f32_e32 v158, v159, v158
	v_mul_f32_e32 v195, 0x3d800000, v158
	v_fmac_f32_e32 v141, 0x3d800000, v158
	s_waitcnt lgkmcnt(0)
	v_mul_f32_e32 v158, v5, v197
	v_fmac_f32_e32 v158, v4, v196
	v_fmac_f32_e32 v158, v6, v198
	v_fmac_f32_e32 v158, v7, v199
	ds_read_b128 v[196:199], v9 offset:2960
	v_add_f32_e32 v158, v157, v158
	s_waitcnt lgkmcnt(0)
	v_mul_f32_e32 v159, v154, v197
	v_fmac_f32_e32 v159, v228, v196
	v_fmac_f32_e32 v159, v155, v198
	v_fmac_f32_e32 v159, v156, v199
	ds_read_b128 v[196:199], v9 offset:2976
	v_add_f32_e32 v158, v158, v159
	s_waitcnt lgkmcnt(0)
	v_mul_f32_e32 v159, v252, v197
	v_fmac_f32_e32 v159, v146, v196
	v_fmac_f32_e32 v159, v253, v198
	v_fmac_f32_e32 v159, v227, v199
	ds_read_b128 v[196:199], v9 offset:2992
	v_add_f32_e32 v158, v158, v159
	s_waitcnt lgkmcnt(0)
	v_mul_f32_e32 v159, v147, v197
	v_fmac_f32_e32 v159, v145, v196
	v_fmac_f32_e32 v159, v230, v198
	v_fmac_f32_e32 v159, v231, v199
	v_add_f32_e32 v158, v158, v159
	v_min_f32_e32 v159, 0, v158
	v_mul_f32_e64 v158, |v158|, s18
	v_exp_f32_e32 v158, v158
	ds_read_b128 v[198:201], v9 offset:3072
	v_add_f32_e32 v158, 1.0, v158
	v_cmp_gt_f32_e32 vcc, s71, v158
	s_nop 1
	v_cndmask_b32_e64 v160, 0, 32, vcc
	v_ldexp_f32 v158, v158, v160
	v_log_f32_e32 v158, v158
	s_nop 0
	v_mul_f32_e32 v160, 0x3f317217, v158
	v_fma_f32 v160, v158, s48, -v160
	v_fmac_f32_e32 v160, 0x3377d1cf, v158
	v_fmac_f32_e32 v160, 0x3f317217, v158
	v_cmp_lt_f32_e64 s[0:1], |v158|, s49
	s_nop 1
	v_cndmask_b32_e64 v158, v158, v160, s[0:1]
	v_cndmask_b32_e32 v160, 0, v233, vcc
	v_sub_f32_e32 v158, v158, v160
	v_sub_f32_e32 v158, v159, v158
	v_mul_f32_e32 v196, 0x3d800000, v158
	v_fmac_f32_e32 v141, 0x3d800000, v158
	s_waitcnt lgkmcnt(0)
	v_mul_f32_e32 v158, v5, v199
	v_fmac_f32_e32 v158, v4, v198
	v_fmac_f32_e32 v158, v6, v200
	v_fmac_f32_e32 v158, v7, v201
	ds_read_b128 v[198:201], v9 offset:3088
	v_add_f32_e32 v158, v157, v158
	s_waitcnt lgkmcnt(0)
	v_mul_f32_e32 v159, v154, v199
	v_fmac_f32_e32 v159, v228, v198
	v_fmac_f32_e32 v159, v155, v200
	v_fmac_f32_e32 v159, v156, v201
	ds_read_b128 v[198:201], v9 offset:3104
	v_add_f32_e32 v158, v158, v159
	s_waitcnt lgkmcnt(0)
	v_mul_f32_e32 v159, v252, v199
	v_fmac_f32_e32 v159, v146, v198
	v_fmac_f32_e32 v159, v253, v200
	v_fmac_f32_e32 v159, v227, v201
	ds_read_b128 v[198:201], v9 offset:3120
	v_add_f32_e32 v158, v158, v159
	s_waitcnt lgkmcnt(0)
	v_mul_f32_e32 v159, v147, v199
	v_fmac_f32_e32 v159, v145, v198
	v_fmac_f32_e32 v159, v230, v200
	v_fmac_f32_e32 v159, v231, v201
	v_add_f32_e32 v158, v158, v159
	v_min_f32_e32 v159, 0, v158
	v_mul_f32_e64 v158, |v158|, s18
	v_exp_f32_e32 v158, v158
	ds_read_b128 v[198:201], v9 offset:3200
	v_add_f32_e32 v158, 1.0, v158
	v_cmp_gt_f32_e32 vcc, s71, v158
	s_nop 1
	v_cndmask_b32_e64 v160, 0, 32, vcc
	v_ldexp_f32 v158, v158, v160
	v_log_f32_e32 v158, v158
	s_nop 0
	v_mul_f32_e32 v160, 0x3f317217, v158
	v_fma_f32 v160, v158, s48, -v160
	v_fmac_f32_e32 v160, 0x3377d1cf, v158
	v_fmac_f32_e32 v160, 0x3f317217, v158
	v_cmp_lt_f32_e64 s[0:1], |v158|, s49
	s_nop 1
	v_cndmask_b32_e64 v158, v158, v160, s[0:1]
	v_cndmask_b32_e32 v160, 0, v233, vcc
	v_sub_f32_e32 v158, v158, v160
	v_sub_f32_e32 v158, v159, v158
	v_mul_f32_e32 v197, 0x3d800000, v158
	v_fmac_f32_e32 v141, 0x3d800000, v158
	s_waitcnt lgkmcnt(0)
	v_mul_f32_e32 v158, v5, v199
	v_fmac_f32_e32 v158, v4, v198
	v_fmac_f32_e32 v158, v6, v200
	v_fmac_f32_e32 v158, v7, v201
	ds_read_b128 v[198:201], v9 offset:3216
	v_add_f32_e32 v158, v157, v158
	s_waitcnt lgkmcnt(0)
	v_mul_f32_e32 v159, v154, v199
	v_fmac_f32_e32 v159, v228, v198
	v_fmac_f32_e32 v159, v155, v200
	v_fmac_f32_e32 v159, v156, v201
	ds_read_b128 v[198:201], v9 offset:3232
	v_add_f32_e32 v158, v158, v159
	s_waitcnt lgkmcnt(0)
	v_mul_f32_e32 v159, v252, v199
	v_fmac_f32_e32 v159, v146, v198
	v_fmac_f32_e32 v159, v253, v200
	v_fmac_f32_e32 v159, v227, v201
	ds_read_b128 v[198:201], v9 offset:3248
	v_add_f32_e32 v158, v158, v159
	s_waitcnt lgkmcnt(0)
	v_mul_f32_e32 v159, v147, v199
	v_fmac_f32_e32 v159, v145, v198
	v_fmac_f32_e32 v159, v230, v200
	v_fmac_f32_e32 v159, v231, v201
	v_add_f32_e32 v158, v158, v159
	v_min_f32_e32 v159, 0, v158
	v_mul_f32_e64 v158, |v158|, s18
	v_exp_f32_e32 v158, v158
	ds_read_b128 v[200:203], v9 offset:3328
	v_add_f32_e32 v158, 1.0, v158
	v_cmp_gt_f32_e32 vcc, s71, v158
	s_nop 1
	v_cndmask_b32_e64 v160, 0, 32, vcc
	v_ldexp_f32 v158, v158, v160
	v_log_f32_e32 v158, v158
	s_nop 0
	v_mul_f32_e32 v160, 0x3f317217, v158
	v_fma_f32 v160, v158, s48, -v160
	v_fmac_f32_e32 v160, 0x3377d1cf, v158
	v_fmac_f32_e32 v160, 0x3f317217, v158
	v_cmp_lt_f32_e64 s[0:1], |v158|, s49
	s_nop 1
	v_cndmask_b32_e64 v158, v158, v160, s[0:1]
	v_cndmask_b32_e32 v160, 0, v233, vcc
	v_sub_f32_e32 v158, v158, v160
	v_sub_f32_e32 v158, v159, v158
	v_mul_f32_e32 v198, 0x3d800000, v158
	v_fmac_f32_e32 v141, 0x3d800000, v158
	s_waitcnt lgkmcnt(0)
	v_mul_f32_e32 v158, v5, v201
	v_fmac_f32_e32 v158, v4, v200
	v_fmac_f32_e32 v158, v6, v202
	v_fmac_f32_e32 v158, v7, v203
	ds_read_b128 v[200:203], v9 offset:3344
	v_add_f32_e32 v158, v157, v158
	s_waitcnt lgkmcnt(0)
	v_mul_f32_e32 v159, v154, v201
	v_fmac_f32_e32 v159, v228, v200
	v_fmac_f32_e32 v159, v155, v202
	v_fmac_f32_e32 v159, v156, v203
	ds_read_b128 v[200:203], v9 offset:3360
	v_add_f32_e32 v158, v158, v159
	s_waitcnt lgkmcnt(0)
	v_mul_f32_e32 v159, v252, v201
	v_fmac_f32_e32 v159, v146, v200
	v_fmac_f32_e32 v159, v253, v202
	v_fmac_f32_e32 v159, v227, v203
	ds_read_b128 v[200:203], v9 offset:3376
	v_add_f32_e32 v158, v158, v159
	s_waitcnt lgkmcnt(0)
	v_mul_f32_e32 v159, v147, v201
	v_fmac_f32_e32 v159, v145, v200
	v_fmac_f32_e32 v159, v230, v202
	v_fmac_f32_e32 v159, v231, v203
	v_add_f32_e32 v158, v158, v159
	v_min_f32_e32 v159, 0, v158
	v_mul_f32_e64 v158, |v158|, s18
	v_exp_f32_e32 v158, v158
	ds_read_b128 v[200:203], v9 offset:3456
	v_add_f32_e32 v158, 1.0, v158
	v_cmp_gt_f32_e32 vcc, s71, v158
	s_nop 1
	v_cndmask_b32_e64 v160, 0, 32, vcc
	v_ldexp_f32 v158, v158, v160
	v_log_f32_e32 v158, v158
	s_nop 0
	v_mul_f32_e32 v160, 0x3f317217, v158
	v_fma_f32 v160, v158, s48, -v160
	v_fmac_f32_e32 v160, 0x3377d1cf, v158
	v_fmac_f32_e32 v160, 0x3f317217, v158
	v_cmp_lt_f32_e64 s[0:1], |v158|, s49
	s_nop 1
	v_cndmask_b32_e64 v158, v158, v160, s[0:1]
	v_cndmask_b32_e32 v160, 0, v233, vcc
	v_sub_f32_e32 v158, v158, v160
	v_sub_f32_e32 v158, v159, v158
	v_mul_f32_e32 v199, 0x3d800000, v158
	v_fmac_f32_e32 v141, 0x3d800000, v158
	s_waitcnt lgkmcnt(0)
	v_mul_f32_e32 v158, v5, v201
	v_fmac_f32_e32 v158, v4, v200
	v_fmac_f32_e32 v158, v6, v202
	v_fmac_f32_e32 v158, v7, v203
	ds_read_b128 v[200:203], v9 offset:3472
	v_add_f32_e32 v158, v157, v158
	s_waitcnt lgkmcnt(0)
	v_mul_f32_e32 v159, v154, v201
	v_fmac_f32_e32 v159, v228, v200
	v_fmac_f32_e32 v159, v155, v202
	v_fmac_f32_e32 v159, v156, v203
	ds_read_b128 v[200:203], v9 offset:3488
	v_add_f32_e32 v158, v158, v159
	s_waitcnt lgkmcnt(0)
	v_mul_f32_e32 v159, v252, v201
	v_fmac_f32_e32 v159, v146, v200
	v_fmac_f32_e32 v159, v253, v202
	v_fmac_f32_e32 v159, v227, v203
	ds_read_b128 v[200:203], v9 offset:3504
	v_add_f32_e32 v158, v158, v159
	s_waitcnt lgkmcnt(0)
	v_mul_f32_e32 v159, v147, v201
	v_fmac_f32_e32 v159, v145, v200
	v_fmac_f32_e32 v159, v230, v202
	v_fmac_f32_e32 v159, v231, v203
	v_add_f32_e32 v158, v158, v159
	v_min_f32_e32 v159, 0, v158
	v_mul_f32_e64 v158, |v158|, s18
	v_exp_f32_e32 v158, v158
	ds_read_b128 v[202:205], v9 offset:3584
	v_add_f32_e32 v158, 1.0, v158
	v_cmp_gt_f32_e32 vcc, s71, v158
	s_nop 1
	v_cndmask_b32_e64 v160, 0, 32, vcc
	v_ldexp_f32 v158, v158, v160
	v_log_f32_e32 v158, v158
	s_nop 0
	v_mul_f32_e32 v160, 0x3f317217, v158
	v_fma_f32 v160, v158, s48, -v160
	v_fmac_f32_e32 v160, 0x3377d1cf, v158
	v_fmac_f32_e32 v160, 0x3f317217, v158
	v_cmp_lt_f32_e64 s[0:1], |v158|, s49
	s_nop 1
	v_cndmask_b32_e64 v158, v158, v160, s[0:1]
	v_cndmask_b32_e32 v160, 0, v233, vcc
	v_sub_f32_e32 v158, v158, v160
	v_sub_f32_e32 v158, v159, v158
	v_mul_f32_e32 v200, 0x3d800000, v158
	v_fmac_f32_e32 v141, 0x3d800000, v158
	s_waitcnt lgkmcnt(0)
	v_mul_f32_e32 v158, v5, v203
	v_fmac_f32_e32 v158, v4, v202
	v_fmac_f32_e32 v158, v6, v204
	v_fmac_f32_e32 v158, v7, v205
	ds_read_b128 v[202:205], v9 offset:3600
	v_add_f32_e32 v158, v157, v158
	s_waitcnt lgkmcnt(0)
	v_mul_f32_e32 v159, v154, v203
	v_fmac_f32_e32 v159, v228, v202
	v_fmac_f32_e32 v159, v155, v204
	v_fmac_f32_e32 v159, v156, v205
	ds_read_b128 v[202:205], v9 offset:3616
	v_add_f32_e32 v158, v158, v159
	s_waitcnt lgkmcnt(0)
	v_mul_f32_e32 v159, v252, v203
	v_fmac_f32_e32 v159, v146, v202
	v_fmac_f32_e32 v159, v253, v204
	v_fmac_f32_e32 v159, v227, v205
	ds_read_b128 v[202:205], v9 offset:3632
	v_add_f32_e32 v158, v158, v159
	s_waitcnt lgkmcnt(0)
	v_mul_f32_e32 v159, v147, v203
	v_fmac_f32_e32 v159, v145, v202
	v_fmac_f32_e32 v159, v230, v204
	v_fmac_f32_e32 v159, v231, v205
	v_add_f32_e32 v158, v158, v159
	v_min_f32_e32 v159, 0, v158
	v_mul_f32_e64 v158, |v158|, s18
	v_exp_f32_e32 v158, v158
	ds_read_b128 v[202:205], v9 offset:3712
	v_add_f32_e32 v158, 1.0, v158
	v_cmp_gt_f32_e32 vcc, s71, v158
	s_nop 1
	v_cndmask_b32_e64 v160, 0, 32, vcc
	v_ldexp_f32 v158, v158, v160
	v_log_f32_e32 v158, v158
	s_nop 0
	v_mul_f32_e32 v160, 0x3f317217, v158
	v_fma_f32 v160, v158, s48, -v160
	v_fmac_f32_e32 v160, 0x3377d1cf, v158
	v_fmac_f32_e32 v160, 0x3f317217, v158
	v_cmp_lt_f32_e64 s[0:1], |v158|, s49
	s_nop 1
	v_cndmask_b32_e64 v158, v158, v160, s[0:1]
	v_cndmask_b32_e32 v160, 0, v233, vcc
	v_sub_f32_e32 v158, v158, v160
	v_sub_f32_e32 v158, v159, v158
	v_mul_f32_e32 v201, 0x3d800000, v158
	v_fmac_f32_e32 v141, 0x3d800000, v158
	s_waitcnt lgkmcnt(0)
	v_mul_f32_e32 v158, v5, v203
	v_fmac_f32_e32 v158, v4, v202
	v_fmac_f32_e32 v158, v6, v204
	v_fmac_f32_e32 v158, v7, v205
	ds_read_b128 v[202:205], v9 offset:3728
	v_add_f32_e32 v158, v157, v158
	s_waitcnt lgkmcnt(0)
	v_mul_f32_e32 v159, v154, v203
	v_fmac_f32_e32 v159, v228, v202
	v_fmac_f32_e32 v159, v155, v204
	v_fmac_f32_e32 v159, v156, v205
	ds_read_b128 v[202:205], v9 offset:3744
	v_add_f32_e32 v158, v158, v159
	s_waitcnt lgkmcnt(0)
	v_mul_f32_e32 v159, v252, v203
	v_fmac_f32_e32 v159, v146, v202
	v_fmac_f32_e32 v159, v253, v204
	v_fmac_f32_e32 v159, v227, v205
	ds_read_b128 v[202:205], v9 offset:3760
	v_add_f32_e32 v158, v158, v159
	s_waitcnt lgkmcnt(0)
	v_mul_f32_e32 v159, v147, v203
	v_fmac_f32_e32 v159, v145, v202
	v_fmac_f32_e32 v159, v230, v204
	v_fmac_f32_e32 v159, v231, v205
	v_add_f32_e32 v158, v158, v159
	v_min_f32_e32 v159, 0, v158
	v_mul_f32_e64 v158, |v158|, s18
	v_exp_f32_e32 v158, v158
	ds_read_b128 v[204:207], v9 offset:3840
	v_add_f32_e32 v158, 1.0, v158
	v_cmp_gt_f32_e32 vcc, s71, v158
	s_nop 1
	v_cndmask_b32_e64 v160, 0, 32, vcc
	v_ldexp_f32 v158, v158, v160
	v_log_f32_e32 v158, v158
	s_nop 0
	v_mul_f32_e32 v160, 0x3f317217, v158
	v_fma_f32 v160, v158, s48, -v160
	v_fmac_f32_e32 v160, 0x3377d1cf, v158
	v_fmac_f32_e32 v160, 0x3f317217, v158
	v_cmp_lt_f32_e64 s[0:1], |v158|, s49
	s_nop 1
	v_cndmask_b32_e64 v158, v158, v160, s[0:1]
	v_cndmask_b32_e32 v160, 0, v233, vcc
	v_sub_f32_e32 v158, v158, v160
	v_sub_f32_e32 v158, v159, v158
	v_mul_f32_e32 v202, 0x3d800000, v158
	v_fmac_f32_e32 v141, 0x3d800000, v158
	s_waitcnt lgkmcnt(0)
	v_mul_f32_e32 v158, v5, v205
	v_fmac_f32_e32 v158, v4, v204
	v_fmac_f32_e32 v158, v6, v206
	v_fmac_f32_e32 v158, v7, v207
	ds_read_b128 v[204:207], v9 offset:3856
	v_add_f32_e32 v158, v157, v158
	s_waitcnt lgkmcnt(0)
	v_mul_f32_e32 v159, v154, v205
	v_fmac_f32_e32 v159, v228, v204
	v_fmac_f32_e32 v159, v155, v206
	v_fmac_f32_e32 v159, v156, v207
	ds_read_b128 v[204:207], v9 offset:3872
	v_add_f32_e32 v158, v158, v159
	s_waitcnt lgkmcnt(0)
	v_mul_f32_e32 v159, v252, v205
	v_fmac_f32_e32 v159, v146, v204
	v_fmac_f32_e32 v159, v253, v206
	v_fmac_f32_e32 v159, v227, v207
	ds_read_b128 v[204:207], v9 offset:3888
	v_add_f32_e32 v158, v158, v159
	s_waitcnt lgkmcnt(0)
	v_mul_f32_e32 v159, v147, v205
	v_fmac_f32_e32 v159, v145, v204
	v_fmac_f32_e32 v159, v230, v206
	v_fmac_f32_e32 v159, v231, v207
	v_add_f32_e32 v158, v158, v159
	v_min_f32_e32 v159, 0, v158
	v_mul_f32_e64 v158, |v158|, s18
	v_exp_f32_e32 v158, v158
	ds_read_b128 v[204:207], v9 offset:3968
	v_add_f32_e32 v158, 1.0, v158
	v_cmp_gt_f32_e32 vcc, s71, v158
	s_nop 1
	v_cndmask_b32_e64 v160, 0, 32, vcc
	v_ldexp_f32 v158, v158, v160
	v_log_f32_e32 v158, v158
	s_nop 0
	v_mul_f32_e32 v160, 0x3f317217, v158
	v_fma_f32 v160, v158, s48, -v160
	v_fmac_f32_e32 v160, 0x3377d1cf, v158
	v_fmac_f32_e32 v160, 0x3f317217, v158
	v_cmp_lt_f32_e64 s[0:1], |v158|, s49
	s_nop 1
	v_cndmask_b32_e64 v158, v158, v160, s[0:1]
	v_cndmask_b32_e32 v160, 0, v233, vcc
	v_sub_f32_e32 v158, v158, v160
	v_sub_f32_e32 v158, v159, v158
	v_mul_f32_e32 v203, 0x3d800000, v158
	v_fmac_f32_e32 v141, 0x3d800000, v158
	s_waitcnt lgkmcnt(0)
	v_mul_f32_e32 v158, v5, v205
	v_fmac_f32_e32 v158, v4, v204
	v_fmac_f32_e32 v158, v6, v206
	v_fmac_f32_e32 v158, v7, v207
	ds_read_b128 v[204:207], v9 offset:3984
	v_add_f32_e32 v158, v157, v158
	s_waitcnt lgkmcnt(0)
	v_mul_f32_e32 v159, v154, v205
	v_fmac_f32_e32 v159, v228, v204
	v_fmac_f32_e32 v159, v155, v206
	v_fmac_f32_e32 v159, v156, v207
	ds_read_b128 v[204:207], v9 offset:4000
	v_add_f32_e32 v158, v158, v159
	s_waitcnt lgkmcnt(0)
	v_mul_f32_e32 v159, v252, v205
	v_fmac_f32_e32 v159, v146, v204
	v_fmac_f32_e32 v159, v253, v206
	v_fmac_f32_e32 v159, v227, v207
	ds_read_b128 v[204:207], v9 offset:4016
	v_add_f32_e32 v158, v158, v159
	s_waitcnt lgkmcnt(0)
	v_mul_f32_e32 v159, v147, v205
	v_fmac_f32_e32 v159, v145, v204
	v_fmac_f32_e32 v159, v230, v206
	v_fmac_f32_e32 v159, v231, v207
	v_add_f32_e32 v158, v158, v159
	v_min_f32_e32 v159, 0, v158
	v_mul_f32_e64 v158, |v158|, s18
	v_exp_f32_e32 v158, v158
	ds_read_b128 v[206:209], v9 offset:4096
	v_add_f32_e32 v158, 1.0, v158
	v_cmp_gt_f32_e32 vcc, s71, v158
	s_nop 1
	v_cndmask_b32_e64 v160, 0, 32, vcc
	v_ldexp_f32 v158, v158, v160
	v_log_f32_e32 v158, v158
	s_nop 0
	v_mul_f32_e32 v160, 0x3f317217, v158
	v_fma_f32 v160, v158, s48, -v160
	v_fmac_f32_e32 v160, 0x3377d1cf, v158
	v_fmac_f32_e32 v160, 0x3f317217, v158
	v_cmp_lt_f32_e64 s[0:1], |v158|, s49
	s_nop 1
	v_cndmask_b32_e64 v158, v158, v160, s[0:1]
	v_cndmask_b32_e32 v160, 0, v233, vcc
	v_sub_f32_e32 v158, v158, v160
	v_sub_f32_e32 v158, v159, v158
	v_mul_f32_e32 v204, 0x3d800000, v158
	v_fmac_f32_e32 v141, 0x3d800000, v158
	s_waitcnt lgkmcnt(0)
	v_mul_f32_e32 v158, v5, v207
	v_fmac_f32_e32 v158, v4, v206
	v_fmac_f32_e32 v158, v6, v208
	v_fmac_f32_e32 v158, v7, v209
	ds_read_b128 v[206:209], v9 offset:4112
	v_add_f32_e32 v158, v157, v158
	s_waitcnt lgkmcnt(0)
	v_mul_f32_e32 v159, v154, v207
	v_fmac_f32_e32 v159, v228, v206
	v_fmac_f32_e32 v159, v155, v208
	v_fmac_f32_e32 v159, v156, v209
	ds_read_b128 v[206:209], v9 offset:4128
	v_add_f32_e32 v158, v158, v159
	s_waitcnt lgkmcnt(0)
	v_mul_f32_e32 v159, v252, v207
	v_fmac_f32_e32 v159, v146, v206
	v_fmac_f32_e32 v159, v253, v208
	v_fmac_f32_e32 v159, v227, v209
	ds_read_b128 v[206:209], v9 offset:4144
	v_add_f32_e32 v158, v158, v159
	s_waitcnt lgkmcnt(0)
	v_mul_f32_e32 v159, v147, v207
	v_fmac_f32_e32 v159, v145, v206
	v_fmac_f32_e32 v159, v230, v208
	v_fmac_f32_e32 v159, v231, v209
	v_add_f32_e32 v158, v158, v159
	v_min_f32_e32 v159, 0, v158
	v_mul_f32_e64 v158, |v158|, s18
	v_exp_f32_e32 v158, v158
	ds_read_b128 v[206:209], v9 offset:4224
	v_add_f32_e32 v158, 1.0, v158
	v_cmp_gt_f32_e32 vcc, s71, v158
	s_nop 1
	v_cndmask_b32_e64 v160, 0, 32, vcc
	v_ldexp_f32 v158, v158, v160
	v_log_f32_e32 v158, v158
	s_nop 0
	v_mul_f32_e32 v160, 0x3f317217, v158
	v_fma_f32 v160, v158, s48, -v160
	v_fmac_f32_e32 v160, 0x3377d1cf, v158
	v_fmac_f32_e32 v160, 0x3f317217, v158
	v_cmp_lt_f32_e64 s[0:1], |v158|, s49
	s_nop 1
	v_cndmask_b32_e64 v158, v158, v160, s[0:1]
	v_cndmask_b32_e32 v160, 0, v233, vcc
	v_sub_f32_e32 v158, v158, v160
	v_sub_f32_e32 v158, v159, v158
	v_mul_f32_e32 v205, 0x3d800000, v158
	v_fmac_f32_e32 v141, 0x3d800000, v158
	s_waitcnt lgkmcnt(0)
	v_mul_f32_e32 v158, v5, v207
	v_fmac_f32_e32 v158, v4, v206
	v_fmac_f32_e32 v158, v6, v208
	v_fmac_f32_e32 v158, v7, v209
	ds_read_b128 v[206:209], v9 offset:4240
	v_add_f32_e32 v158, v157, v158
	s_waitcnt lgkmcnt(0)
	v_mul_f32_e32 v159, v154, v207
	v_fmac_f32_e32 v159, v228, v206
	v_fmac_f32_e32 v159, v155, v208
	v_fmac_f32_e32 v159, v156, v209
	ds_read_b128 v[206:209], v9 offset:4256
	v_add_f32_e32 v158, v158, v159
	s_waitcnt lgkmcnt(0)
	v_mul_f32_e32 v159, v252, v207
	v_fmac_f32_e32 v159, v146, v206
	v_fmac_f32_e32 v159, v253, v208
	v_fmac_f32_e32 v159, v227, v209
	ds_read_b128 v[206:209], v9 offset:4272
	v_add_f32_e32 v158, v158, v159
	s_waitcnt lgkmcnt(0)
	v_mul_f32_e32 v159, v147, v207
	v_fmac_f32_e32 v159, v145, v206
	v_fmac_f32_e32 v159, v230, v208
	v_fmac_f32_e32 v159, v231, v209
	v_add_f32_e32 v158, v158, v159
	v_min_f32_e32 v159, 0, v158
	v_mul_f32_e64 v158, |v158|, s18
	v_exp_f32_e32 v158, v158
	ds_read_b128 v[208:211], v9 offset:4352
	v_add_f32_e32 v158, 1.0, v158
	v_cmp_gt_f32_e32 vcc, s71, v158
	s_nop 1
	v_cndmask_b32_e64 v160, 0, 32, vcc
	v_ldexp_f32 v158, v158, v160
	v_log_f32_e32 v158, v158
	s_nop 0
	v_mul_f32_e32 v160, 0x3f317217, v158
	v_fma_f32 v160, v158, s48, -v160
	v_fmac_f32_e32 v160, 0x3377d1cf, v158
	v_fmac_f32_e32 v160, 0x3f317217, v158
	v_cmp_lt_f32_e64 s[0:1], |v158|, s49
	s_nop 1
	v_cndmask_b32_e64 v158, v158, v160, s[0:1]
	v_cndmask_b32_e32 v160, 0, v233, vcc
	v_sub_f32_e32 v158, v158, v160
	v_sub_f32_e32 v158, v159, v158
	v_mul_f32_e32 v207, 0x3d800000, v158
	v_fmac_f32_e32 v141, 0x3d800000, v158
	s_waitcnt lgkmcnt(0)
	v_mul_f32_e32 v158, v5, v209
	v_fmac_f32_e32 v158, v4, v208
	v_fmac_f32_e32 v158, v6, v210
	v_fmac_f32_e32 v158, v7, v211
	ds_read_b128 v[208:211], v9 offset:4368
	v_add_f32_e32 v158, v157, v158
	s_waitcnt lgkmcnt(0)
	v_mul_f32_e32 v159, v154, v209
	v_fmac_f32_e32 v159, v228, v208
	v_fmac_f32_e32 v159, v155, v210
	v_fmac_f32_e32 v159, v156, v211
	ds_read_b128 v[208:211], v9 offset:4384
	v_add_f32_e32 v158, v158, v159
	s_waitcnt lgkmcnt(0)
	v_mul_f32_e32 v159, v252, v209
	v_fmac_f32_e32 v159, v146, v208
	v_fmac_f32_e32 v159, v253, v210
	v_fmac_f32_e32 v159, v227, v211
	ds_read_b128 v[208:211], v9 offset:4400
	v_add_f32_e32 v158, v158, v159
	s_waitcnt lgkmcnt(0)
	v_mul_f32_e32 v159, v147, v209
	v_fmac_f32_e32 v159, v145, v208
	v_fmac_f32_e32 v159, v230, v210
	v_fmac_f32_e32 v159, v231, v211
	v_add_f32_e32 v158, v158, v159
	v_min_f32_e32 v159, 0, v158
	v_mul_f32_e64 v158, |v158|, s18
	v_exp_f32_e32 v158, v158
	s_nop 0
	v_add_f32_e32 v158, 1.0, v158
	v_cmp_gt_f32_e32 vcc, s71, v158
	s_nop 1
	v_cndmask_b32_e64 v160, 0, 32, vcc
	v_ldexp_f32 v158, v158, v160
	v_log_f32_e32 v158, v158
	s_nop 0
	v_mul_f32_e32 v160, 0x3f317217, v158
	v_fma_f32 v160, v158, s48, -v160
	v_fmac_f32_e32 v160, 0x3377d1cf, v158
	v_fmac_f32_e32 v160, 0x3f317217, v158
	v_cmp_lt_f32_e64 s[0:1], |v158|, s49
	s_nop 1
	v_cndmask_b32_e64 v158, v158, v160, s[0:1]
	v_cndmask_b32_e32 v160, 0, v233, vcc
	v_sub_f32_e32 v158, v158, v160
	v_sub_f32_e32 v158, v159, v158
	v_mul_f32_e32 v210, 0x3d800000, v158
	v_fmac_f32_e32 v141, 0x3d800000, v158
	v_mul_f32_e32 v158, v5, v213
	v_fmac_f32_e32 v158, v4, v212
	v_fmac_f32_e32 v158, v6, v214
	v_fmac_f32_e32 v158, v7, v215
	ds_read_b128 v[212:215], v9 offset:4496
	v_add_f32_e32 v158, v157, v158
	s_waitcnt lgkmcnt(0)
	v_mul_f32_e32 v159, v154, v213
	v_fmac_f32_e32 v159, v228, v212
	v_fmac_f32_e32 v159, v155, v214
	v_fmac_f32_e32 v159, v156, v215
	ds_read_b128 v[212:215], v9 offset:4512
	v_add_f32_e32 v158, v158, v159
	s_waitcnt lgkmcnt(0)
	v_mul_f32_e32 v159, v252, v213
	v_fmac_f32_e32 v159, v146, v212
	v_fmac_f32_e32 v159, v253, v214
	v_fmac_f32_e32 v159, v227, v215
	ds_read_b128 v[212:215], v9 offset:4528
	v_add_f32_e32 v158, v158, v159
	s_waitcnt lgkmcnt(0)
	v_mul_f32_e32 v159, v147, v213
	v_fmac_f32_e32 v159, v145, v212
	v_fmac_f32_e32 v159, v230, v214
	v_fmac_f32_e32 v159, v231, v215
	v_add_f32_e32 v158, v158, v159
	v_min_f32_e32 v159, 0, v158
	v_mul_f32_e64 v158, |v158|, s18
	v_exp_f32_e32 v158, v158
	ds_read_b128 v[214:217], v9 offset:4608
	v_add_f32_e32 v158, 1.0, v158
	v_cmp_gt_f32_e32 vcc, s71, v158
	s_nop 1
	v_cndmask_b32_e64 v160, 0, 32, vcc
	v_ldexp_f32 v158, v158, v160
	v_log_f32_e32 v158, v158
	s_nop 0
	v_mul_f32_e32 v160, 0x3f317217, v158
	v_fma_f32 v160, v158, s48, -v160
	v_fmac_f32_e32 v160, 0x3377d1cf, v158
	v_fmac_f32_e32 v160, 0x3f317217, v158
	v_cmp_lt_f32_e64 s[0:1], |v158|, s49
	s_nop 1
	v_cndmask_b32_e64 v158, v158, v160, s[0:1]
	v_cndmask_b32_e32 v160, 0, v233, vcc
	v_sub_f32_e32 v158, v158, v160
	v_sub_f32_e32 v158, v159, v158
	v_mul_f32_e32 v212, 0x3d800000, v158
	v_fmac_f32_e32 v141, 0x3d800000, v158
	s_waitcnt lgkmcnt(0)
	v_mul_f32_e32 v158, v5, v215
	v_fmac_f32_e32 v158, v4, v214
	v_fmac_f32_e32 v158, v6, v216
	v_fmac_f32_e32 v158, v7, v217
	ds_read_b128 v[214:217], v9 offset:4624
	v_add_f32_e32 v158, v157, v158
	s_waitcnt lgkmcnt(0)
	v_mul_f32_e32 v159, v154, v215
	v_fmac_f32_e32 v159, v228, v214
	v_fmac_f32_e32 v159, v155, v216
	v_fmac_f32_e32 v159, v156, v217
	ds_read_b128 v[214:217], v9 offset:4640
	v_add_f32_e32 v158, v158, v159
	s_waitcnt lgkmcnt(0)
	v_mul_f32_e32 v159, v252, v215
	v_fmac_f32_e32 v159, v146, v214
	v_fmac_f32_e32 v159, v253, v216
	v_fmac_f32_e32 v159, v227, v217
	ds_read_b128 v[214:217], v9 offset:4656
	v_add_f32_e32 v158, v158, v159
	s_waitcnt lgkmcnt(0)
	v_mul_f32_e32 v159, v147, v215
	v_fmac_f32_e32 v159, v145, v214
	v_fmac_f32_e32 v159, v230, v216
	v_fmac_f32_e32 v159, v231, v217
	v_add_f32_e32 v158, v158, v159
	v_min_f32_e32 v159, 0, v158
	v_mul_f32_e64 v158, |v158|, s18
	v_exp_f32_e32 v158, v158
	ds_read_b128 v[214:217], v9 offset:4736
	v_add_f32_e32 v158, 1.0, v158
	v_cmp_gt_f32_e32 vcc, s71, v158
	s_nop 1
	v_cndmask_b32_e64 v160, 0, 32, vcc
	v_ldexp_f32 v158, v158, v160
	v_log_f32_e32 v158, v158
	s_nop 0
	v_mul_f32_e32 v160, 0x3f317217, v158
	v_fma_f32 v160, v158, s48, -v160
	v_fmac_f32_e32 v160, 0x3377d1cf, v158
	v_fmac_f32_e32 v160, 0x3f317217, v158
	v_cmp_lt_f32_e64 s[0:1], |v158|, s49
	s_nop 1
	v_cndmask_b32_e64 v158, v158, v160, s[0:1]
	v_cndmask_b32_e32 v160, 0, v233, vcc
	v_sub_f32_e32 v158, v158, v160
	v_sub_f32_e32 v158, v159, v158
	v_mul_f32_e32 v206, 0x3d800000, v158
	v_fmac_f32_e32 v141, 0x3d800000, v158
	s_waitcnt lgkmcnt(0)
	v_mul_f32_e32 v158, v5, v215
	v_fmac_f32_e32 v158, v4, v214
	v_fmac_f32_e32 v158, v6, v216
	v_fmac_f32_e32 v158, v7, v217
	ds_read_b128 v[214:217], v9 offset:4752
	v_add_f32_e32 v158, v157, v158
	s_waitcnt lgkmcnt(0)
	v_mul_f32_e32 v159, v154, v215
	v_fmac_f32_e32 v159, v228, v214
	v_fmac_f32_e32 v159, v155, v216
	v_fmac_f32_e32 v159, v156, v217
	ds_read_b128 v[214:217], v9 offset:4768
	v_add_f32_e32 v158, v158, v159
	s_waitcnt lgkmcnt(0)
	v_mul_f32_e32 v159, v252, v215
	v_fmac_f32_e32 v159, v146, v214
	v_fmac_f32_e32 v159, v253, v216
	v_fmac_f32_e32 v159, v227, v217
	ds_read_b128 v[214:217], v9 offset:4784
	v_add_f32_e32 v158, v158, v159
	s_waitcnt lgkmcnt(0)
	v_mul_f32_e32 v159, v147, v215
	v_fmac_f32_e32 v159, v145, v214
	v_fmac_f32_e32 v159, v230, v216
	v_fmac_f32_e32 v159, v231, v217
	v_add_f32_e32 v158, v158, v159
	v_min_f32_e32 v159, 0, v158
	v_mul_f32_e64 v158, |v158|, s18
	v_exp_f32_e32 v158, v158
	ds_read_b128 v[214:217], v9 offset:4864
	v_add_f32_e32 v158, 1.0, v158
	v_cmp_gt_f32_e32 vcc, s71, v158
	s_nop 1
	v_cndmask_b32_e64 v160, 0, 32, vcc
	v_ldexp_f32 v158, v158, v160
	v_log_f32_e32 v158, v158
	s_nop 0
	v_mul_f32_e32 v160, 0x3f317217, v158
	v_fma_f32 v160, v158, s48, -v160
	v_fmac_f32_e32 v160, 0x3377d1cf, v158
	v_fmac_f32_e32 v160, 0x3f317217, v158
	v_cmp_lt_f32_e64 s[0:1], |v158|, s49
	s_nop 1
	v_cndmask_b32_e64 v158, v158, v160, s[0:1]
	v_cndmask_b32_e32 v160, 0, v233, vcc
	v_sub_f32_e32 v158, v158, v160
	v_sub_f32_e32 v158, v159, v158
	v_mul_f32_e32 v209, 0x3d800000, v158
	v_fmac_f32_e32 v141, 0x3d800000, v158
	s_waitcnt lgkmcnt(0)
	v_mul_f32_e32 v158, v5, v215
	v_fmac_f32_e32 v158, v4, v214
	v_fmac_f32_e32 v158, v6, v216
	v_fmac_f32_e32 v158, v7, v217
	ds_read_b128 v[214:217], v9 offset:4880
	v_add_f32_e32 v158, v157, v158
	s_waitcnt lgkmcnt(0)
	v_mul_f32_e32 v159, v154, v215
	v_fmac_f32_e32 v159, v228, v214
	v_fmac_f32_e32 v159, v155, v216
	v_fmac_f32_e32 v159, v156, v217
	ds_read_b128 v[214:217], v9 offset:4896
	v_add_f32_e32 v158, v158, v159
	s_waitcnt lgkmcnt(0)
	v_mul_f32_e32 v159, v252, v215
	v_fmac_f32_e32 v159, v146, v214
	v_fmac_f32_e32 v159, v253, v216
	v_fmac_f32_e32 v159, v227, v217
	ds_read_b128 v[214:217], v9 offset:4912
	v_add_f32_e32 v158, v158, v159
	s_waitcnt lgkmcnt(0)
	v_mul_f32_e32 v159, v147, v215
	v_fmac_f32_e32 v159, v145, v214
	v_fmac_f32_e32 v159, v230, v216
	v_fmac_f32_e32 v159, v231, v217
	v_add_f32_e32 v158, v158, v159
	v_min_f32_e32 v159, 0, v158
	v_mul_f32_e64 v158, |v158|, s18
	v_exp_f32_e32 v158, v158
	s_nop 0
	v_add_f32_e32 v158, 1.0, v158
	v_cmp_gt_f32_e32 vcc, s71, v158
	s_nop 1
	v_cndmask_b32_e64 v160, 0, 32, vcc
	v_ldexp_f32 v158, v158, v160
	v_log_f32_e32 v158, v158
	s_nop 0
	v_mul_f32_e32 v160, 0x3f317217, v158
	v_fma_f32 v160, v158, s48, -v160
	v_fmac_f32_e32 v160, 0x3377d1cf, v158
	v_fmac_f32_e32 v160, 0x3f317217, v158
	v_cmp_lt_f32_e64 s[0:1], |v158|, s49
	s_nop 1
	v_cndmask_b32_e64 v158, v158, v160, s[0:1]
	v_cndmask_b32_e32 v160, 0, v233, vcc
	v_sub_f32_e32 v158, v158, v160
	v_sub_f32_e32 v158, v159, v158
	v_mul_f32_e32 v214, 0x3d800000, v158
	v_fmac_f32_e32 v141, 0x3d800000, v158
	v_mul_f32_e32 v158, v5, v235
	v_fmac_f32_e32 v158, v4, v234
	v_fmac_f32_e32 v158, v6, v236
	v_fmac_f32_e32 v158, v7, v237
	ds_read_b128 v[234:237], v9 offset:5008
	v_add_f32_e32 v158, v157, v158
	s_waitcnt lgkmcnt(0)
	v_mul_f32_e32 v159, v154, v235
	v_fmac_f32_e32 v159, v228, v234
	v_fmac_f32_e32 v159, v155, v236
	v_fmac_f32_e32 v159, v156, v237
	ds_read_b128 v[234:237], v9 offset:5024
	v_add_f32_e32 v158, v158, v159
	s_waitcnt lgkmcnt(0)
	v_mul_f32_e32 v159, v252, v235
	v_fmac_f32_e32 v159, v146, v234
	v_fmac_f32_e32 v159, v253, v236
	v_fmac_f32_e32 v159, v227, v237
	ds_read_b128 v[234:237], v9 offset:5040
	v_add_f32_e32 v158, v158, v159
	s_waitcnt lgkmcnt(0)
	v_mul_f32_e32 v159, v147, v235
	v_fmac_f32_e32 v159, v145, v234
	v_fmac_f32_e32 v159, v230, v236
	v_fmac_f32_e32 v159, v231, v237
	v_add_f32_e32 v158, v158, v159
	v_min_f32_e32 v159, 0, v158
	v_mul_f32_e64 v158, |v158|, s18
	v_exp_f32_e32 v158, v158
	ds_read_b128 v[234:237], v9 offset:5120
	v_add_f32_e32 v158, 1.0, v158
	v_cmp_gt_f32_e32 vcc, s71, v158
	s_nop 1
	v_cndmask_b32_e64 v160, 0, 32, vcc
	v_ldexp_f32 v158, v158, v160
	v_log_f32_e32 v158, v158
	s_nop 0
	v_mul_f32_e32 v160, 0x3f317217, v158
	v_fma_f32 v160, v158, s48, -v160
	v_fmac_f32_e32 v160, 0x3377d1cf, v158
	v_fmac_f32_e32 v160, 0x3f317217, v158
	v_cmp_lt_f32_e64 s[0:1], |v158|, s49
	s_nop 1
	v_cndmask_b32_e64 v158, v158, v160, s[0:1]
	v_cndmask_b32_e32 v160, 0, v233, vcc
	v_sub_f32_e32 v158, v158, v160
	v_sub_f32_e32 v158, v159, v158
	v_mul_f32_e32 v216, 0x3d800000, v158
	v_fmac_f32_e32 v141, 0x3d800000, v158
	s_waitcnt lgkmcnt(0)
	v_mul_f32_e32 v158, v5, v235
	v_fmac_f32_e32 v158, v4, v234
	v_fmac_f32_e32 v158, v6, v236
	v_fmac_f32_e32 v158, v7, v237
	ds_read_b128 v[234:237], v9 offset:5136
	v_add_f32_e32 v158, v157, v158
	s_waitcnt lgkmcnt(0)
	v_mul_f32_e32 v159, v154, v235
	v_fmac_f32_e32 v159, v228, v234
	v_fmac_f32_e32 v159, v155, v236
	v_fmac_f32_e32 v159, v156, v237
	ds_read_b128 v[234:237], v9 offset:5152
	v_add_f32_e32 v158, v158, v159
	s_waitcnt lgkmcnt(0)
	v_mul_f32_e32 v159, v252, v235
	v_fmac_f32_e32 v159, v146, v234
	v_fmac_f32_e32 v159, v253, v236
	v_fmac_f32_e32 v159, v227, v237
	ds_read_b128 v[234:237], v9 offset:5168
	v_add_f32_e32 v158, v158, v159
	s_waitcnt lgkmcnt(0)
	v_mul_f32_e32 v159, v147, v235
	v_fmac_f32_e32 v159, v145, v234
	v_fmac_f32_e32 v159, v230, v236
	v_fmac_f32_e32 v159, v231, v237
	v_add_f32_e32 v158, v158, v159
	v_min_f32_e32 v159, 0, v158
	v_mul_f32_e64 v158, |v158|, s18
	v_exp_f32_e32 v158, v158
	ds_read_b128 v[234:237], v9 offset:5248
	v_add_f32_e32 v158, 1.0, v158
	v_cmp_gt_f32_e32 vcc, s71, v158
	s_nop 1
	v_cndmask_b32_e64 v160, 0, 32, vcc
	v_ldexp_f32 v158, v158, v160
	v_log_f32_e32 v158, v158
	s_nop 0
	v_mul_f32_e32 v160, 0x3f317217, v158
	v_fma_f32 v160, v158, s48, -v160
	v_fmac_f32_e32 v160, 0x3377d1cf, v158
	v_fmac_f32_e32 v160, 0x3f317217, v158
	v_cmp_lt_f32_e64 s[0:1], |v158|, s49
	s_nop 1
	v_cndmask_b32_e64 v158, v158, v160, s[0:1]
	v_cndmask_b32_e32 v160, 0, v233, vcc
	v_sub_f32_e32 v158, v158, v160
	v_sub_f32_e32 v158, v159, v158
	v_mul_f32_e32 v208, 0x3d800000, v158
	v_fmac_f32_e32 v141, 0x3d800000, v158
	s_waitcnt lgkmcnt(0)
	v_mul_f32_e32 v158, v5, v235
	v_fmac_f32_e32 v158, v4, v234
	v_fmac_f32_e32 v158, v6, v236
	v_fmac_f32_e32 v158, v7, v237
	ds_read_b128 v[234:237], v9 offset:5264
	v_add_f32_e32 v158, v157, v158
	s_waitcnt lgkmcnt(0)
	v_mul_f32_e32 v159, v154, v235
	v_fmac_f32_e32 v159, v228, v234
	v_fmac_f32_e32 v159, v155, v236
	v_fmac_f32_e32 v159, v156, v237
	ds_read_b128 v[234:237], v9 offset:5280
	v_add_f32_e32 v158, v158, v159
	s_waitcnt lgkmcnt(0)
	v_mul_f32_e32 v159, v252, v235
	v_fmac_f32_e32 v159, v146, v234
	v_fmac_f32_e32 v159, v253, v236
	v_fmac_f32_e32 v159, v227, v237
	ds_read_b128 v[234:237], v9 offset:5296
	v_add_f32_e32 v158, v158, v159
	s_waitcnt lgkmcnt(0)
	v_mul_f32_e32 v159, v147, v235
	v_fmac_f32_e32 v159, v145, v234
	v_fmac_f32_e32 v159, v230, v236
	v_fmac_f32_e32 v159, v231, v237
	v_add_f32_e32 v158, v158, v159
	v_min_f32_e32 v159, 0, v158
	v_mul_f32_e64 v158, |v158|, s18
	v_exp_f32_e32 v158, v158
	ds_read_b128 v[234:237], v9 offset:5376
	v_add_f32_e32 v158, 1.0, v158
	v_cmp_gt_f32_e32 vcc, s71, v158
	s_nop 1
	v_cndmask_b32_e64 v160, 0, 32, vcc
	v_ldexp_f32 v158, v158, v160
	v_log_f32_e32 v158, v158
	s_nop 0
	v_mul_f32_e32 v160, 0x3f317217, v158
	v_fma_f32 v160, v158, s48, -v160
	v_fmac_f32_e32 v160, 0x3377d1cf, v158
	v_fmac_f32_e32 v160, 0x3f317217, v158
	v_cmp_lt_f32_e64 s[0:1], |v158|, s49
	s_nop 1
	v_cndmask_b32_e64 v158, v158, v160, s[0:1]
	v_cndmask_b32_e32 v160, 0, v233, vcc
	v_sub_f32_e32 v158, v158, v160
	v_sub_f32_e32 v158, v159, v158
	v_mul_f32_e32 v213, 0x3d800000, v158
	v_fmac_f32_e32 v141, 0x3d800000, v158
	s_waitcnt lgkmcnt(0)
	v_mul_f32_e32 v158, v5, v235
	v_fmac_f32_e32 v158, v4, v234
	v_fmac_f32_e32 v158, v6, v236
	v_fmac_f32_e32 v158, v7, v237
	ds_read_b128 v[234:237], v9 offset:5392
	v_add_f32_e32 v158, v157, v158
	s_waitcnt lgkmcnt(0)
	v_mul_f32_e32 v159, v154, v235
	v_fmac_f32_e32 v159, v228, v234
	v_fmac_f32_e32 v159, v155, v236
	v_fmac_f32_e32 v159, v156, v237
	ds_read_b128 v[234:237], v9 offset:5408
	v_add_f32_e32 v158, v158, v159
	s_waitcnt lgkmcnt(0)
	v_mul_f32_e32 v159, v252, v235
	v_fmac_f32_e32 v159, v146, v234
	v_fmac_f32_e32 v159, v253, v236
	v_fmac_f32_e32 v159, v227, v237
	ds_read_b128 v[234:237], v9 offset:5424
	v_add_f32_e32 v158, v158, v159
	s_waitcnt lgkmcnt(0)
	v_mul_f32_e32 v159, v147, v235
	v_fmac_f32_e32 v159, v145, v234
	v_fmac_f32_e32 v159, v230, v236
	v_fmac_f32_e32 v159, v231, v237
	v_add_f32_e32 v158, v158, v159
	v_min_f32_e32 v159, 0, v158
	v_mul_f32_e64 v158, |v158|, s18
	v_exp_f32_e32 v158, v158
	ds_read_b128 v[236:239], v9 offset:5504
	v_add_f32_e32 v158, 1.0, v158
	v_cmp_gt_f32_e32 vcc, s71, v158
	s_nop 1
	v_cndmask_b32_e64 v160, 0, 32, vcc
	v_ldexp_f32 v158, v158, v160
	v_log_f32_e32 v158, v158
	s_nop 0
	v_mul_f32_e32 v160, 0x3f317217, v158
	v_fma_f32 v160, v158, s48, -v160
	v_fmac_f32_e32 v160, 0x3377d1cf, v158
	v_fmac_f32_e32 v160, 0x3f317217, v158
	v_cmp_lt_f32_e64 s[0:1], |v158|, s49
	s_nop 1
	v_cndmask_b32_e64 v158, v158, v160, s[0:1]
	v_cndmask_b32_e32 v160, 0, v233, vcc
	v_sub_f32_e32 v158, v158, v160
	v_sub_f32_e32 v158, v159, v158
	v_mul_f32_e32 v234, 0x3d800000, v158
	v_fmac_f32_e32 v141, 0x3d800000, v158
	s_waitcnt lgkmcnt(0)
	v_mul_f32_e32 v158, v5, v237
	v_fmac_f32_e32 v158, v4, v236
	v_fmac_f32_e32 v158, v6, v238
	v_fmac_f32_e32 v158, v7, v239
	ds_read_b128 v[236:239], v9 offset:5520
	v_add_f32_e32 v158, v157, v158
	s_waitcnt lgkmcnt(0)
	v_mul_f32_e32 v159, v154, v237
	v_fmac_f32_e32 v159, v228, v236
	v_fmac_f32_e32 v159, v155, v238
	v_fmac_f32_e32 v159, v156, v239
	ds_read_b128 v[236:239], v9 offset:5536
	v_add_f32_e32 v158, v158, v159
	s_waitcnt lgkmcnt(0)
	v_mul_f32_e32 v159, v252, v237
	v_fmac_f32_e32 v159, v146, v236
	v_fmac_f32_e32 v159, v253, v238
	v_fmac_f32_e32 v159, v227, v239
	ds_read_b128 v[236:239], v9 offset:5552
	v_add_f32_e32 v158, v158, v159
	s_waitcnt lgkmcnt(0)
	v_mul_f32_e32 v159, v147, v237
	v_fmac_f32_e32 v159, v145, v236
	v_fmac_f32_e32 v159, v230, v238
	v_fmac_f32_e32 v159, v231, v239
	v_add_f32_e32 v158, v158, v159
	v_min_f32_e32 v159, 0, v158
	v_mul_f32_e64 v158, |v158|, s18
	v_exp_f32_e32 v158, v158
	ds_read_b128 v[238:241], v9 offset:5632
	v_add_f32_e32 v158, 1.0, v158
	v_cmp_gt_f32_e32 vcc, s71, v158
	s_nop 1
	v_cndmask_b32_e64 v160, 0, 32, vcc
	v_ldexp_f32 v158, v158, v160
	v_log_f32_e32 v158, v158
	s_nop 0
	v_mul_f32_e32 v160, 0x3f317217, v158
	v_fma_f32 v160, v158, s48, -v160
	v_fmac_f32_e32 v160, 0x3377d1cf, v158
	v_fmac_f32_e32 v160, 0x3f317217, v158
	v_cmp_lt_f32_e64 s[0:1], |v158|, s49
	s_nop 1
	v_cndmask_b32_e64 v158, v158, v160, s[0:1]
	v_cndmask_b32_e32 v160, 0, v233, vcc
	v_sub_f32_e32 v158, v158, v160
	v_sub_f32_e32 v158, v159, v158
	v_mul_f32_e32 v236, 0x3d800000, v158
	v_fmac_f32_e32 v141, 0x3d800000, v158
	s_waitcnt lgkmcnt(0)
	v_mul_f32_e32 v158, v5, v239
	v_fmac_f32_e32 v158, v4, v238
	v_fmac_f32_e32 v158, v6, v240
	v_fmac_f32_e32 v158, v7, v241
	ds_read_b128 v[238:241], v9 offset:5648
	v_add_f32_e32 v158, v157, v158
	s_waitcnt lgkmcnt(0)
	v_mul_f32_e32 v159, v154, v239
	v_fmac_f32_e32 v159, v228, v238
	v_fmac_f32_e32 v159, v155, v240
	v_fmac_f32_e32 v159, v156, v241
	ds_read_b128 v[238:241], v9 offset:5664
	v_add_f32_e32 v158, v158, v159
	s_waitcnt lgkmcnt(0)
	v_mul_f32_e32 v159, v252, v239
	v_fmac_f32_e32 v159, v146, v238
	v_fmac_f32_e32 v159, v253, v240
	v_fmac_f32_e32 v159, v227, v241
	ds_read_b128 v[238:241], v9 offset:5680
	v_add_f32_e32 v158, v158, v159
	s_waitcnt lgkmcnt(0)
	v_mul_f32_e32 v159, v147, v239
	v_fmac_f32_e32 v159, v145, v238
	v_fmac_f32_e32 v159, v230, v240
	v_fmac_f32_e32 v159, v231, v241
	v_add_f32_e32 v158, v158, v159
	v_min_f32_e32 v159, 0, v158
	v_mul_f32_e64 v158, |v158|, s18
	v_exp_f32_e32 v158, v158
	ds_read_b128 v[238:241], v9 offset:5760
	v_add_f32_e32 v158, 1.0, v158
	v_cmp_gt_f32_e32 vcc, s71, v158
	s_nop 1
	v_cndmask_b32_e64 v160, 0, 32, vcc
	v_ldexp_f32 v158, v158, v160
	v_log_f32_e32 v158, v158
	s_nop 0
	v_mul_f32_e32 v160, 0x3f317217, v158
	v_fma_f32 v160, v158, s48, -v160
	v_fmac_f32_e32 v160, 0x3377d1cf, v158
	v_fmac_f32_e32 v160, 0x3f317217, v158
	v_cmp_lt_f32_e64 s[0:1], |v158|, s49
	s_nop 1
	v_cndmask_b32_e64 v158, v158, v160, s[0:1]
	v_cndmask_b32_e32 v160, 0, v233, vcc
	v_sub_f32_e32 v158, v158, v160
	v_sub_f32_e32 v158, v159, v158
	v_mul_f32_e32 v211, 0x3d800000, v158
	v_fmac_f32_e32 v141, 0x3d800000, v158
	s_waitcnt lgkmcnt(0)
	v_mul_f32_e32 v158, v5, v239
	v_fmac_f32_e32 v158, v4, v238
	v_fmac_f32_e32 v158, v6, v240
	v_fmac_f32_e32 v158, v7, v241
	ds_read_b128 v[238:241], v9 offset:5776
	v_add_f32_e32 v158, v157, v158
	s_waitcnt lgkmcnt(0)
	v_mul_f32_e32 v159, v154, v239
	v_fmac_f32_e32 v159, v228, v238
	v_fmac_f32_e32 v159, v155, v240
	v_fmac_f32_e32 v159, v156, v241
	ds_read_b128 v[238:241], v9 offset:5792
	v_add_f32_e32 v158, v158, v159
	s_waitcnt lgkmcnt(0)
	v_mul_f32_e32 v159, v252, v239
	v_fmac_f32_e32 v159, v146, v238
	v_fmac_f32_e32 v159, v253, v240
	v_fmac_f32_e32 v159, v227, v241
	ds_read_b128 v[238:241], v9 offset:5808
	v_add_f32_e32 v158, v158, v159
	s_waitcnt lgkmcnt(0)
	v_mul_f32_e32 v159, v147, v239
	v_fmac_f32_e32 v159, v145, v238
	v_fmac_f32_e32 v159, v230, v240
	v_fmac_f32_e32 v159, v231, v241
	v_add_f32_e32 v158, v158, v159
	v_min_f32_e32 v159, 0, v158
	v_mul_f32_e64 v158, |v158|, s18
	v_exp_f32_e32 v158, v158
	ds_read_b128 v[238:241], v9 offset:5888
	v_add_f32_e32 v158, 1.0, v158
	v_cmp_gt_f32_e32 vcc, s71, v158
	s_nop 1
	v_cndmask_b32_e64 v160, 0, 32, vcc
	v_ldexp_f32 v158, v158, v160
	v_log_f32_e32 v158, v158
	s_nop 0
	v_mul_f32_e32 v160, 0x3f317217, v158
	v_fma_f32 v160, v158, s48, -v160
	v_fmac_f32_e32 v160, 0x3377d1cf, v158
	v_fmac_f32_e32 v160, 0x3f317217, v158
	v_cmp_lt_f32_e64 s[0:1], |v158|, s49
	s_nop 1
	v_cndmask_b32_e64 v158, v158, v160, s[0:1]
	v_cndmask_b32_e32 v160, 0, v233, vcc
	v_sub_f32_e32 v158, v158, v160
	v_sub_f32_e32 v158, v159, v158
	v_mul_f32_e32 v217, 0x3d800000, v158
	v_fmac_f32_e32 v141, 0x3d800000, v158
	s_waitcnt lgkmcnt(0)
	v_mul_f32_e32 v158, v5, v239
	v_fmac_f32_e32 v158, v4, v238
	v_fmac_f32_e32 v158, v6, v240
	v_fmac_f32_e32 v158, v7, v241
	ds_read_b128 v[238:241], v9 offset:5904
	v_add_f32_e32 v158, v157, v158
	s_waitcnt lgkmcnt(0)
	v_mul_f32_e32 v159, v154, v239
	v_fmac_f32_e32 v159, v228, v238
	v_fmac_f32_e32 v159, v155, v240
	v_fmac_f32_e32 v159, v156, v241
	ds_read_b128 v[238:241], v9 offset:5920
	v_add_f32_e32 v158, v158, v159
	s_waitcnt lgkmcnt(0)
	v_mul_f32_e32 v159, v252, v239
	v_fmac_f32_e32 v159, v146, v238
	v_fmac_f32_e32 v159, v253, v240
	v_fmac_f32_e32 v159, v227, v241
	ds_read_b128 v[238:241], v9 offset:5936
	v_add_f32_e32 v158, v158, v159
	s_waitcnt lgkmcnt(0)
	v_mul_f32_e32 v159, v147, v239
	v_fmac_f32_e32 v159, v145, v238
	v_fmac_f32_e32 v159, v230, v240
	v_fmac_f32_e32 v159, v231, v241
	v_add_f32_e32 v158, v158, v159
	v_min_f32_e32 v159, 0, v158
	v_mul_f32_e64 v158, |v158|, s18
	v_exp_f32_e32 v158, v158
	ds_read_b128 v[240:243], v9 offset:6016
	v_add_f32_e32 v158, 1.0, v158
	v_cmp_gt_f32_e32 vcc, s71, v158
	s_nop 1
	v_cndmask_b32_e64 v160, 0, 32, vcc
	v_ldexp_f32 v158, v158, v160
	v_log_f32_e32 v158, v158
	s_nop 0
	v_mul_f32_e32 v160, 0x3f317217, v158
	v_fma_f32 v160, v158, s48, -v160
	v_fmac_f32_e32 v160, 0x3377d1cf, v158
	v_fmac_f32_e32 v160, 0x3f317217, v158
	v_cmp_lt_f32_e64 s[0:1], |v158|, s49
	s_nop 1
	v_cndmask_b32_e64 v158, v158, v160, s[0:1]
	v_cndmask_b32_e32 v160, 0, v233, vcc
	v_sub_f32_e32 v158, v158, v160
	v_sub_f32_e32 v158, v159, v158
	v_mul_f32_e32 v238, 0x3d800000, v158
	v_fmac_f32_e32 v141, 0x3d800000, v158
	s_waitcnt lgkmcnt(0)
	v_mul_f32_e32 v158, v5, v241
	v_fmac_f32_e32 v158, v4, v240
	v_fmac_f32_e32 v158, v6, v242
	v_fmac_f32_e32 v158, v7, v243
	ds_read_b128 v[240:243], v9 offset:6032
	v_add_f32_e32 v158, v157, v158
	s_waitcnt lgkmcnt(0)
	v_mul_f32_e32 v159, v154, v241
	v_fmac_f32_e32 v159, v228, v240
	v_fmac_f32_e32 v159, v155, v242
	v_fmac_f32_e32 v159, v156, v243
	ds_read_b128 v[240:243], v9 offset:6048
	v_add_f32_e32 v158, v158, v159
	s_waitcnt lgkmcnt(0)
	v_mul_f32_e32 v159, v252, v241
	v_fmac_f32_e32 v159, v146, v240
	v_fmac_f32_e32 v159, v253, v242
	v_fmac_f32_e32 v159, v227, v243
	ds_read_b128 v[240:243], v9 offset:6064
	v_add_f32_e32 v158, v158, v159
	s_waitcnt lgkmcnt(0)
	v_mul_f32_e32 v159, v147, v241
	v_fmac_f32_e32 v159, v145, v240
	v_fmac_f32_e32 v159, v230, v242
	v_fmac_f32_e32 v159, v231, v243
	v_add_f32_e32 v158, v158, v159
	v_min_f32_e32 v159, 0, v158
	v_mul_f32_e64 v158, |v158|, s18
	v_exp_f32_e32 v158, v158
	ds_read_b128 v[242:245], v9 offset:6144
	v_add_f32_e32 v158, 1.0, v158
	v_cmp_gt_f32_e32 vcc, s71, v158
	s_nop 1
	v_cndmask_b32_e64 v160, 0, 32, vcc
	v_ldexp_f32 v158, v158, v160
	v_log_f32_e32 v158, v158
	s_nop 0
	v_mul_f32_e32 v160, 0x3f317217, v158
	v_fma_f32 v160, v158, s48, -v160
	v_fmac_f32_e32 v160, 0x3377d1cf, v158
	v_fmac_f32_e32 v160, 0x3f317217, v158
	v_cmp_lt_f32_e64 s[0:1], |v158|, s49
	s_nop 1
	v_cndmask_b32_e64 v158, v158, v160, s[0:1]
	v_cndmask_b32_e32 v160, 0, v233, vcc
	v_sub_f32_e32 v158, v158, v160
	v_sub_f32_e32 v158, v159, v158
	v_mul_f32_e32 v240, 0x3d800000, v158
	v_fmac_f32_e32 v141, 0x3d800000, v158
	s_waitcnt lgkmcnt(0)
	v_mul_f32_e32 v158, v5, v243
	v_fmac_f32_e32 v158, v4, v242
	v_fmac_f32_e32 v158, v6, v244
	v_fmac_f32_e32 v158, v7, v245
	ds_read_b128 v[242:245], v9 offset:6160
	v_add_f32_e32 v158, v157, v158
	s_waitcnt lgkmcnt(0)
	v_mul_f32_e32 v159, v154, v243
	v_fmac_f32_e32 v159, v228, v242
	v_fmac_f32_e32 v159, v155, v244
	v_fmac_f32_e32 v159, v156, v245
	ds_read_b128 v[242:245], v9 offset:6176
	v_add_f32_e32 v158, v158, v159
	s_waitcnt lgkmcnt(0)
	v_mul_f32_e32 v159, v252, v243
	v_fmac_f32_e32 v159, v146, v242
	v_fmac_f32_e32 v159, v253, v244
	v_fmac_f32_e32 v159, v227, v245
	ds_read_b128 v[242:245], v9 offset:6192
	v_add_f32_e32 v158, v158, v159
	s_waitcnt lgkmcnt(0)
	v_mul_f32_e32 v159, v147, v243
	v_fmac_f32_e32 v159, v145, v242
	v_fmac_f32_e32 v159, v230, v244
	v_fmac_f32_e32 v159, v231, v245
	v_add_f32_e32 v158, v158, v159
	v_min_f32_e32 v159, 0, v158
	v_mul_f32_e64 v158, |v158|, s18
	v_exp_f32_e32 v158, v158
	ds_read_b128 v[242:245], v9 offset:6272
	v_add_f32_e32 v158, 1.0, v158
	v_cmp_gt_f32_e32 vcc, s71, v158
	s_nop 1
	v_cndmask_b32_e64 v160, 0, 32, vcc
	v_ldexp_f32 v158, v158, v160
	v_log_f32_e32 v158, v158
	s_nop 0
	v_mul_f32_e32 v160, 0x3f317217, v158
	v_fma_f32 v160, v158, s48, -v160
	v_fmac_f32_e32 v160, 0x3377d1cf, v158
	v_fmac_f32_e32 v160, 0x3f317217, v158
	v_cmp_lt_f32_e64 s[0:1], |v158|, s49
	s_nop 1
	v_cndmask_b32_e64 v158, v158, v160, s[0:1]
	v_cndmask_b32_e32 v160, 0, v233, vcc
	v_sub_f32_e32 v158, v158, v160
	v_sub_f32_e32 v158, v159, v158
	v_mul_f32_e32 v215, 0x3d800000, v158
	v_fmac_f32_e32 v141, 0x3d800000, v158
	s_waitcnt lgkmcnt(0)
	v_mul_f32_e32 v158, v5, v243
	v_fmac_f32_e32 v158, v4, v242
	v_fmac_f32_e32 v158, v6, v244
	v_fmac_f32_e32 v158, v7, v245
	ds_read_b128 v[242:245], v9 offset:6288
	v_add_f32_e32 v158, v157, v158
	s_waitcnt lgkmcnt(0)
	v_mul_f32_e32 v159, v154, v243
	v_fmac_f32_e32 v159, v228, v242
	v_fmac_f32_e32 v159, v155, v244
	v_fmac_f32_e32 v159, v156, v245
	ds_read_b128 v[242:245], v9 offset:6304
	v_add_f32_e32 v158, v158, v159
	s_waitcnt lgkmcnt(0)
	v_mul_f32_e32 v159, v252, v243
	v_fmac_f32_e32 v159, v146, v242
	v_fmac_f32_e32 v159, v253, v244
	v_fmac_f32_e32 v159, v227, v245
	ds_read_b128 v[242:245], v9 offset:6320
	v_add_f32_e32 v158, v158, v159
	s_waitcnt lgkmcnt(0)
	v_mul_f32_e32 v159, v147, v243
	v_fmac_f32_e32 v159, v145, v242
	v_fmac_f32_e32 v159, v230, v244
	v_fmac_f32_e32 v159, v231, v245
	v_add_f32_e32 v158, v158, v159
	v_min_f32_e32 v159, 0, v158
	v_mul_f32_e64 v158, |v158|, s18
	v_exp_f32_e32 v158, v158
	ds_read_b128 v[242:245], v9 offset:6400
	v_add_f32_e32 v158, 1.0, v158
	v_cmp_gt_f32_e32 vcc, s71, v158
	s_nop 1
	v_cndmask_b32_e64 v160, 0, 32, vcc
	v_ldexp_f32 v158, v158, v160
	v_log_f32_e32 v158, v158
	s_nop 0
	v_mul_f32_e32 v160, 0x3f317217, v158
	v_fma_f32 v160, v158, s48, -v160
	v_fmac_f32_e32 v160, 0x3377d1cf, v158
	v_fmac_f32_e32 v160, 0x3f317217, v158
	v_cmp_lt_f32_e64 s[0:1], |v158|, s49
	s_nop 1
	v_cndmask_b32_e64 v158, v158, v160, s[0:1]
	v_cndmask_b32_e32 v160, 0, v233, vcc
	v_sub_f32_e32 v158, v158, v160
	v_sub_f32_e32 v158, v159, v158
	v_mul_f32_e32 v237, 0x3d800000, v158
	v_fmac_f32_e32 v141, 0x3d800000, v158
	s_waitcnt lgkmcnt(0)
	v_mul_f32_e32 v158, v5, v243
	v_fmac_f32_e32 v158, v4, v242
	v_fmac_f32_e32 v158, v6, v244
	v_fmac_f32_e32 v158, v7, v245
	ds_read_b128 v[242:245], v9 offset:6416
	v_add_f32_e32 v158, v157, v158
	s_waitcnt lgkmcnt(0)
	v_mul_f32_e32 v159, v154, v243
	v_fmac_f32_e32 v159, v228, v242
	v_fmac_f32_e32 v159, v155, v244
	v_fmac_f32_e32 v159, v156, v245
	ds_read_b128 v[242:245], v9 offset:6432
	v_add_f32_e32 v158, v158, v159
	s_waitcnt lgkmcnt(0)
	v_mul_f32_e32 v159, v252, v243
	v_fmac_f32_e32 v159, v146, v242
	v_fmac_f32_e32 v159, v253, v244
	v_fmac_f32_e32 v159, v227, v245
	ds_read_b128 v[242:245], v9 offset:6448
	v_add_f32_e32 v158, v158, v159
	s_waitcnt lgkmcnt(0)
	v_mul_f32_e32 v159, v147, v243
	v_fmac_f32_e32 v159, v145, v242
	v_fmac_f32_e32 v159, v230, v244
	v_fmac_f32_e32 v159, v231, v245
	v_add_f32_e32 v158, v158, v159
	v_min_f32_e32 v159, 0, v158
	v_mul_f32_e64 v158, |v158|, s18
	v_exp_f32_e32 v158, v158
	ds_read_b128 v[244:247], v9 offset:6528
	v_add_f32_e32 v158, 1.0, v158
	v_cmp_gt_f32_e32 vcc, s71, v158
	s_nop 1
	v_cndmask_b32_e64 v160, 0, 32, vcc
	v_ldexp_f32 v158, v158, v160
	v_log_f32_e32 v158, v158
	s_nop 0
	v_mul_f32_e32 v160, 0x3f317217, v158
	v_fma_f32 v160, v158, s48, -v160
	v_fmac_f32_e32 v160, 0x3377d1cf, v158
	v_fmac_f32_e32 v160, 0x3f317217, v158
	v_cmp_lt_f32_e64 s[0:1], |v158|, s49
	s_nop 1
	v_cndmask_b32_e64 v158, v158, v160, s[0:1]
	v_cndmask_b32_e32 v160, 0, v233, vcc
	v_sub_f32_e32 v158, v158, v160
	v_sub_f32_e32 v158, v159, v158
	v_mul_f32_e32 v242, 0x3d800000, v158
	v_fmac_f32_e32 v141, 0x3d800000, v158
	s_waitcnt lgkmcnt(0)
	v_mul_f32_e32 v158, v5, v245
	v_fmac_f32_e32 v158, v4, v244
	v_fmac_f32_e32 v158, v6, v246
	v_fmac_f32_e32 v158, v7, v247
	ds_read_b128 v[244:247], v9 offset:6544
	v_add_f32_e32 v158, v157, v158
	s_waitcnt lgkmcnt(0)
	v_mul_f32_e32 v159, v154, v245
	v_fmac_f32_e32 v159, v228, v244
	v_fmac_f32_e32 v159, v155, v246
	v_fmac_f32_e32 v159, v156, v247
	ds_read_b128 v[244:247], v9 offset:6560
	v_add_f32_e32 v158, v158, v159
	s_waitcnt lgkmcnt(0)
	v_mul_f32_e32 v159, v252, v245
	v_fmac_f32_e32 v159, v146, v244
	v_fmac_f32_e32 v159, v253, v246
	v_fmac_f32_e32 v159, v227, v247
	ds_read_b128 v[244:247], v9 offset:6576
	v_add_f32_e32 v158, v158, v159
	s_waitcnt lgkmcnt(0)
	v_mul_f32_e32 v159, v147, v245
	v_fmac_f32_e32 v159, v145, v244
	v_fmac_f32_e32 v159, v230, v246
	v_fmac_f32_e32 v159, v231, v247
	v_add_f32_e32 v158, v158, v159
	v_min_f32_e32 v159, 0, v158
	v_mul_f32_e64 v158, |v158|, s18
	v_exp_f32_e32 v158, v158
	ds_read_b128 v[246:249], v9 offset:6656
	v_add_f32_e32 v158, 1.0, v158
	v_cmp_gt_f32_e32 vcc, s71, v158
	s_nop 1
	v_cndmask_b32_e64 v160, 0, 32, vcc
	v_ldexp_f32 v158, v158, v160
	v_log_f32_e32 v158, v158
	s_nop 0
	v_mul_f32_e32 v160, 0x3f317217, v158
	v_fma_f32 v160, v158, s48, -v160
	v_fmac_f32_e32 v160, 0x3377d1cf, v158
	v_fmac_f32_e32 v160, 0x3f317217, v158
	v_cmp_lt_f32_e64 s[0:1], |v158|, s49
	s_nop 1
	v_cndmask_b32_e64 v158, v158, v160, s[0:1]
	v_cndmask_b32_e32 v160, 0, v233, vcc
	v_sub_f32_e32 v158, v158, v160
	v_sub_f32_e32 v158, v159, v158
	v_mul_f32_e32 v244, 0x3d800000, v158
	v_fmac_f32_e32 v141, 0x3d800000, v158
	s_waitcnt lgkmcnt(0)
	v_mul_f32_e32 v158, v5, v247
	v_fmac_f32_e32 v158, v4, v246
	v_fmac_f32_e32 v158, v6, v248
	v_fmac_f32_e32 v158, v7, v249
	ds_read_b128 v[246:249], v9 offset:6672
	v_add_f32_e32 v158, v157, v158
	s_waitcnt lgkmcnt(0)
	v_mul_f32_e32 v159, v154, v247
	v_fmac_f32_e32 v159, v228, v246
	v_fmac_f32_e32 v159, v155, v248
	v_fmac_f32_e32 v159, v156, v249
	ds_read_b128 v[246:249], v9 offset:6688
	v_add_f32_e32 v158, v158, v159
	s_waitcnt lgkmcnt(0)
	v_mul_f32_e32 v159, v252, v247
	v_fmac_f32_e32 v159, v146, v246
	v_fmac_f32_e32 v159, v253, v248
	v_fmac_f32_e32 v159, v227, v249
	ds_read_b128 v[246:249], v9 offset:6704
	v_add_f32_e32 v158, v158, v159
	s_waitcnt lgkmcnt(0)
	v_mul_f32_e32 v159, v147, v247
	v_fmac_f32_e32 v159, v145, v246
	v_fmac_f32_e32 v159, v230, v248
	v_fmac_f32_e32 v159, v231, v249
	v_add_f32_e32 v158, v158, v159
	v_min_f32_e32 v159, 0, v158
	v_mul_f32_e64 v158, |v158|, s18
	v_exp_f32_e32 v158, v158
	ds_read_b128 v[246:249], v9 offset:6784
	v_add_f32_e32 v158, 1.0, v158
	v_cmp_gt_f32_e32 vcc, s71, v158
	s_nop 1
	v_cndmask_b32_e64 v160, 0, 32, vcc
	v_ldexp_f32 v158, v158, v160
	v_log_f32_e32 v158, v158
	s_nop 0
	v_mul_f32_e32 v160, 0x3f317217, v158
	v_fma_f32 v160, v158, s48, -v160
	v_fmac_f32_e32 v160, 0x3377d1cf, v158
	v_fmac_f32_e32 v160, 0x3f317217, v158
	v_cmp_lt_f32_e64 s[0:1], |v158|, s49
	s_nop 1
	v_cndmask_b32_e64 v158, v158, v160, s[0:1]
	v_cndmask_b32_e32 v160, 0, v233, vcc
	v_sub_f32_e32 v158, v158, v160
	v_sub_f32_e32 v158, v159, v158
	v_mul_f32_e32 v235, 0x3d800000, v158
	v_fmac_f32_e32 v141, 0x3d800000, v158
	s_waitcnt lgkmcnt(0)
	v_mul_f32_e32 v158, v5, v247
	v_fmac_f32_e32 v158, v4, v246
	v_fmac_f32_e32 v158, v6, v248
	v_fmac_f32_e32 v158, v7, v249
	ds_read_b128 v[246:249], v9 offset:6800
	v_add_f32_e32 v158, v157, v158
	s_waitcnt lgkmcnt(0)
	v_mul_f32_e32 v159, v154, v247
	v_fmac_f32_e32 v159, v228, v246
	v_fmac_f32_e32 v159, v155, v248
	v_fmac_f32_e32 v159, v156, v249
	ds_read_b128 v[246:249], v9 offset:6816
	v_add_f32_e32 v158, v158, v159
	s_waitcnt lgkmcnt(0)
	v_mul_f32_e32 v159, v252, v247
	v_fmac_f32_e32 v159, v146, v246
	v_fmac_f32_e32 v159, v253, v248
	v_fmac_f32_e32 v159, v227, v249
	ds_read_b128 v[246:249], v9 offset:6832
	v_add_f32_e32 v158, v158, v159
	s_waitcnt lgkmcnt(0)
	v_mul_f32_e32 v159, v147, v247
	v_fmac_f32_e32 v159, v145, v246
	v_fmac_f32_e32 v159, v230, v248
	v_fmac_f32_e32 v159, v231, v249
	v_add_f32_e32 v158, v158, v159
	v_min_f32_e32 v159, 0, v158
	v_mul_f32_e64 v158, |v158|, s18
	v_exp_f32_e32 v158, v158
	ds_read_b128 v[246:249], v9 offset:6912
	v_add_f32_e32 v158, 1.0, v158
	v_cmp_gt_f32_e32 vcc, s71, v158
	s_nop 1
	v_cndmask_b32_e64 v160, 0, 32, vcc
	v_ldexp_f32 v158, v158, v160
	v_log_f32_e32 v158, v158
	s_nop 0
	v_mul_f32_e32 v160, 0x3f317217, v158
	v_fma_f32 v160, v158, s48, -v160
	v_fmac_f32_e32 v160, 0x3377d1cf, v158
	v_fmac_f32_e32 v160, 0x3f317217, v158
	v_cmp_lt_f32_e64 s[0:1], |v158|, s49
	s_nop 1
	v_cndmask_b32_e64 v158, v158, v160, s[0:1]
	v_cndmask_b32_e32 v160, 0, v233, vcc
	v_sub_f32_e32 v158, v158, v160
	v_sub_f32_e32 v158, v159, v158
	v_mul_f32_e32 v241, 0x3d800000, v158
	v_fmac_f32_e32 v141, 0x3d800000, v158
	s_waitcnt lgkmcnt(0)
	v_mul_f32_e32 v158, v5, v247
	v_fmac_f32_e32 v158, v4, v246
	v_fmac_f32_e32 v158, v6, v248
	v_fmac_f32_e32 v158, v7, v249
	ds_read_b128 v[246:249], v9 offset:6928
	v_add_f32_e32 v158, v157, v158
	s_waitcnt lgkmcnt(0)
	v_mul_f32_e32 v159, v154, v247
	v_fmac_f32_e32 v159, v228, v246
	v_fmac_f32_e32 v159, v155, v248
	v_fmac_f32_e32 v159, v156, v249
	ds_read_b128 v[246:249], v9 offset:6944
	v_add_f32_e32 v158, v158, v159
	s_waitcnt lgkmcnt(0)
	v_mul_f32_e32 v159, v252, v247
	v_fmac_f32_e32 v159, v146, v246
	v_fmac_f32_e32 v159, v253, v248
	v_fmac_f32_e32 v159, v227, v249
	ds_read_b128 v[246:249], v9 offset:6960
	v_add_f32_e32 v158, v158, v159
	s_waitcnt lgkmcnt(0)
	v_mul_f32_e32 v159, v147, v247
	v_fmac_f32_e32 v159, v145, v246
	v_fmac_f32_e32 v159, v230, v248
	v_fmac_f32_e32 v159, v231, v249
	v_add_f32_e32 v158, v158, v159
	v_min_f32_e32 v159, 0, v158
	v_mul_f32_e64 v158, |v158|, s18
	v_exp_f32_e32 v158, v158
	ds_read_b128 v[248:251], v9 offset:7040
	v_add_f32_e32 v158, 1.0, v158
	v_cmp_gt_f32_e32 vcc, s71, v158
	s_nop 1
	v_cndmask_b32_e64 v160, 0, 32, vcc
	v_ldexp_f32 v158, v158, v160
	v_log_f32_e32 v158, v158
	s_nop 0
	v_mul_f32_e32 v160, 0x3f317217, v158
	v_fma_f32 v160, v158, s48, -v160
	v_fmac_f32_e32 v160, 0x3377d1cf, v158
	v_fmac_f32_e32 v160, 0x3f317217, v158
	v_cmp_lt_f32_e64 s[0:1], |v158|, s49
	s_nop 1
	v_cndmask_b32_e64 v158, v158, v160, s[0:1]
	v_cndmask_b32_e32 v160, 0, v233, vcc
	v_sub_f32_e32 v158, v158, v160
	v_sub_f32_e32 v158, v159, v158
	v_mul_f32_e32 v246, 0x3d800000, v158
	v_fmac_f32_e32 v141, 0x3d800000, v158
	s_waitcnt lgkmcnt(0)
	v_mul_f32_e32 v158, v5, v249
	v_fmac_f32_e32 v158, v4, v248
	v_fmac_f32_e32 v158, v6, v250
	v_fmac_f32_e32 v158, v7, v251
	ds_read_b128 v[248:251], v9 offset:7056
	v_add_f32_e32 v158, v157, v158
	s_waitcnt lgkmcnt(0)
	v_mul_f32_e32 v159, v154, v249
	v_fmac_f32_e32 v159, v228, v248
	v_fmac_f32_e32 v159, v155, v250
	v_fmac_f32_e32 v159, v156, v251
	ds_read_b128 v[248:251], v9 offset:7072
	v_add_f32_e32 v158, v158, v159
	s_waitcnt lgkmcnt(0)
	v_mul_f32_e32 v159, v252, v249
	v_fmac_f32_e32 v159, v146, v248
	v_fmac_f32_e32 v159, v253, v250
	v_fmac_f32_e32 v159, v227, v251
	ds_read_b128 v[248:251], v9 offset:7088
	v_add_f32_e32 v158, v158, v159
	s_waitcnt lgkmcnt(0)
	v_mul_f32_e32 v159, v147, v249
	v_fmac_f32_e32 v159, v145, v248
	v_fmac_f32_e32 v159, v230, v250
	v_fmac_f32_e32 v159, v231, v251
	v_add_f32_e32 v158, v158, v159
	v_min_f32_e32 v159, 0, v158
	v_mul_f32_e64 v158, |v158|, s18
	v_exp_f32_e32 v158, v158
	ds_read_b128 v[248:251], v9 offset:7168
	v_add_f32_e32 v158, 1.0, v158
	v_cmp_gt_f32_e32 vcc, s71, v158
	s_nop 1
	v_cndmask_b32_e64 v160, 0, 32, vcc
	v_ldexp_f32 v158, v158, v160
	v_log_f32_e32 v158, v158
	s_nop 0
	v_mul_f32_e32 v160, 0x3f317217, v158
	v_fma_f32 v160, v158, s48, -v160
	v_fmac_f32_e32 v160, 0x3377d1cf, v158
	v_fmac_f32_e32 v160, 0x3f317217, v158
	v_cmp_lt_f32_e64 s[0:1], |v158|, s49
	s_nop 1
	v_cndmask_b32_e64 v158, v158, v160, s[0:1]
	v_cndmask_b32_e32 v160, 0, v233, vcc
	v_sub_f32_e32 v158, v158, v160
	v_sub_f32_e32 v158, v159, v158
	v_mul_f32_e32 v247, 0x3d800000, v158
	v_fmac_f32_e32 v141, 0x3d800000, v158
	s_waitcnt lgkmcnt(0)
	v_mul_f32_e32 v158, v5, v249
	v_fmac_f32_e32 v158, v4, v248
	v_fmac_f32_e32 v158, v6, v250
	v_fmac_f32_e32 v158, v7, v251
	ds_read_b128 v[248:251], v9 offset:7184
	v_add_f32_e32 v158, v157, v158
	s_waitcnt lgkmcnt(0)
	v_mul_f32_e32 v159, v154, v249
	v_fmac_f32_e32 v159, v228, v248
	v_fmac_f32_e32 v159, v155, v250
	v_fmac_f32_e32 v159, v156, v251
	ds_read_b128 v[248:251], v9 offset:7200
	v_add_f32_e32 v158, v158, v159
	s_waitcnt lgkmcnt(0)
	v_mul_f32_e32 v159, v252, v249
	v_fmac_f32_e32 v159, v146, v248
	v_fmac_f32_e32 v159, v253, v250
	v_fmac_f32_e32 v159, v227, v251
	ds_read_b128 v[248:251], v9 offset:7216
	v_add_f32_e32 v158, v158, v159
	s_waitcnt lgkmcnt(0)
	v_mul_f32_e32 v159, v147, v249
	v_fmac_f32_e32 v159, v145, v248
	v_fmac_f32_e32 v159, v230, v250
	v_fmac_f32_e32 v159, v231, v251
	v_add_f32_e32 v158, v158, v159
	v_min_f32_e32 v159, 0, v158
	v_mul_f32_e64 v158, |v158|, s18
	v_exp_f32_e32 v158, v158
	ds_read_b128 v[248:251], v9 offset:7296
	v_add_f32_e32 v158, 1.0, v158
	v_cmp_gt_f32_e32 vcc, s71, v158
	s_nop 1
	v_cndmask_b32_e64 v160, 0, 32, vcc
	v_ldexp_f32 v158, v158, v160
	v_log_f32_e32 v158, v158
	s_nop 0
	v_mul_f32_e32 v160, 0x3f317217, v158
	v_fma_f32 v160, v158, s48, -v160
	v_fmac_f32_e32 v160, 0x3377d1cf, v158
	v_fmac_f32_e32 v160, 0x3f317217, v158
	v_cmp_lt_f32_e64 s[0:1], |v158|, s49
	s_nop 1
	v_cndmask_b32_e64 v158, v158, v160, s[0:1]
	v_cndmask_b32_e32 v160, 0, v233, vcc
	v_sub_f32_e32 v158, v158, v160
	v_sub_f32_e32 v158, v159, v158
	v_mul_f32_e32 v239, 0x3d800000, v158
	v_fmac_f32_e32 v141, 0x3d800000, v158
	s_waitcnt lgkmcnt(0)
	v_mul_f32_e32 v158, v5, v249
	v_fmac_f32_e32 v158, v4, v248
	v_fmac_f32_e32 v158, v6, v250
	v_fmac_f32_e32 v158, v7, v251
	ds_read_b128 v[248:251], v9 offset:7312
	v_add_f32_e32 v158, v157, v158
	s_waitcnt lgkmcnt(0)
	v_mul_f32_e32 v159, v154, v249
	v_fmac_f32_e32 v159, v228, v248
	v_fmac_f32_e32 v159, v155, v250
	v_fmac_f32_e32 v159, v156, v251
	ds_read_b128 v[248:251], v9 offset:7328
	v_add_f32_e32 v158, v158, v159
	s_waitcnt lgkmcnt(0)
	v_mul_f32_e32 v159, v252, v249
	v_fmac_f32_e32 v159, v146, v248
	v_fmac_f32_e32 v159, v253, v250
	v_fmac_f32_e32 v159, v227, v251
	ds_read_b128 v[248:251], v9 offset:7344
	v_add_f32_e32 v158, v158, v159
	s_waitcnt lgkmcnt(0)
	v_mul_f32_e32 v159, v147, v249
	v_fmac_f32_e32 v159, v145, v248
	v_fmac_f32_e32 v159, v230, v250
	v_fmac_f32_e32 v159, v231, v251
	v_add_f32_e32 v158, v158, v159
	v_min_f32_e32 v159, 0, v158
	v_mul_f32_e64 v158, |v158|, s18
	v_exp_f32_e32 v158, v158
	ds_read_b128 v[248:251], v9 offset:7424
	v_add_f32_e32 v158, 1.0, v158
	v_cmp_gt_f32_e32 vcc, s71, v158
	s_nop 1
	v_cndmask_b32_e64 v160, 0, 32, vcc
	v_ldexp_f32 v158, v158, v160
	v_log_f32_e32 v158, v158
	s_nop 0
	v_mul_f32_e32 v160, 0x3f317217, v158
	v_fma_f32 v160, v158, s48, -v160
	v_fmac_f32_e32 v160, 0x3377d1cf, v158
	v_fmac_f32_e32 v160, 0x3f317217, v158
	v_cmp_lt_f32_e64 s[0:1], |v158|, s49
	s_nop 1
	v_cndmask_b32_e64 v158, v158, v160, s[0:1]
	v_cndmask_b32_e32 v160, 0, v233, vcc
	v_sub_f32_e32 v158, v158, v160
	v_sub_f32_e32 v158, v159, v158
	v_mul_f32_e32 v245, 0x3d800000, v158
	v_fmac_f32_e32 v141, 0x3d800000, v158
	s_waitcnt lgkmcnt(0)
	v_mul_f32_e32 v158, v5, v249
	v_fmac_f32_e32 v158, v4, v248
	v_fmac_f32_e32 v158, v6, v250
	v_fmac_f32_e32 v158, v7, v251
	ds_read_b128 v[248:251], v9 offset:7440
	v_add_f32_e32 v158, v157, v158
	s_waitcnt lgkmcnt(0)
	v_mul_f32_e32 v159, v154, v249
	v_fmac_f32_e32 v159, v228, v248
	v_fmac_f32_e32 v159, v155, v250
	v_fmac_f32_e32 v159, v156, v251
	ds_read_b128 v[248:251], v9 offset:7456
	v_add_f32_e32 v158, v158, v159
	s_waitcnt lgkmcnt(0)
	v_mul_f32_e32 v159, v252, v249
	v_fmac_f32_e32 v159, v146, v248
	v_fmac_f32_e32 v159, v253, v250
	v_fmac_f32_e32 v159, v227, v251
	ds_read_b128 v[248:251], v9 offset:7472
	v_add_f32_e32 v158, v158, v159
	s_waitcnt lgkmcnt(0)
	v_mul_f32_e32 v159, v147, v249
	v_fmac_f32_e32 v159, v145, v248
	v_fmac_f32_e32 v159, v230, v250
	v_fmac_f32_e32 v159, v231, v251
	v_add_f32_e32 v158, v158, v159
	v_min_f32_e32 v159, 0, v158
	v_mul_f32_e64 v158, |v158|, s18
	v_exp_f32_e32 v158, v158
	s_nop 0
	v_add_f32_e32 v158, 1.0, v158
	v_cmp_gt_f32_e32 vcc, s71, v158
	s_nop 1
	v_cndmask_b32_e64 v160, 0, 32, vcc
	v_ldexp_f32 v158, v158, v160
	v_log_f32_e32 v158, v158
	s_nop 0
	v_mul_f32_e32 v160, 0x3f317217, v158
	v_fma_f32 v160, v158, s48, -v160
	v_fmac_f32_e32 v160, 0x3377d1cf, v158
	v_fmac_f32_e32 v160, 0x3f317217, v158
	v_cmp_lt_f32_e64 s[0:1], |v158|, s49
	s_nop 1
	v_cndmask_b32_e64 v158, v158, v160, s[0:1]
	v_cndmask_b32_e32 v160, 0, v233, vcc
	v_sub_f32_e32 v158, v158, v160
	v_sub_f32_e32 v158, v159, v158
	v_mul_f32_e32 v249, 0x3d800000, v158
	v_fmac_f32_e32 v141, 0x3d800000, v158
	ds_read_b128 v[158:161], v9 offset:7552
	s_waitcnt lgkmcnt(0)
	v_mul_f32_e32 v159, v5, v159
	v_fmac_f32_e32 v159, v4, v158
	v_fmac_f32_e32 v159, v6, v160
	v_fmac_f32_e32 v159, v7, v161
	v_add_f32_e32 v243, v157, v159
	ds_read_b128 v[158:161], v9 offset:7568
	s_waitcnt lgkmcnt(0)
	v_mul_f32_e32 v159, v154, v159
	v_fmac_f32_e32 v159, v228, v158
	v_fmac_f32_e32 v159, v155, v160
	v_fmac_f32_e32 v159, v156, v161
	v_add_f32_e32 v243, v243, v159
	ds_read_b128 v[158:161], v9 offset:7584
	s_waitcnt lgkmcnt(0)
	v_mul_f32_e32 v159, v252, v159
	v_fmac_f32_e32 v159, v146, v158
	v_fmac_f32_e32 v159, v253, v160
	v_fmac_f32_e32 v159, v227, v161
	v_add_f32_e32 v243, v243, v159
	ds_read_b128 v[158:161], v9 offset:7600
	s_waitcnt lgkmcnt(0)
	v_mul_f32_e32 v159, v147, v159
	v_fmac_f32_e32 v159, v145, v158
	v_fmac_f32_e32 v159, v230, v160
	v_fmac_f32_e32 v159, v231, v161
	v_add_f32_e32 v158, v243, v159
	v_min_f32_e32 v159, 0, v158
	v_mul_f32_e64 v158, |v158|, s18
	v_exp_f32_e32 v158, v158
	s_nop 0
	v_add_f32_e32 v158, 1.0, v158
	v_cmp_gt_f32_e32 vcc, s71, v158
	s_nop 1
	v_cndmask_b32_e64 v160, 0, 32, vcc
	v_ldexp_f32 v158, v158, v160
	v_log_f32_e32 v158, v158
	s_nop 0
	v_mul_f32_e32 v160, 0x3f317217, v158
	v_fma_f32 v160, v158, s48, -v160
	v_fmac_f32_e32 v160, 0x3377d1cf, v158
	v_fmac_f32_e32 v160, 0x3f317217, v158
	v_cmp_lt_f32_e64 s[0:1], |v158|, s49
	s_nop 1
	v_cndmask_b32_e64 v158, v158, v160, s[0:1]
	v_cndmask_b32_e32 v160, 0, v233, vcc
	v_sub_f32_e32 v158, v158, v160
	v_sub_f32_e32 v158, v159, v158
	v_mul_f32_e32 v250, 0x3d800000, v158
	v_fmac_f32_e32 v141, 0x3d800000, v158
	ds_read_b128 v[158:161], v9 offset:7680
	s_waitcnt lgkmcnt(0)
	v_mul_f32_e32 v159, v5, v159
	v_fmac_f32_e32 v159, v4, v158
	v_fmac_f32_e32 v159, v6, v160
	v_fmac_f32_e32 v159, v7, v161
	v_add_f32_e32 v243, v157, v159
	ds_read_b128 v[158:161], v9 offset:7696
	s_waitcnt lgkmcnt(0)
	v_mul_f32_e32 v159, v154, v159
	v_fmac_f32_e32 v159, v228, v158
	v_fmac_f32_e32 v159, v155, v160
	v_fmac_f32_e32 v159, v156, v161
	v_add_f32_e32 v243, v243, v159
	ds_read_b128 v[158:161], v9 offset:7712
	s_waitcnt lgkmcnt(0)
	v_mul_f32_e32 v159, v252, v159
	v_fmac_f32_e32 v159, v146, v158
	v_fmac_f32_e32 v159, v253, v160
	v_fmac_f32_e32 v159, v227, v161
	v_add_f32_e32 v243, v243, v159
	ds_read_b128 v[158:161], v9 offset:7728
	s_waitcnt lgkmcnt(0)
	v_mul_f32_e32 v159, v147, v159
	v_fmac_f32_e32 v159, v145, v158
	v_fmac_f32_e32 v159, v230, v160
	v_fmac_f32_e32 v159, v231, v161
	v_add_f32_e32 v158, v243, v159
	v_min_f32_e32 v159, 0, v158
	v_mul_f32_e64 v158, |v158|, s18
	v_exp_f32_e32 v158, v158
	s_nop 0
	v_add_f32_e32 v158, 1.0, v158
	v_cmp_gt_f32_e32 vcc, s71, v158
	s_nop 1
	v_cndmask_b32_e64 v160, 0, 32, vcc
	v_ldexp_f32 v158, v158, v160
	v_log_f32_e32 v158, v158
	s_nop 0
	v_mul_f32_e32 v160, 0x3f317217, v158
	v_fma_f32 v160, v158, s48, -v160
	v_fmac_f32_e32 v160, 0x3377d1cf, v158
	v_fmac_f32_e32 v160, 0x3f317217, v158
	v_cmp_lt_f32_e64 s[0:1], |v158|, s49
	s_nop 1
	v_cndmask_b32_e64 v158, v158, v160, s[0:1]
	v_cndmask_b32_e32 v160, 0, v233, vcc
	v_sub_f32_e32 v158, v158, v160
	v_sub_f32_e32 v158, v159, v158
	v_mul_f32_e32 v243, 0x3d800000, v158
	v_fmac_f32_e32 v141, 0x3d800000, v158
	ds_read_b128 v[158:161], v9 offset:7808
	s_waitcnt lgkmcnt(0)
	v_mul_f32_e32 v159, v5, v159
	v_fmac_f32_e32 v159, v4, v158
	v_fmac_f32_e32 v159, v6, v160
	v_fmac_f32_e32 v159, v7, v161
	v_add_f32_e32 v248, v157, v159
	ds_read_b128 v[158:161], v9 offset:7824
	s_waitcnt lgkmcnt(0)
	v_mul_f32_e32 v159, v154, v159
	v_fmac_f32_e32 v159, v228, v158
	v_fmac_f32_e32 v159, v155, v160
	v_fmac_f32_e32 v159, v156, v161
	v_add_f32_e32 v248, v248, v159
	ds_read_b128 v[158:161], v9 offset:7840
	s_waitcnt lgkmcnt(0)
	v_mul_f32_e32 v159, v252, v159
	v_fmac_f32_e32 v159, v146, v158
	v_fmac_f32_e32 v159, v253, v160
	v_fmac_f32_e32 v159, v227, v161
	v_add_f32_e32 v248, v248, v159
	ds_read_b128 v[158:161], v9 offset:7856
	s_waitcnt lgkmcnt(0)
	v_mul_f32_e32 v159, v147, v159
	v_fmac_f32_e32 v159, v145, v158
	v_fmac_f32_e32 v159, v230, v160
	v_fmac_f32_e32 v159, v231, v161
	v_add_f32_e32 v158, v248, v159
	v_min_f32_e32 v159, 0, v158
	v_mul_f32_e64 v158, |v158|, s18
	v_exp_f32_e32 v158, v158
	s_nop 0
	v_add_f32_e32 v158, 1.0, v158
	v_cmp_gt_f32_e32 vcc, s71, v158
	s_nop 1
	v_cndmask_b32_e64 v160, 0, 32, vcc
	v_ldexp_f32 v158, v158, v160
	v_log_f32_e32 v158, v158
	s_nop 0
	v_mul_f32_e32 v160, 0x3f317217, v158
	v_fma_f32 v160, v158, s48, -v160
	v_fmac_f32_e32 v160, 0x3377d1cf, v158
	v_fmac_f32_e32 v160, 0x3f317217, v158
	v_cmp_lt_f32_e64 s[0:1], |v158|, s49
	s_nop 1
	v_cndmask_b32_e64 v158, v158, v160, s[0:1]
	v_cndmask_b32_e32 v160, 0, v233, vcc
	v_sub_f32_e32 v158, v158, v160
	v_sub_f32_e32 v158, v159, v158
	v_mul_f32_e32 v248, 0x3d800000, v158
	v_fmac_f32_e32 v141, 0x3d800000, v158
	ds_read_b128 v[158:161], v9 offset:7936
	s_waitcnt lgkmcnt(0)
	v_mul_f32_e32 v159, v5, v159
	v_fmac_f32_e32 v159, v4, v158
	v_fmac_f32_e32 v159, v6, v160
	v_fmac_f32_e32 v159, v7, v161
	v_add_f32_e32 v251, v157, v159
	ds_read_b128 v[158:161], v9 offset:7952
	s_waitcnt lgkmcnt(0)
	v_mul_f32_e32 v159, v154, v159
	v_fmac_f32_e32 v159, v228, v158
	v_fmac_f32_e32 v159, v155, v160
	v_fmac_f32_e32 v159, v156, v161
	v_add_f32_e32 v251, v251, v159
	ds_read_b128 v[158:161], v9 offset:7968
	s_waitcnt lgkmcnt(0)
	v_mul_f32_e32 v159, v252, v159
	v_fmac_f32_e32 v159, v146, v158
	v_fmac_f32_e32 v159, v253, v160
	v_fmac_f32_e32 v159, v227, v161
	v_add_f32_e32 v251, v251, v159
	ds_read_b128 v[158:161], v9 offset:7984
	s_waitcnt lgkmcnt(0)
	v_mul_f32_e32 v159, v147, v159
	v_fmac_f32_e32 v159, v145, v158
	v_fmac_f32_e32 v159, v230, v160
	v_fmac_f32_e32 v159, v231, v161
	v_add_f32_e32 v158, v251, v159
	v_min_f32_e32 v159, 0, v158
	v_mul_f32_e64 v158, |v158|, s18
	v_exp_f32_e32 v158, v158
	s_nop 0
	v_add_f32_e32 v158, 1.0, v158
	v_cmp_gt_f32_e32 vcc, s71, v158
	s_nop 1
	v_cndmask_b32_e64 v160, 0, 32, vcc
	v_ldexp_f32 v158, v158, v160
	v_log_f32_e32 v158, v158
	s_nop 0
	v_mul_f32_e32 v160, 0x3f317217, v158
	v_fma_f32 v160, v158, s48, -v160
	v_fmac_f32_e32 v160, 0x3377d1cf, v158
	v_fmac_f32_e32 v160, 0x3f317217, v158
	v_cmp_lt_f32_e64 s[0:1], |v158|, s49
	s_nop 1
	v_cndmask_b32_e64 v158, v158, v160, s[0:1]
	v_cndmask_b32_e32 v160, 0, v233, vcc
	v_sub_f32_e32 v158, v158, v160
	v_sub_f32_e32 v158, v159, v158
	v_mul_f32_e32 v251, 0x3d800000, v158
	v_fmac_f32_e32 v141, 0x3d800000, v158
	ds_read_b128 v[158:161], v9 offset:8064
	s_waitcnt lgkmcnt(0)
	v_mul_f32_e32 v5, v5, v159
	v_fmac_f32_e32 v5, v4, v158
	v_fmac_f32_e32 v5, v6, v160
	v_fmac_f32_e32 v5, v7, v161
	v_add_f32_e32 v157, v157, v5
	ds_read_b128 v[4:7], v9 offset:8080
	s_waitcnt lgkmcnt(0)
	v_mul_f32_e32 v5, v154, v5
	v_fmac_f32_e32 v5, v228, v4
	v_fmac_f32_e32 v5, v155, v6
	v_fmac_f32_e32 v5, v156, v7
	v_add_f32_e32 v4, v157, v5
	ds_read_b128 v[154:157], v9 offset:8096
	s_waitcnt lgkmcnt(0)
	v_mul_f32_e32 v5, v252, v155
	v_fmac_f32_e32 v5, v146, v154
	v_fmac_f32_e32 v5, v253, v156
	v_fmac_f32_e32 v5, v227, v157
	v_add_f32_e32 v146, v4, v5
	ds_read_b128 v[4:7], v9 offset:8112
	s_waitcnt lgkmcnt(0)
	v_mul_f32_e32 v5, v147, v5
	v_fmac_f32_e32 v5, v145, v4
	v_fmac_f32_e32 v5, v230, v6
	v_fmac_f32_e32 v5, v231, v7
	v_add_f32_e32 v4, v146, v5
	v_min_f32_e32 v5, 0, v4
	v_mul_f32_e64 v4, |v4|, s18
	v_exp_f32_e32 v4, v4
	v_ashrrev_i32_e32 v145, 31, v144
	v_mov_b32_e32 v147, v3
	v_add_f32_e32 v4, 1.0, v4
	v_cmp_gt_f32_e32 vcc, s71, v4
	s_nop 1
	v_cndmask_b32_e64 v6, 0, 32, vcc
	v_ldexp_f32 v4, v4, v6
	v_log_f32_e32 v4, v4
	s_nop 0
	v_mul_f32_e32 v6, 0x3f317217, v4
	v_fma_f32 v6, v4, s48, -v6
	v_fmac_f32_e32 v6, 0x3377d1cf, v4
	v_fmac_f32_e32 v6, 0x3f317217, v4
	v_cmp_lt_f32_e64 s[0:1], |v4|, s49
	s_nop 1
	v_cndmask_b32_e64 v4, v4, v6, s[0:1]
	v_cndmask_b32_e32 v6, 0, v233, vcc
	v_sub_f32_e32 v4, v4, v6
	v_sub_f32_e32 v4, v5, v4
	v_lshlrev_b64 v[6:7], 7, v[144:145]
	ds_read_u16 v145, v41 offset:24576
	v_mul_f32_e32 v252, 0x3d800000, v4
	v_cndmask_b32_e64 v144, v252, v173, s[4:5]
	v_add_f32_e32 v156, 0, v144
	ds_read_u16 v144, v41 offset:8192
	s_waitcnt lgkmcnt(1)
	v_lshlrev_b32_e32 v157, 16, v145
	v_mul_f32_e32 v145, 0x3fb8aa3b, v156
	v_exp_f32_e32 v145, v145
	v_fmac_f32_e32 v141, 0x3d800000, v4
	s_waitcnt lgkmcnt(0)
	v_lshlrev_b32_e32 v144, 16, v144
	v_or_b32_e32 v4, v143, v11
	v_mul_f32_e32 v144, 0x3db504f3, v144
	v_lshlrev_b32_e32 v146, 13, v4
	v_ashrrev_i32_e32 v143, 31, v142
	v_mul_f32_e32 v144, v144, v145
	v_lshl_add_u64 v[142:143], v[146:147], 0, v[142:143]
	v_bfe_u32 v145, v144, 16, 1
	v_add3_u32 v158, v144, v145, s73
	v_or_b32_e32 v144, v142, v10
	v_mov_b32_e32 v145, v143
	v_lshlrev_b64 v[146:147], 8, v[144:145]
	v_mul_f32_e32 v145, 0xbfb8aa3b, v156
	v_exp_f32_e32 v145, v145
	v_lshlrev_b32_e32 v144, 1, v8
	v_or_b32_e32 v146, v146, v144
	v_lshl_add_u64 v[154:155], s[36:37], 0, v[146:147]
	v_mul_f32_e32 v145, v145, v157
	v_and_b32_e32 v227, 0xff, v0
	v_lshrrev_b32_e32 v228, 8, v0
	v_lshlrev_b32_e32 v227, 2, v227
	v_lshl_add_u32 v227, v228, 16, v227
	ds_write_b32 v227, v218 offset:40960
	ds_write_b32 v227, v219 offset:41984
	ds_write_b32 v227, v220 offset:43008
	ds_write_b32 v227, v221 offset:44032
	ds_write_b32 v227, v222 offset:45056
	ds_write_b32 v227, v223 offset:46080
	ds_write_b32 v227, v224 offset:47104
	ds_write_b32 v227, v225 offset:48128
	ds_write_b32 v227, v226 offset:49152
	v_cndmask_b32_e64 v224, 0, -14, s[4:5]
	v_cndmask_b32_e64 v225, 0, -1, s[4:5]
	s_mov_b32 s98, 0xffff0000
	global_store_short_d16_hi v[154:155], v158, off
	v_bfe_u32 v154, v145, 16, 1
	v_add3_u32 v145, v145, v154, s73
	v_lshl_add_u64 v[146:147], s[38:39], 0, v[146:147]
	global_store_short_d16_hi v[146:147], v145, off
	v_sub_f32_e32 v145, v141, v156
	v_mul_f32_e32 v145, 0x3fb8aa3b, v145
	v_exp_f32_e32 v145, v145
	v_lshlrev_b32_e32 v4, 14, v4
	v_mov_b32_e32 v5, v3
	v_lshl_add_u64 v[4:5], v[4:5], 0, v[6:7]
	v_or_b32_e32 v4, v4, v8
	v_mul_f32_e32 v145, v145, v157
	v_lshlrev_b64 v[6:7], 7, v[4:5]
	v_bfe_u32 v146, v145, 16, 1
	v_lshl_add_u64 v[6:7], s[54:55], 0, v[6:7]
	v_add3_u32 v145, v145, v146, s73
	v_lshlrev_b32_e32 v146, 1, v10
	v_mov_b32_e32 v147, v3
	v_lshl_add_u64 v[146:147], v[6:7], 0, v[146:147]
	v_lshrrev_b32_e32 v220, 16, v145
	ds_read_u16 v146, v43 offset:8192
	ds_read_u16 v147, v43 offset:24576
	v_cndmask_b32_e64 v145, v251, v174, s[4:5]
	v_add_f32_e32 v145, v145, v156
	s_movk_i32 s0, 0x1ff
	s_waitcnt lgkmcnt(1)
	v_lshlrev_b32_e32 v146, 16, v146
	s_waitcnt lgkmcnt(0)
	v_lshlrev_b32_e32 v156, 16, v147
	v_mul_f32_e32 v147, 0x3fb8aa3b, v145
	v_exp_f32_e32 v147, v147
	v_mul_f32_e32 v146, 0x3db504f3, v146
	v_cmp_lt_i32_e32 vcc, s0, v1
	v_lshl_add_u64 v[4:5], v[4:5], 2, s[50:51]
	v_mul_f32_e32 v146, v146, v147
	v_bfe_u32 v147, v146, 16, 1
	v_add3_u32 v157, v146, v147, s73
	v_or_b32_e32 v146, v142, v12
	v_mov_b32_e32 v147, v143
	v_lshlrev_b64 v[146:147], 8, v[146:147]
	v_or_b32_e32 v146, v146, v144
	v_lshl_add_u64 v[154:155], s[36:37], 0, v[146:147]
	global_store_short_d16_hi v[154:155], v157, off
	v_mul_f32_e32 v154, 0xbfb8aa3b, v145
	v_exp_f32_e32 v154, v154
	v_lshl_add_u64 v[146:147], s[38:39], 0, v[146:147]
	s_or_b64 s[12:13], vcc, s[12:13]
	v_mul_f32_e32 v154, v154, v156
	v_bfe_u32 v155, v154, 16, 1
	v_add3_u32 v154, v154, v155, s73
	global_store_short_d16_hi v[146:147], v154, off
	v_sub_f32_e32 v146, v141, v145
	v_mul_f32_e32 v146, 0x3fb8aa3b, v146
	v_exp_f32_e32 v146, v146
	s_nop 0
	v_mul_f32_e32 v146, v146, v156
	v_bfe_u32 v147, v146, 16, 1
	v_add3_u32 v154, v146, v147, s73
	v_lshlrev_b32_e32 v146, 1, v12
	v_mov_b32_e32 v147, v3
	v_lshl_add_u64 v[146:147], v[6:7], 0, v[146:147]
	v_and_or_b32 v220, v154, s98, v220
	ds_read_u16 v147, v45 offset:24576
	v_cndmask_b32_e64 v146, v248, v175, s[4:5]
	v_add_f32_e32 v145, v146, v145
	ds_read_u16 v146, v45 offset:8192
	s_waitcnt lgkmcnt(1)
	v_lshlrev_b32_e32 v156, 16, v147
	v_mul_f32_e32 v147, 0x3fb8aa3b, v145
	v_exp_f32_e32 v147, v147
	s_waitcnt lgkmcnt(0)
	v_lshlrev_b32_e32 v146, 16, v146
	v_mul_f32_e32 v146, 0x3db504f3, v146
	v_mul_f32_e32 v146, v146, v147
	v_bfe_u32 v147, v146, 16, 1
	v_add3_u32 v157, v146, v147, s73
	v_or_b32_e32 v146, v142, v14
	v_mov_b32_e32 v147, v143
	v_lshlrev_b64 v[146:147], 8, v[146:147]
	v_or_b32_e32 v146, v146, v144
	v_lshl_add_u64 v[154:155], s[36:37], 0, v[146:147]
	global_store_short_d16_hi v[154:155], v157, off
	v_mul_f32_e32 v154, 0xbfb8aa3b, v145
	v_exp_f32_e32 v154, v154
	v_lshl_add_u64 v[146:147], s[38:39], 0, v[146:147]
	v_mul_f32_e32 v154, v154, v156
	v_bfe_u32 v155, v154, 16, 1
	v_add3_u32 v154, v154, v155, s73
	global_store_short_d16_hi v[146:147], v154, off
	v_sub_f32_e32 v146, v141, v145
	v_mul_f32_e32 v146, 0x3fb8aa3b, v146
	v_exp_f32_e32 v146, v146
	v_mov_b32_e32 v155, v143
	v_mul_f32_e32 v146, v146, v156
	v_bfe_u32 v147, v146, 16, 1
	v_add3_u32 v154, v146, v147, s73
	v_lshlrev_b32_e32 v146, 1, v14
	v_mov_b32_e32 v147, v3
	v_lshl_add_u64 v[146:147], v[6:7], 0, v[146:147]
	v_lshrrev_b32_e32 v221, 16, v154
	v_cndmask_b32_e64 v146, v243, v176, s[4:5]
	v_add_f32_e32 v145, v146, v145
	ds_read_u16 v146, v47 offset:8192
	v_mul_f32_e32 v154, 0x3fb8aa3b, v145
	v_exp_f32_e32 v154, v154
	s_waitcnt lgkmcnt(0)
	v_lshlrev_b32_e32 v147, 16, v146
	v_mul_f32_e32 v147, 0x3db504f3, v147
	v_mul_f32_e32 v147, v154, v147
	v_bfe_u32 v154, v147, 16, 1
	v_add3_u32 v147, v147, v154, s73
	v_or_b32_e32 v154, v142, v16
	v_lshlrev_b64 v[154:155], 8, v[154:155]
	v_or_b32_e32 v154, v154, v144
	ds_read_u16 v146, v47 offset:24576
	v_lshl_add_u64 v[156:157], s[36:37], 0, v[154:155]
	global_store_short_d16_hi v[156:157], v147, off
	v_mul_f32_e32 v147, 0xbfb8aa3b, v145
	v_exp_f32_e32 v147, v147
	s_waitcnt lgkmcnt(0)
	v_lshlrev_b32_e32 v146, 16, v146
	v_lshl_add_u64 v[154:155], s[38:39], 0, v[154:155]
	v_mul_f32_e32 v147, v147, v146
	v_bfe_u32 v156, v147, 16, 1
	v_add3_u32 v147, v147, v156, s73
	global_store_short_d16_hi v[154:155], v147, off
	v_sub_f32_e32 v147, v141, v145
	v_mul_f32_e32 v147, 0x3fb8aa3b, v147
	v_exp_f32_e32 v147, v147
	s_nop 0
	v_mul_f32_e32 v146, v147, v146
	v_bfe_u32 v147, v146, 16, 1
	v_add3_u32 v154, v146, v147, s73
	v_lshlrev_b32_e32 v146, 1, v16
	v_mov_b32_e32 v147, v3
	v_lshl_add_u64 v[146:147], v[6:7], 0, v[146:147]
	v_and_or_b32 v221, v154, s98, v221
	ds_read_u16 v147, v49 offset:24576
	v_cndmask_b32_e64 v146, v250, v177, s[4:5]
	v_add_f32_e32 v145, v146, v145
	ds_read_u16 v146, v49 offset:8192
	s_waitcnt lgkmcnt(1)
	v_lshlrev_b32_e32 v156, 16, v147
	v_mul_f32_e32 v147, 0x3fb8aa3b, v145
	v_exp_f32_e32 v147, v147
	s_waitcnt lgkmcnt(0)
	v_lshlrev_b32_e32 v146, 16, v146
	v_mul_f32_e32 v146, 0x3db504f3, v146
	v_mul_f32_e32 v146, v147, v146
	v_bfe_u32 v147, v146, 16, 1
	v_add3_u32 v157, v146, v147, s73
	v_or_b32_e32 v146, v142, v18
	v_mov_b32_e32 v147, v143
	v_lshlrev_b64 v[146:147], 8, v[146:147]
	v_or_b32_e32 v146, v146, v144
	v_lshl_add_u64 v[154:155], s[36:37], 0, v[146:147]
	global_store_short_d16_hi v[154:155], v157, off
	v_mul_f32_e32 v154, 0xbfb8aa3b, v145
	v_exp_f32_e32 v154, v154
	v_lshl_add_u64 v[146:147], s[38:39], 0, v[146:147]
	v_mul_f32_e32 v154, v154, v156
	v_bfe_u32 v155, v154, 16, 1
	v_add3_u32 v154, v154, v155, s73
	global_store_short_d16_hi v[146:147], v154, off
	v_sub_f32_e32 v146, v141, v145
	v_mul_f32_e32 v146, 0x3fb8aa3b, v146
	v_exp_f32_e32 v146, v146
	s_nop 0
	v_mul_f32_e32 v146, v146, v156
	v_bfe_u32 v147, v146, 16, 1
	v_add3_u32 v154, v146, v147, s73
	v_lshlrev_b32_e32 v146, 1, v18
	v_mov_b32_e32 v147, v3
	v_lshl_add_u64 v[146:147], v[6:7], 0, v[146:147]
	v_lshrrev_b32_e32 v222, 16, v154
	ds_read_u16 v147, v51 offset:24576
	v_cndmask_b32_e64 v146, v249, v178, s[4:5]
	v_add_f32_e32 v145, v146, v145
	ds_read_u16 v146, v51 offset:8192
	s_waitcnt lgkmcnt(1)
	v_lshlrev_b32_e32 v156, 16, v147
	v_mul_f32_e32 v147, 0x3fb8aa3b, v145
	v_exp_f32_e32 v147, v147
	s_waitcnt lgkmcnt(0)
	v_lshlrev_b32_e32 v146, 16, v146
	v_mul_f32_e32 v146, 0x3db504f3, v146
	v_mul_f32_e32 v146, v147, v146
	v_bfe_u32 v147, v146, 16, 1
	v_add3_u32 v157, v146, v147, s73
	v_or_b32_e32 v146, v142, v20
	v_mov_b32_e32 v147, v143
	v_lshlrev_b64 v[146:147], 8, v[146:147]
	v_or_b32_e32 v146, v146, v144
	v_lshl_add_u64 v[154:155], s[36:37], 0, v[146:147]
	global_store_short_d16_hi v[154:155], v157, off
	v_mul_f32_e32 v154, 0xbfb8aa3b, v145
	v_exp_f32_e32 v154, v154
	v_lshl_add_u64 v[146:147], s[38:39], 0, v[146:147]
	v_mul_f32_e32 v154, v154, v156
	v_bfe_u32 v155, v154, 16, 1
	v_add3_u32 v154, v154, v155, s73
	global_store_short_d16_hi v[146:147], v154, off
	v_sub_f32_e32 v146, v141, v145
	v_mul_f32_e32 v146, 0x3fb8aa3b, v146
	v_exp_f32_e32 v146, v146
	s_nop 0
	v_mul_f32_e32 v146, v146, v156
	v_bfe_u32 v147, v146, 16, 1
	v_add3_u32 v154, v146, v147, s73
	v_lshlrev_b32_e32 v146, 1, v20
	v_mov_b32_e32 v147, v3
	v_lshl_add_u64 v[146:147], v[6:7], 0, v[146:147]
	v_and_or_b32 v222, v154, s98, v222
	ds_read_u16 v147, v53 offset:24576
	v_cndmask_b32_e64 v146, v245, v179, s[4:5]
	v_add_f32_e32 v145, v146, v145
	ds_read_u16 v146, v53 offset:8192
	s_waitcnt lgkmcnt(1)
	v_lshlrev_b32_e32 v156, 16, v147
	v_mul_f32_e32 v147, 0x3fb8aa3b, v145
	v_exp_f32_e32 v147, v147
	s_waitcnt lgkmcnt(0)
	v_lshlrev_b32_e32 v146, 16, v146
	v_mul_f32_e32 v146, 0x3db504f3, v146
	v_mul_f32_e32 v146, v147, v146
	v_bfe_u32 v147, v146, 16, 1
	v_add3_u32 v157, v146, v147, s73
	v_or_b32_e32 v146, v142, v22
	v_mov_b32_e32 v147, v143
	v_lshlrev_b64 v[146:147], 8, v[146:147]
	v_or_b32_e32 v146, v146, v144
	v_lshl_add_u64 v[154:155], s[36:37], 0, v[146:147]
	global_store_short_d16_hi v[154:155], v157, off
	v_mul_f32_e32 v154, 0xbfb8aa3b, v145
	v_exp_f32_e32 v154, v154
	v_lshl_add_u64 v[146:147], s[38:39], 0, v[146:147]
	v_mul_f32_e32 v154, v154, v156
	v_bfe_u32 v155, v154, 16, 1
	v_add3_u32 v154, v154, v155, s73
	global_store_short_d16_hi v[146:147], v154, off
	v_sub_f32_e32 v146, v141, v145
	v_mul_f32_e32 v146, 0x3fb8aa3b, v146
	v_exp_f32_e32 v146, v146
	s_nop 0
	v_mul_f32_e32 v146, v146, v156
	v_bfe_u32 v147, v146, 16, 1
	v_add3_u32 v154, v146, v147, s73
	v_lshlrev_b32_e32 v146, 1, v22
	v_mov_b32_e32 v147, v3
	v_lshl_add_u64 v[146:147], v[6:7], 0, v[146:147]
	v_lshrrev_b32_e32 v223, 16, v154
	ds_read_u16 v147, v55 offset:24576
	v_cndmask_b32_e64 v146, v239, v180, s[4:5]
	v_add_f32_e32 v145, v146, v145
	ds_read_u16 v146, v55 offset:8192
	s_waitcnt lgkmcnt(1)
	v_lshlrev_b32_e32 v156, 16, v147
	v_mul_f32_e32 v147, 0x3fb8aa3b, v145
	v_exp_f32_e32 v147, v147
	s_waitcnt lgkmcnt(0)
	v_lshlrev_b32_e32 v146, 16, v146
	v_mul_f32_e32 v146, 0x3db504f3, v146
	v_mul_f32_e32 v146, v147, v146
	v_bfe_u32 v147, v146, 16, 1
	v_add3_u32 v157, v146, v147, s73
	v_or_b32_e32 v146, v142, v24
	v_mov_b32_e32 v147, v143
	v_lshlrev_b64 v[146:147], 8, v[146:147]
	v_or_b32_e32 v146, v146, v144
	v_lshl_add_u64 v[154:155], s[36:37], 0, v[146:147]
	global_store_short_d16_hi v[154:155], v157, off
	v_mul_f32_e32 v154, 0xbfb8aa3b, v145
	v_exp_f32_e32 v154, v154
	v_lshl_add_u64 v[146:147], s[38:39], 0, v[146:147]
	v_mul_f32_e32 v154, v154, v156
	v_bfe_u32 v155, v154, 16, 1
	v_add3_u32 v154, v154, v155, s73
	global_store_short_d16_hi v[146:147], v154, off
	v_sub_f32_e32 v146, v141, v145
	v_mul_f32_e32 v146, 0x3fb8aa3b, v146
	v_exp_f32_e32 v146, v146
	s_nop 0
	v_mul_f32_e32 v146, v146, v156
	v_bfe_u32 v147, v146, 16, 1
	v_add3_u32 v154, v146, v147, s73
	v_lshlrev_b32_e32 v146, 1, v24
	v_mov_b32_e32 v147, v3
	v_lshl_add_u64 v[146:147], v[6:7], 0, v[146:147]
	v_and_or_b32 v223, v154, s98, v223
	v_alignbit_b32 v226, v223, v223, 16
	v_alignbit_b32 v218, v220, v220, 16
	v_cndmask_b32_e64 v220, v226, v220, s[4:5]
	v_cndmask_b32_e64 v223, v218, v223, s[4:5]
	v_alignbit_b32 v226, v222, v222, 16
	v_alignbit_b32 v218, v221, v221, 16
	v_cndmask_b32_e64 v221, v226, v221, s[4:5]
	v_cndmask_b32_e64 v222, v218, v222, s[4:5]
	v_lshl_add_u64 v[218:219], v[146:147], 0, v[224:225]
	global_store_dwordx4 v[218:219], v[220:223], off
	s_nop 1
	ds_read_u16 v147, v57 offset:24576
	v_cndmask_b32_e64 v146, v247, v181, s[4:5]
	v_add_f32_e32 v145, v146, v145
	ds_read_u16 v146, v57 offset:8192
	s_waitcnt lgkmcnt(1)
	v_lshlrev_b32_e32 v156, 16, v147
	v_mul_f32_e32 v147, 0x3fb8aa3b, v145
	v_exp_f32_e32 v147, v147
	s_waitcnt lgkmcnt(0)
	v_lshlrev_b32_e32 v146, 16, v146
	v_mul_f32_e32 v146, 0x3db504f3, v146
	v_mul_f32_e32 v146, v147, v146
	v_bfe_u32 v147, v146, 16, 1
	v_add3_u32 v157, v146, v147, s73
	v_or_b32_e32 v146, v142, v26
	v_mov_b32_e32 v147, v143
	v_lshlrev_b64 v[146:147], 8, v[146:147]
	v_or_b32_e32 v146, v146, v144
	v_lshl_add_u64 v[154:155], s[36:37], 0, v[146:147]
	global_store_short_d16_hi v[154:155], v157, off
	v_mul_f32_e32 v154, 0xbfb8aa3b, v145
	v_exp_f32_e32 v154, v154
	v_lshl_add_u64 v[146:147], s[38:39], 0, v[146:147]
	v_mul_f32_e32 v154, v154, v156
	v_bfe_u32 v155, v154, 16, 1
	v_add3_u32 v154, v154, v155, s73
	global_store_short_d16_hi v[146:147], v154, off
	v_sub_f32_e32 v146, v141, v145
	v_mul_f32_e32 v146, 0x3fb8aa3b, v146
	v_exp_f32_e32 v146, v146
	s_nop 0
	v_mul_f32_e32 v146, v146, v156
	v_bfe_u32 v147, v146, 16, 1
	v_add3_u32 v154, v146, v147, s73
	v_lshlrev_b32_e32 v146, 1, v26
	v_mov_b32_e32 v147, v3
	v_lshl_add_u64 v[146:147], v[6:7], 0, v[146:147]
	v_lshrrev_b32_e32 v220, 16, v154
	ds_read_u16 v147, v59 offset:24576
	v_cndmask_b32_e64 v146, v246, v182, s[4:5]
	v_add_f32_e32 v145, v146, v145
	ds_read_u16 v146, v59 offset:8192
	s_waitcnt lgkmcnt(1)
	v_lshlrev_b32_e32 v156, 16, v147
	v_mul_f32_e32 v147, 0x3fb8aa3b, v145
	v_exp_f32_e32 v147, v147
	s_waitcnt lgkmcnt(0)
	v_lshlrev_b32_e32 v146, 16, v146
	v_mul_f32_e32 v146, 0x3db504f3, v146
	v_mul_f32_e32 v146, v147, v146
	v_bfe_u32 v147, v146, 16, 1
	v_add3_u32 v157, v146, v147, s73
	v_or_b32_e32 v146, v142, v28
	v_mov_b32_e32 v147, v143
	v_lshlrev_b64 v[146:147], 8, v[146:147]
	v_or_b32_e32 v146, v146, v144
	v_lshl_add_u64 v[154:155], s[36:37], 0, v[146:147]
	global_store_short_d16_hi v[154:155], v157, off
	v_mul_f32_e32 v154, 0xbfb8aa3b, v145
	v_exp_f32_e32 v154, v154
	v_lshl_add_u64 v[146:147], s[38:39], 0, v[146:147]
	v_mul_f32_e32 v154, v154, v156
	v_bfe_u32 v155, v154, 16, 1
	v_add3_u32 v154, v154, v155, s73
	global_store_short_d16_hi v[146:147], v154, off
	v_sub_f32_e32 v146, v141, v145
	v_mul_f32_e32 v146, 0x3fb8aa3b, v146
	v_exp_f32_e32 v146, v146
	s_nop 0
	v_mul_f32_e32 v146, v146, v156
	v_bfe_u32 v147, v146, 16, 1
	v_add3_u32 v154, v146, v147, s73
	v_lshlrev_b32_e32 v146, 1, v28
	v_mov_b32_e32 v147, v3
	v_lshl_add_u64 v[146:147], v[6:7], 0, v[146:147]
	v_and_or_b32 v220, v154, s98, v220
	ds_read_u16 v147, v61 offset:24576
	v_cndmask_b32_e64 v146, v241, v183, s[4:5]
	v_add_f32_e32 v145, v146, v145
	ds_read_u16 v146, v61 offset:8192
	s_waitcnt lgkmcnt(1)
	v_lshlrev_b32_e32 v156, 16, v147
	v_mul_f32_e32 v147, 0x3fb8aa3b, v145
	v_exp_f32_e32 v147, v147
	s_waitcnt lgkmcnt(0)
	v_lshlrev_b32_e32 v146, 16, v146
	v_mul_f32_e32 v146, 0x3db504f3, v146
	v_mul_f32_e32 v146, v147, v146
	v_bfe_u32 v147, v146, 16, 1
	v_add3_u32 v157, v146, v147, s73
	v_or_b32_e32 v146, v142, v30
	v_mov_b32_e32 v147, v143
	v_lshlrev_b64 v[146:147], 8, v[146:147]
	v_or_b32_e32 v146, v146, v144
	v_lshl_add_u64 v[154:155], s[36:37], 0, v[146:147]
	global_store_short_d16_hi v[154:155], v157, off
	v_mul_f32_e32 v154, 0xbfb8aa3b, v145
	v_exp_f32_e32 v154, v154
	v_lshl_add_u64 v[146:147], s[38:39], 0, v[146:147]
	v_mul_f32_e32 v154, v154, v156
	v_bfe_u32 v155, v154, 16, 1
	v_add3_u32 v154, v154, v155, s73
	global_store_short_d16_hi v[146:147], v154, off
	v_sub_f32_e32 v146, v141, v145
	v_mul_f32_e32 v146, 0x3fb8aa3b, v146
	v_exp_f32_e32 v146, v146
	s_nop 0
	v_mul_f32_e32 v146, v146, v156
	v_bfe_u32 v147, v146, 16, 1
	v_add3_u32 v154, v146, v147, s73
	v_lshlrev_b32_e32 v146, 1, v30
	v_mov_b32_e32 v147, v3
	v_lshl_add_u64 v[146:147], v[6:7], 0, v[146:147]
	v_lshrrev_b32_e32 v221, 16, v154
	ds_read_u16 v147, v63 offset:24576
	v_cndmask_b32_e64 v146, v235, v184, s[4:5]
	v_add_f32_e32 v145, v146, v145
	ds_read_u16 v146, v63 offset:8192
	s_waitcnt lgkmcnt(1)
	v_lshlrev_b32_e32 v156, 16, v147
	v_mul_f32_e32 v147, 0x3fb8aa3b, v145
	v_exp_f32_e32 v147, v147
	s_waitcnt lgkmcnt(0)
	v_lshlrev_b32_e32 v146, 16, v146
	v_mul_f32_e32 v146, 0x3db504f3, v146
	v_mul_f32_e32 v146, v147, v146
	v_bfe_u32 v147, v146, 16, 1
	v_add3_u32 v157, v146, v147, s73
	v_or_b32_e32 v146, v142, v32
	v_mov_b32_e32 v147, v143
	v_lshlrev_b64 v[146:147], 8, v[146:147]
	v_or_b32_e32 v146, v146, v144
	v_lshl_add_u64 v[154:155], s[36:37], 0, v[146:147]
	global_store_short_d16_hi v[154:155], v157, off
	v_mul_f32_e32 v154, 0xbfb8aa3b, v145
	v_exp_f32_e32 v154, v154
	v_lshl_add_u64 v[146:147], s[38:39], 0, v[146:147]
	v_mul_f32_e32 v154, v154, v156
	v_bfe_u32 v155, v154, 16, 1
	v_add3_u32 v154, v154, v155, s73
	global_store_short_d16_hi v[146:147], v154, off
	v_sub_f32_e32 v146, v141, v145
	v_mul_f32_e32 v146, 0x3fb8aa3b, v146
	v_exp_f32_e32 v146, v146
	s_nop 0
	v_mul_f32_e32 v146, v146, v156
	v_bfe_u32 v147, v146, 16, 1
	v_add3_u32 v154, v146, v147, s73
	v_lshlrev_b32_e32 v146, 1, v32
	v_mov_b32_e32 v147, v3
	v_lshl_add_u64 v[146:147], v[6:7], 0, v[146:147]
	v_and_or_b32 v221, v154, s98, v221
	ds_read_u16 v147, v65 offset:24576
	v_cndmask_b32_e64 v146, v244, v185, s[4:5]
	v_add_f32_e32 v145, v146, v145
	ds_read_u16 v146, v65 offset:8192
	s_waitcnt lgkmcnt(1)
	v_lshlrev_b32_e32 v156, 16, v147
	v_mul_f32_e32 v147, 0x3fb8aa3b, v145
	v_exp_f32_e32 v147, v147
	s_waitcnt lgkmcnt(0)
	v_lshlrev_b32_e32 v146, 16, v146
	v_mul_f32_e32 v146, 0x3db504f3, v146
	v_mul_f32_e32 v146, v147, v146
	v_bfe_u32 v147, v146, 16, 1
	v_add3_u32 v157, v146, v147, s73
	v_or_b32_e32 v146, v142, v34
	v_mov_b32_e32 v147, v143
	v_lshlrev_b64 v[146:147], 8, v[146:147]
	v_or_b32_e32 v146, v146, v144
	v_lshl_add_u64 v[154:155], s[36:37], 0, v[146:147]
	global_store_short_d16_hi v[154:155], v157, off
	v_mul_f32_e32 v154, 0xbfb8aa3b, v145
	v_exp_f32_e32 v154, v154
	v_lshl_add_u64 v[146:147], s[38:39], 0, v[146:147]
	v_mul_f32_e32 v154, v154, v156
	v_bfe_u32 v155, v154, 16, 1
	v_add3_u32 v154, v154, v155, s73
	global_store_short_d16_hi v[146:147], v154, off
	v_sub_f32_e32 v146, v141, v145
	v_mul_f32_e32 v146, 0x3fb8aa3b, v146
	v_exp_f32_e32 v146, v146
	s_nop 0
	v_mul_f32_e32 v146, v146, v156
	v_bfe_u32 v147, v146, 16, 1
	v_add3_u32 v154, v146, v147, s73
	v_lshlrev_b32_e32 v146, 1, v34
	v_mov_b32_e32 v147, v3
	v_lshl_add_u64 v[146:147], v[6:7], 0, v[146:147]
	v_lshrrev_b32_e32 v222, 16, v154
	ds_read_u16 v147, v67 offset:24576
	v_cndmask_b32_e64 v146, v242, v186, s[4:5]
	v_add_f32_e32 v145, v146, v145
	ds_read_u16 v146, v67 offset:8192
	s_waitcnt lgkmcnt(1)
	v_lshlrev_b32_e32 v156, 16, v147
	v_mul_f32_e32 v147, 0x3fb8aa3b, v145
	v_exp_f32_e32 v147, v147
	s_waitcnt lgkmcnt(0)
	v_lshlrev_b32_e32 v146, 16, v146
	v_mul_f32_e32 v146, 0x3db504f3, v146
	v_mul_f32_e32 v146, v147, v146
	v_bfe_u32 v147, v146, 16, 1
	v_add3_u32 v157, v146, v147, s73
	v_or_b32_e32 v146, v142, v38
	v_mov_b32_e32 v147, v143
	v_lshlrev_b64 v[146:147], 8, v[146:147]
	v_or_b32_e32 v146, v146, v144
	v_lshl_add_u64 v[154:155], s[36:37], 0, v[146:147]
	global_store_short_d16_hi v[154:155], v157, off
	v_mul_f32_e32 v154, 0xbfb8aa3b, v145
	v_exp_f32_e32 v154, v154
	v_lshl_add_u64 v[146:147], s[38:39], 0, v[146:147]
	v_mul_f32_e32 v154, v154, v156
	v_bfe_u32 v155, v154, 16, 1
	v_add3_u32 v154, v154, v155, s73
	global_store_short_d16_hi v[146:147], v154, off
	v_sub_f32_e32 v146, v141, v145
	v_mul_f32_e32 v146, 0x3fb8aa3b, v146
	v_exp_f32_e32 v146, v146
	s_nop 0
	v_mul_f32_e32 v146, v146, v156
	v_bfe_u32 v147, v146, 16, 1
	v_add3_u32 v154, v146, v147, s73
	v_lshlrev_b32_e32 v146, 1, v38
	v_mov_b32_e32 v147, v3
	v_lshl_add_u64 v[146:147], v[6:7], 0, v[146:147]
	v_and_or_b32 v222, v154, s98, v222
	ds_read_u16 v147, v69 offset:24576
	v_cndmask_b32_e64 v146, v237, v187, s[4:5]
	v_add_f32_e32 v145, v146, v145
	ds_read_u16 v146, v69 offset:8192
	s_waitcnt lgkmcnt(1)
	v_lshlrev_b32_e32 v156, 16, v147
	v_mul_f32_e32 v147, 0x3fb8aa3b, v145
	v_exp_f32_e32 v147, v147
	s_waitcnt lgkmcnt(0)
	v_lshlrev_b32_e32 v146, 16, v146
	v_mul_f32_e32 v146, 0x3db504f3, v146
	v_mul_f32_e32 v146, v147, v146
	v_bfe_u32 v147, v146, 16, 1
	v_add3_u32 v157, v146, v147, s73
	v_or_b32_e32 v146, v142, v40
	v_mov_b32_e32 v147, v143
	v_lshlrev_b64 v[146:147], 8, v[146:147]
	v_or_b32_e32 v146, v146, v144
	v_lshl_add_u64 v[154:155], s[36:37], 0, v[146:147]
	global_store_short_d16_hi v[154:155], v157, off
	v_mul_f32_e32 v154, 0xbfb8aa3b, v145
	v_exp_f32_e32 v154, v154
	v_lshl_add_u64 v[146:147], s[38:39], 0, v[146:147]
	v_mul_f32_e32 v154, v154, v156
	v_bfe_u32 v155, v154, 16, 1
	v_add3_u32 v154, v154, v155, s73
	global_store_short_d16_hi v[146:147], v154, off
	v_sub_f32_e32 v146, v141, v145
	v_mul_f32_e32 v146, 0x3fb8aa3b, v146
	v_exp_f32_e32 v146, v146
	s_nop 0
	v_mul_f32_e32 v146, v146, v156
	v_bfe_u32 v147, v146, 16, 1
	v_add3_u32 v154, v146, v147, s73
	v_lshlrev_b32_e32 v146, 1, v40
	v_mov_b32_e32 v147, v3
	v_lshl_add_u64 v[146:147], v[6:7], 0, v[146:147]
	v_lshrrev_b32_e32 v223, 16, v154
	ds_read_u16 v147, v71 offset:24576
	v_cndmask_b32_e64 v146, v215, v188, s[4:5]
	v_add_f32_e32 v145, v146, v145
	ds_read_u16 v146, v71 offset:8192
	s_waitcnt lgkmcnt(1)
	v_lshlrev_b32_e32 v156, 16, v147
	v_mul_f32_e32 v147, 0x3fb8aa3b, v145
	v_exp_f32_e32 v147, v147
	s_waitcnt lgkmcnt(0)
	v_lshlrev_b32_e32 v146, 16, v146
	v_mul_f32_e32 v146, 0x3db504f3, v146
	v_mul_f32_e32 v146, v147, v146
	v_bfe_u32 v147, v146, 16, 1
	v_add3_u32 v157, v146, v147, s73
	v_or_b32_e32 v146, v142, v42
	v_mov_b32_e32 v147, v143
	v_lshlrev_b64 v[146:147], 8, v[146:147]
	v_or_b32_e32 v146, v146, v144
	v_lshl_add_u64 v[154:155], s[36:37], 0, v[146:147]
	global_store_short_d16_hi v[154:155], v157, off
	v_mul_f32_e32 v154, 0xbfb8aa3b, v145
	v_exp_f32_e32 v154, v154
	v_lshl_add_u64 v[146:147], s[38:39], 0, v[146:147]
	v_mul_f32_e32 v154, v154, v156
	v_bfe_u32 v155, v154, 16, 1
	v_add3_u32 v154, v154, v155, s73
	global_store_short_d16_hi v[146:147], v154, off
	v_sub_f32_e32 v146, v141, v145
	v_mul_f32_e32 v146, 0x3fb8aa3b, v146
	v_exp_f32_e32 v146, v146
	s_nop 0
	v_mul_f32_e32 v146, v146, v156
	v_bfe_u32 v147, v146, 16, 1
	v_add3_u32 v154, v146, v147, s73
	v_lshlrev_b32_e32 v146, 1, v42
	v_mov_b32_e32 v147, v3
	v_lshl_add_u64 v[146:147], v[6:7], 0, v[146:147]
	v_and_or_b32 v223, v154, s98, v223
	v_alignbit_b32 v226, v223, v223, 16
	v_alignbit_b32 v218, v220, v220, 16
	v_cndmask_b32_e64 v220, v226, v220, s[4:5]
	v_cndmask_b32_e64 v223, v218, v223, s[4:5]
	v_alignbit_b32 v226, v222, v222, 16
	v_alignbit_b32 v218, v221, v221, 16
	v_cndmask_b32_e64 v221, v226, v221, s[4:5]
	v_cndmask_b32_e64 v222, v218, v222, s[4:5]
	v_lshl_add_u64 v[218:219], v[146:147], 0, v[224:225]
	global_store_dwordx4 v[218:219], v[220:223], off
	s_nop 1
	ds_read_u16 v147, v73 offset:24576
	v_cndmask_b32_e64 v146, v240, v189, s[4:5]
	v_add_f32_e32 v145, v146, v145
	ds_read_u16 v146, v73 offset:8192
	s_waitcnt lgkmcnt(1)
	v_lshlrev_b32_e32 v156, 16, v147
	v_mul_f32_e32 v147, 0x3fb8aa3b, v145
	v_exp_f32_e32 v147, v147
	s_waitcnt lgkmcnt(0)
	v_lshlrev_b32_e32 v146, 16, v146
	v_mul_f32_e32 v146, 0x3db504f3, v146
	v_mul_f32_e32 v146, v147, v146
	v_bfe_u32 v147, v146, 16, 1
	v_add3_u32 v157, v146, v147, s73
	v_or_b32_e32 v146, v142, v44
	v_mov_b32_e32 v147, v143
	v_lshlrev_b64 v[146:147], 8, v[146:147]
	v_or_b32_e32 v146, v146, v144
	v_lshl_add_u64 v[154:155], s[36:37], 0, v[146:147]
	global_store_short_d16_hi v[154:155], v157, off
	v_mul_f32_e32 v154, 0xbfb8aa3b, v145
	v_exp_f32_e32 v154, v154
	v_lshl_add_u64 v[146:147], s[38:39], 0, v[146:147]
	v_mul_f32_e32 v154, v154, v156
	v_bfe_u32 v155, v154, 16, 1
	v_add3_u32 v154, v154, v155, s73
	global_store_short_d16_hi v[146:147], v154, off
	v_sub_f32_e32 v146, v141, v145
	v_mul_f32_e32 v146, 0x3fb8aa3b, v146
	v_exp_f32_e32 v146, v146
	s_nop 0
	v_mul_f32_e32 v146, v146, v156
	v_bfe_u32 v147, v146, 16, 1
	v_add3_u32 v154, v146, v147, s73
	v_lshlrev_b32_e32 v146, 1, v44
	v_mov_b32_e32 v147, v3
	v_lshl_add_u64 v[146:147], v[6:7], 0, v[146:147]
	v_lshrrev_b32_e32 v220, 16, v154
	ds_read_u16 v147, v75 offset:24576
	v_cndmask_b32_e64 v146, v238, v190, s[4:5]
	v_add_f32_e32 v145, v146, v145
	ds_read_u16 v146, v75 offset:8192
	s_waitcnt lgkmcnt(1)
	v_lshlrev_b32_e32 v156, 16, v147
	v_mul_f32_e32 v147, 0x3fb8aa3b, v145
	v_exp_f32_e32 v147, v147
	s_waitcnt lgkmcnt(0)
	v_lshlrev_b32_e32 v146, 16, v146
	v_mul_f32_e32 v146, 0x3db504f3, v146
	v_mul_f32_e32 v146, v147, v146
	v_bfe_u32 v147, v146, 16, 1
	v_add3_u32 v157, v146, v147, s73
	v_or_b32_e32 v146, v142, v46
	v_mov_b32_e32 v147, v143
	v_lshlrev_b64 v[146:147], 8, v[146:147]
	v_or_b32_e32 v146, v146, v144
	v_lshl_add_u64 v[154:155], s[36:37], 0, v[146:147]
	global_store_short_d16_hi v[154:155], v157, off
	v_mul_f32_e32 v154, 0xbfb8aa3b, v145
	v_exp_f32_e32 v154, v154
	v_lshl_add_u64 v[146:147], s[38:39], 0, v[146:147]
	v_mul_f32_e32 v154, v154, v156
	v_bfe_u32 v155, v154, 16, 1
	v_add3_u32 v154, v154, v155, s73
	global_store_short_d16_hi v[146:147], v154, off
	v_sub_f32_e32 v146, v141, v145
	v_mul_f32_e32 v146, 0x3fb8aa3b, v146
	v_exp_f32_e32 v146, v146
	s_nop 0
	v_mul_f32_e32 v146, v146, v156
	v_bfe_u32 v147, v146, 16, 1
	v_add3_u32 v154, v146, v147, s73
	v_lshlrev_b32_e32 v146, 1, v46
	v_mov_b32_e32 v147, v3
	v_lshl_add_u64 v[146:147], v[6:7], 0, v[146:147]
	v_and_or_b32 v220, v154, s98, v220
	ds_read_u16 v147, v77 offset:24576
	v_cndmask_b32_e64 v146, v217, v191, s[4:5]
	v_add_f32_e32 v145, v146, v145
	ds_read_u16 v146, v77 offset:8192
	s_waitcnt lgkmcnt(1)
	v_lshlrev_b32_e32 v156, 16, v147
	v_mul_f32_e32 v147, 0x3fb8aa3b, v145
	v_exp_f32_e32 v147, v147
	s_waitcnt lgkmcnt(0)
	v_lshlrev_b32_e32 v146, 16, v146
	v_mul_f32_e32 v146, 0x3db504f3, v146
	v_mul_f32_e32 v146, v147, v146
	v_bfe_u32 v147, v146, 16, 1
	v_add3_u32 v157, v146, v147, s73
	v_or_b32_e32 v146, v142, v48
	v_mov_b32_e32 v147, v143
	v_lshlrev_b64 v[146:147], 8, v[146:147]
	v_or_b32_e32 v146, v146, v144
	v_lshl_add_u64 v[154:155], s[36:37], 0, v[146:147]
	global_store_short_d16_hi v[154:155], v157, off
	v_mul_f32_e32 v154, 0xbfb8aa3b, v145
	v_exp_f32_e32 v154, v154
	v_lshl_add_u64 v[146:147], s[38:39], 0, v[146:147]
	v_mul_f32_e32 v154, v154, v156
	v_bfe_u32 v155, v154, 16, 1
	v_add3_u32 v154, v154, v155, s73
	global_store_short_d16_hi v[146:147], v154, off
	v_sub_f32_e32 v146, v141, v145
	v_mul_f32_e32 v146, 0x3fb8aa3b, v146
	v_exp_f32_e32 v146, v146
	s_nop 0
	v_mul_f32_e32 v146, v146, v156
	v_bfe_u32 v147, v146, 16, 1
	v_add3_u32 v154, v146, v147, s73
	v_lshlrev_b32_e32 v146, 1, v48
	v_mov_b32_e32 v147, v3
	v_lshl_add_u64 v[146:147], v[6:7], 0, v[146:147]
	v_lshrrev_b32_e32 v221, 16, v154
	ds_read_u16 v147, v79 offset:24576
	v_cndmask_b32_e64 v146, v211, v192, s[4:5]
	v_add_f32_e32 v145, v146, v145
	ds_read_u16 v146, v79 offset:8192
	s_waitcnt lgkmcnt(1)
	v_lshlrev_b32_e32 v156, 16, v147
	v_mul_f32_e32 v147, 0x3fb8aa3b, v145
	v_exp_f32_e32 v147, v147
	s_waitcnt lgkmcnt(0)
	v_lshlrev_b32_e32 v146, 16, v146
	v_mul_f32_e32 v146, 0x3db504f3, v146
	v_mul_f32_e32 v146, v147, v146
	v_bfe_u32 v147, v146, 16, 1
	v_add3_u32 v157, v146, v147, s73
	v_or_b32_e32 v146, v142, v50
	v_mov_b32_e32 v147, v143
	v_lshlrev_b64 v[146:147], 8, v[146:147]
	v_or_b32_e32 v146, v146, v144
	v_lshl_add_u64 v[154:155], s[36:37], 0, v[146:147]
	global_store_short_d16_hi v[154:155], v157, off
	v_mul_f32_e32 v154, 0xbfb8aa3b, v145
	v_exp_f32_e32 v154, v154
	v_lshl_add_u64 v[146:147], s[38:39], 0, v[146:147]
	v_mul_f32_e32 v154, v154, v156
	v_bfe_u32 v155, v154, 16, 1
	v_add3_u32 v154, v154, v155, s73
	global_store_short_d16_hi v[146:147], v154, off
	v_sub_f32_e32 v146, v141, v145
	v_mul_f32_e32 v146, 0x3fb8aa3b, v146
	v_exp_f32_e32 v146, v146
	s_nop 0
	v_mul_f32_e32 v146, v146, v156
	v_bfe_u32 v147, v146, 16, 1
	v_add3_u32 v154, v146, v147, s73
	v_lshlrev_b32_e32 v146, 1, v50
	v_mov_b32_e32 v147, v3
	v_lshl_add_u64 v[146:147], v[6:7], 0, v[146:147]
	v_and_or_b32 v221, v154, s98, v221
	ds_read_u16 v147, v81 offset:24576
	v_cndmask_b32_e64 v146, v236, v193, s[4:5]
	v_add_f32_e32 v145, v146, v145
	ds_read_u16 v146, v81 offset:8192
	s_waitcnt lgkmcnt(1)
	v_lshlrev_b32_e32 v156, 16, v147
	v_mul_f32_e32 v147, 0x3fb8aa3b, v145
	v_exp_f32_e32 v147, v147
	s_waitcnt lgkmcnt(0)
	v_lshlrev_b32_e32 v146, 16, v146
	v_mul_f32_e32 v146, 0x3db504f3, v146
	v_mul_f32_e32 v146, v147, v146
	v_bfe_u32 v147, v146, 16, 1
	v_add3_u32 v157, v146, v147, s73
	v_or_b32_e32 v146, v142, v52
	v_mov_b32_e32 v147, v143
	v_lshlrev_b64 v[146:147], 8, v[146:147]
	v_or_b32_e32 v146, v146, v144
	v_lshl_add_u64 v[154:155], s[36:37], 0, v[146:147]
	global_store_short_d16_hi v[154:155], v157, off
	v_mul_f32_e32 v154, 0xbfb8aa3b, v145
	v_exp_f32_e32 v154, v154
	v_lshl_add_u64 v[146:147], s[38:39], 0, v[146:147]
	v_mul_f32_e32 v154, v154, v156
	v_bfe_u32 v155, v154, 16, 1
	v_add3_u32 v154, v154, v155, s73
	global_store_short_d16_hi v[146:147], v154, off
	v_sub_f32_e32 v146, v141, v145
	v_mul_f32_e32 v146, 0x3fb8aa3b, v146
	v_exp_f32_e32 v146, v146
	s_nop 0
	v_mul_f32_e32 v146, v146, v156
	v_bfe_u32 v147, v146, 16, 1
	v_add3_u32 v154, v146, v147, s73
	v_lshlrev_b32_e32 v146, 1, v52
	v_mov_b32_e32 v147, v3
	v_lshl_add_u64 v[146:147], v[6:7], 0, v[146:147]
	v_lshrrev_b32_e32 v222, 16, v154
	ds_read_u16 v147, v83 offset:24576
	v_cndmask_b32_e64 v146, v234, v194, s[4:5]
	v_add_f32_e32 v145, v146, v145
	ds_read_u16 v146, v83 offset:8192
	s_waitcnt lgkmcnt(1)
	v_lshlrev_b32_e32 v156, 16, v147
	v_mul_f32_e32 v147, 0x3fb8aa3b, v145
	v_exp_f32_e32 v147, v147
	s_waitcnt lgkmcnt(0)
	v_lshlrev_b32_e32 v146, 16, v146
	v_mul_f32_e32 v146, 0x3db504f3, v146
	v_mul_f32_e32 v146, v147, v146
	v_bfe_u32 v147, v146, 16, 1
	v_add3_u32 v157, v146, v147, s73
	v_or_b32_e32 v146, v142, v54
	v_mov_b32_e32 v147, v143
	v_lshlrev_b64 v[146:147], 8, v[146:147]
	v_or_b32_e32 v146, v146, v144
	v_lshl_add_u64 v[154:155], s[36:37], 0, v[146:147]
	global_store_short_d16_hi v[154:155], v157, off
	v_mul_f32_e32 v154, 0xbfb8aa3b, v145
	v_exp_f32_e32 v154, v154
	v_lshl_add_u64 v[146:147], s[38:39], 0, v[146:147]
	v_mul_f32_e32 v154, v154, v156
	v_bfe_u32 v155, v154, 16, 1
	v_add3_u32 v154, v154, v155, s73
	global_store_short_d16_hi v[146:147], v154, off
	v_sub_f32_e32 v146, v141, v145
	v_mul_f32_e32 v146, 0x3fb8aa3b, v146
	v_exp_f32_e32 v146, v146
	s_nop 0
	v_mul_f32_e32 v146, v146, v156
	v_bfe_u32 v147, v146, 16, 1
	v_add3_u32 v154, v146, v147, s73
	v_lshlrev_b32_e32 v146, 1, v54
	v_mov_b32_e32 v147, v3
	v_lshl_add_u64 v[146:147], v[6:7], 0, v[146:147]
	v_and_or_b32 v222, v154, s98, v222
	ds_read_u16 v147, v85 offset:24576
	v_cndmask_b32_e64 v146, v213, v195, s[4:5]
	v_add_f32_e32 v145, v146, v145
	ds_read_u16 v146, v85 offset:8192
	s_waitcnt lgkmcnt(1)
	v_lshlrev_b32_e32 v156, 16, v147
	v_mul_f32_e32 v147, 0x3fb8aa3b, v145
	v_exp_f32_e32 v147, v147
	s_waitcnt lgkmcnt(0)
	v_lshlrev_b32_e32 v146, 16, v146
	v_mul_f32_e32 v146, 0x3db504f3, v146
	v_mul_f32_e32 v146, v147, v146
	v_bfe_u32 v147, v146, 16, 1
	v_add3_u32 v157, v146, v147, s73
	v_or_b32_e32 v146, v142, v56
	v_mov_b32_e32 v147, v143
	v_lshlrev_b64 v[146:147], 8, v[146:147]
	v_or_b32_e32 v146, v146, v144
	v_lshl_add_u64 v[154:155], s[36:37], 0, v[146:147]
	global_store_short_d16_hi v[154:155], v157, off
	v_mul_f32_e32 v154, 0xbfb8aa3b, v145
	v_exp_f32_e32 v154, v154
	v_lshl_add_u64 v[146:147], s[38:39], 0, v[146:147]
	v_mul_f32_e32 v154, v154, v156
	v_bfe_u32 v155, v154, 16, 1
	v_add3_u32 v154, v154, v155, s73
	global_store_short_d16_hi v[146:147], v154, off
	v_sub_f32_e32 v146, v141, v145
	v_mul_f32_e32 v146, 0x3fb8aa3b, v146
	v_exp_f32_e32 v146, v146
	s_nop 0
	v_mul_f32_e32 v146, v146, v156
	v_bfe_u32 v147, v146, 16, 1
	v_add3_u32 v154, v146, v147, s73
	v_lshlrev_b32_e32 v146, 1, v56
	v_mov_b32_e32 v147, v3
	v_lshl_add_u64 v[146:147], v[6:7], 0, v[146:147]
	v_lshrrev_b32_e32 v223, 16, v154
	ds_read_u16 v147, v87 offset:24576
	v_cndmask_b32_e64 v146, v208, v196, s[4:5]
	v_add_f32_e32 v145, v146, v145
	ds_read_u16 v146, v87 offset:8192
	s_waitcnt lgkmcnt(1)
	v_lshlrev_b32_e32 v156, 16, v147
	v_mul_f32_e32 v147, 0x3fb8aa3b, v145
	v_exp_f32_e32 v147, v147
	s_waitcnt lgkmcnt(0)
	v_lshlrev_b32_e32 v146, 16, v146
	v_mul_f32_e32 v146, 0x3db504f3, v146
	v_mul_f32_e32 v146, v147, v146
	v_bfe_u32 v147, v146, 16, 1
	v_add3_u32 v157, v146, v147, s73
	v_or_b32_e32 v146, v142, v58
	v_mov_b32_e32 v147, v143
	v_lshlrev_b64 v[146:147], 8, v[146:147]
	v_or_b32_e32 v146, v146, v144
	v_lshl_add_u64 v[154:155], s[36:37], 0, v[146:147]
	global_store_short_d16_hi v[154:155], v157, off
	v_mul_f32_e32 v154, 0xbfb8aa3b, v145
	v_exp_f32_e32 v154, v154
	v_lshl_add_u64 v[146:147], s[38:39], 0, v[146:147]
	v_mul_f32_e32 v154, v154, v156
	v_bfe_u32 v155, v154, 16, 1
	v_add3_u32 v154, v154, v155, s73
	global_store_short_d16_hi v[146:147], v154, off
	v_sub_f32_e32 v146, v141, v145
	v_mul_f32_e32 v146, 0x3fb8aa3b, v146
	v_exp_f32_e32 v146, v146
	s_nop 0
	v_mul_f32_e32 v146, v146, v156
	v_bfe_u32 v147, v146, 16, 1
	v_add3_u32 v154, v146, v147, s73
	v_lshlrev_b32_e32 v146, 1, v58
	v_mov_b32_e32 v147, v3
	v_lshl_add_u64 v[146:147], v[6:7], 0, v[146:147]
	v_and_or_b32 v223, v154, s98, v223
	v_alignbit_b32 v226, v223, v223, 16
	v_alignbit_b32 v218, v220, v220, 16
	v_cndmask_b32_e64 v220, v226, v220, s[4:5]
	v_cndmask_b32_e64 v223, v218, v223, s[4:5]
	v_alignbit_b32 v226, v222, v222, 16
	v_alignbit_b32 v218, v221, v221, 16
	v_cndmask_b32_e64 v221, v226, v221, s[4:5]
	v_cndmask_b32_e64 v222, v218, v222, s[4:5]
	v_lshl_add_u64 v[218:219], v[146:147], 0, v[224:225]
	global_store_dwordx4 v[218:219], v[220:223], off
	s_nop 1
	ds_read_u16 v147, v89 offset:24576
	v_cndmask_b32_e64 v146, v216, v197, s[4:5]
	v_add_f32_e32 v145, v146, v145
	ds_read_u16 v146, v89 offset:8192
	s_waitcnt lgkmcnt(1)
	v_lshlrev_b32_e32 v156, 16, v147
	v_mul_f32_e32 v147, 0x3fb8aa3b, v145
	v_exp_f32_e32 v147, v147
	s_waitcnt lgkmcnt(0)
	v_lshlrev_b32_e32 v146, 16, v146
	v_mul_f32_e32 v146, 0x3db504f3, v146
	v_mul_f32_e32 v146, v147, v146
	v_bfe_u32 v147, v146, 16, 1
	v_add3_u32 v157, v146, v147, s73
	v_or_b32_e32 v146, v142, v60
	v_mov_b32_e32 v147, v143
	v_lshlrev_b64 v[146:147], 8, v[146:147]
	v_or_b32_e32 v146, v146, v144
	v_lshl_add_u64 v[154:155], s[36:37], 0, v[146:147]
	global_store_short_d16_hi v[154:155], v157, off
	v_mul_f32_e32 v154, 0xbfb8aa3b, v145
	v_exp_f32_e32 v154, v154
	v_lshl_add_u64 v[146:147], s[38:39], 0, v[146:147]
	v_mul_f32_e32 v154, v154, v156
	v_bfe_u32 v155, v154, 16, 1
	v_add3_u32 v154, v154, v155, s73
	global_store_short_d16_hi v[146:147], v154, off
	v_sub_f32_e32 v146, v141, v145
	v_mul_f32_e32 v146, 0x3fb8aa3b, v146
	v_exp_f32_e32 v146, v146
	s_nop 0
	v_mul_f32_e32 v146, v146, v156
	v_bfe_u32 v147, v146, 16, 1
	v_add3_u32 v154, v146, v147, s73
	v_lshlrev_b32_e32 v146, 1, v60
	v_mov_b32_e32 v147, v3
	v_lshl_add_u64 v[146:147], v[6:7], 0, v[146:147]
	v_lshrrev_b32_e32 v220, 16, v154
	ds_read_u16 v147, v91 offset:24576
	v_cndmask_b32_e64 v146, v214, v198, s[4:5]
	v_add_f32_e32 v145, v146, v145
	ds_read_u16 v146, v91 offset:8192
	s_waitcnt lgkmcnt(1)
	v_lshlrev_b32_e32 v156, 16, v147
	v_mul_f32_e32 v147, 0x3fb8aa3b, v145
	v_exp_f32_e32 v147, v147
	s_waitcnt lgkmcnt(0)
	v_lshlrev_b32_e32 v146, 16, v146
	v_mul_f32_e32 v146, 0x3db504f3, v146
	v_mul_f32_e32 v146, v147, v146
	v_bfe_u32 v147, v146, 16, 1
	v_add3_u32 v157, v146, v147, s73
	v_or_b32_e32 v146, v142, v62
	v_mov_b32_e32 v147, v143
	v_lshlrev_b64 v[146:147], 8, v[146:147]
	v_or_b32_e32 v146, v146, v144
	v_lshl_add_u64 v[154:155], s[36:37], 0, v[146:147]
	global_store_short_d16_hi v[154:155], v157, off
	v_mul_f32_e32 v154, 0xbfb8aa3b, v145
	v_exp_f32_e32 v154, v154
	v_lshl_add_u64 v[146:147], s[38:39], 0, v[146:147]
	v_mul_f32_e32 v154, v154, v156
	v_bfe_u32 v155, v154, 16, 1
	v_add3_u32 v154, v154, v155, s73
	global_store_short_d16_hi v[146:147], v154, off
	v_sub_f32_e32 v146, v141, v145
	v_mul_f32_e32 v146, 0x3fb8aa3b, v146
	v_exp_f32_e32 v146, v146
	s_nop 0
	v_mul_f32_e32 v146, v146, v156
	v_bfe_u32 v147, v146, 16, 1
	v_add3_u32 v154, v146, v147, s73
	v_lshlrev_b32_e32 v146, 1, v62
	v_mov_b32_e32 v147, v3
	v_lshl_add_u64 v[146:147], v[6:7], 0, v[146:147]
	v_and_or_b32 v220, v154, s98, v220
	ds_read_u16 v147, v93 offset:24576
	v_cndmask_b32_e64 v146, v209, v199, s[4:5]
	v_add_f32_e32 v145, v146, v145
	ds_read_u16 v146, v93 offset:8192
	s_waitcnt lgkmcnt(1)
	v_lshlrev_b32_e32 v156, 16, v147
	v_mul_f32_e32 v147, 0x3fb8aa3b, v145
	v_exp_f32_e32 v147, v147
	s_waitcnt lgkmcnt(0)
	v_lshlrev_b32_e32 v146, 16, v146
	v_mul_f32_e32 v146, 0x3db504f3, v146
	v_mul_f32_e32 v146, v147, v146
	v_bfe_u32 v147, v146, 16, 1
	v_add3_u32 v157, v146, v147, s73
	v_or_b32_e32 v146, v142, v64
	v_mov_b32_e32 v147, v143
	v_lshlrev_b64 v[146:147], 8, v[146:147]
	v_or_b32_e32 v146, v146, v144
	v_lshl_add_u64 v[154:155], s[36:37], 0, v[146:147]
	global_store_short_d16_hi v[154:155], v157, off
	v_mul_f32_e32 v154, 0xbfb8aa3b, v145
	v_exp_f32_e32 v154, v154
	v_lshl_add_u64 v[146:147], s[38:39], 0, v[146:147]
	v_mul_f32_e32 v154, v154, v156
	v_bfe_u32 v155, v154, 16, 1
	v_add3_u32 v154, v154, v155, s73
	global_store_short_d16_hi v[146:147], v154, off
	v_sub_f32_e32 v146, v141, v145
	v_mul_f32_e32 v146, 0x3fb8aa3b, v146
	v_exp_f32_e32 v146, v146
	s_nop 0
	v_mul_f32_e32 v146, v146, v156
	v_bfe_u32 v147, v146, 16, 1
	v_add3_u32 v154, v146, v147, s73
	v_lshlrev_b32_e32 v146, 1, v64
	v_mov_b32_e32 v147, v3
	v_lshl_add_u64 v[146:147], v[6:7], 0, v[146:147]
	v_lshrrev_b32_e32 v221, 16, v154
	ds_read_u16 v147, v95 offset:24576
	v_cndmask_b32_e64 v146, v206, v200, s[4:5]
	v_add_f32_e32 v145, v146, v145
	ds_read_u16 v146, v95 offset:8192
	s_waitcnt lgkmcnt(1)
	v_lshlrev_b32_e32 v156, 16, v147
	v_mul_f32_e32 v147, 0x3fb8aa3b, v145
	v_exp_f32_e32 v147, v147
	s_waitcnt lgkmcnt(0)
	v_lshlrev_b32_e32 v146, 16, v146
	v_mul_f32_e32 v146, 0x3db504f3, v146
	v_mul_f32_e32 v146, v147, v146
	v_bfe_u32 v147, v146, 16, 1
	v_add3_u32 v157, v146, v147, s73
	v_or_b32_e32 v146, v142, v66
	v_mov_b32_e32 v147, v143
	v_lshlrev_b64 v[146:147], 8, v[146:147]
	v_or_b32_e32 v146, v146, v144
	v_lshl_add_u64 v[154:155], s[36:37], 0, v[146:147]
	global_store_short_d16_hi v[154:155], v157, off
	v_mul_f32_e32 v154, 0xbfb8aa3b, v145
	v_exp_f32_e32 v154, v154
	v_lshl_add_u64 v[146:147], s[38:39], 0, v[146:147]
	v_mul_f32_e32 v154, v154, v156
	v_bfe_u32 v155, v154, 16, 1
	v_add3_u32 v154, v154, v155, s73
	global_store_short_d16_hi v[146:147], v154, off
	v_sub_f32_e32 v146, v141, v145
	v_mul_f32_e32 v146, 0x3fb8aa3b, v146
	v_exp_f32_e32 v146, v146
	s_nop 0
	v_mul_f32_e32 v146, v146, v156
	v_bfe_u32 v147, v146, 16, 1
	v_add3_u32 v154, v146, v147, s73
	v_lshlrev_b32_e32 v146, 1, v66
	v_mov_b32_e32 v147, v3
	v_lshl_add_u64 v[146:147], v[6:7], 0, v[146:147]
	v_and_or_b32 v221, v154, s98, v221
	ds_read_u16 v147, v97 offset:24576
	v_cndmask_b32_e64 v146, v212, v201, s[4:5]
	v_add_f32_e32 v145, v146, v145
	ds_read_u16 v146, v97 offset:8192
	s_waitcnt lgkmcnt(1)
	v_lshlrev_b32_e32 v156, 16, v147
	v_mul_f32_e32 v147, 0x3fb8aa3b, v145
	v_exp_f32_e32 v147, v147
	s_waitcnt lgkmcnt(0)
	v_lshlrev_b32_e32 v146, 16, v146
	v_mul_f32_e32 v146, 0x3db504f3, v146
	v_mul_f32_e32 v146, v147, v146
	v_bfe_u32 v147, v146, 16, 1
	v_add3_u32 v157, v146, v147, s73
	v_or_b32_e32 v146, v142, v68
	v_mov_b32_e32 v147, v143
	v_lshlrev_b64 v[146:147], 8, v[146:147]
	v_or_b32_e32 v146, v146, v144
	v_lshl_add_u64 v[154:155], s[36:37], 0, v[146:147]
	global_store_short_d16_hi v[154:155], v157, off
	v_mul_f32_e32 v154, 0xbfb8aa3b, v145
	v_exp_f32_e32 v154, v154
	v_lshl_add_u64 v[146:147], s[38:39], 0, v[146:147]
	v_mul_f32_e32 v154, v154, v156
	v_bfe_u32 v155, v154, 16, 1
	v_add3_u32 v154, v154, v155, s73
	global_store_short_d16_hi v[146:147], v154, off
	v_sub_f32_e32 v146, v141, v145
	v_mul_f32_e32 v146, 0x3fb8aa3b, v146
	v_exp_f32_e32 v146, v146
	s_nop 0
	v_mul_f32_e32 v146, v146, v156
	v_bfe_u32 v147, v146, 16, 1
	v_add3_u32 v154, v146, v147, s73
	v_lshlrev_b32_e32 v146, 1, v68
	v_mov_b32_e32 v147, v3
	v_lshl_add_u64 v[146:147], v[6:7], 0, v[146:147]
	v_lshrrev_b32_e32 v222, 16, v154
	ds_read_u16 v147, v99 offset:24576
	v_cndmask_b32_e64 v146, v210, v202, s[4:5]
	v_add_f32_e32 v145, v146, v145
	ds_read_u16 v146, v99 offset:8192
	s_waitcnt lgkmcnt(1)
	v_lshlrev_b32_e32 v156, 16, v147
	v_mul_f32_e32 v147, 0x3fb8aa3b, v145
	v_exp_f32_e32 v147, v147
	s_waitcnt lgkmcnt(0)
	v_lshlrev_b32_e32 v146, 16, v146
	v_mul_f32_e32 v146, 0x3db504f3, v146
	v_mul_f32_e32 v146, v147, v146
	v_bfe_u32 v147, v146, 16, 1
	v_add3_u32 v157, v146, v147, s73
	v_or_b32_e32 v146, v142, v70
	v_mov_b32_e32 v147, v143
	v_lshlrev_b64 v[146:147], 8, v[146:147]
	v_or_b32_e32 v146, v146, v144
	v_lshl_add_u64 v[154:155], s[36:37], 0, v[146:147]
	global_store_short_d16_hi v[154:155], v157, off
	v_mul_f32_e32 v154, 0xbfb8aa3b, v145
	v_exp_f32_e32 v154, v154
	v_lshl_add_u64 v[146:147], s[38:39], 0, v[146:147]
	v_mul_f32_e32 v154, v154, v156
	v_bfe_u32 v155, v154, 16, 1
	v_add3_u32 v154, v154, v155, s73
	global_store_short_d16_hi v[146:147], v154, off
	v_sub_f32_e32 v146, v141, v145
	v_mul_f32_e32 v146, 0x3fb8aa3b, v146
	v_exp_f32_e32 v146, v146
	s_nop 0
	v_mul_f32_e32 v146, v146, v156
	v_bfe_u32 v147, v146, 16, 1
	v_add3_u32 v154, v146, v147, s73
	v_lshlrev_b32_e32 v146, 1, v70
	v_mov_b32_e32 v147, v3
	v_lshl_add_u64 v[146:147], v[6:7], 0, v[146:147]
	v_and_or_b32 v222, v154, s98, v222
	ds_read_u16 v147, v101 offset:24576
	v_cndmask_b32_e64 v146, v207, v203, s[4:5]
	v_add_f32_e32 v145, v146, v145
	ds_read_u16 v146, v101 offset:8192
	s_waitcnt lgkmcnt(1)
	v_lshlrev_b32_e32 v156, 16, v147
	v_mul_f32_e32 v147, 0x3fb8aa3b, v145
	v_exp_f32_e32 v147, v147
	s_waitcnt lgkmcnt(0)
	v_lshlrev_b32_e32 v146, 16, v146
	v_mul_f32_e32 v146, 0x3db504f3, v146
	v_mul_f32_e32 v146, v147, v146
	v_bfe_u32 v147, v146, 16, 1
	v_add3_u32 v157, v146, v147, s73
	v_or_b32_e32 v146, v142, v72
	v_mov_b32_e32 v147, v143
	v_lshlrev_b64 v[146:147], 8, v[146:147]
	v_or_b32_e32 v146, v146, v144
	v_lshl_add_u64 v[154:155], s[36:37], 0, v[146:147]
	global_store_short_d16_hi v[154:155], v157, off
	v_mul_f32_e32 v154, 0xbfb8aa3b, v145
	v_exp_f32_e32 v154, v154
	v_lshl_add_u64 v[146:147], s[38:39], 0, v[146:147]
	v_mul_f32_e32 v154, v154, v156
	v_bfe_u32 v155, v154, 16, 1
	v_add3_u32 v154, v154, v155, s73
	global_store_short_d16_hi v[146:147], v154, off
	v_sub_f32_e32 v146, v141, v145
	v_mul_f32_e32 v146, 0x3fb8aa3b, v146
	v_exp_f32_e32 v146, v146
	s_nop 0
	v_mul_f32_e32 v146, v146, v156
	v_bfe_u32 v147, v146, 16, 1
	v_add3_u32 v154, v146, v147, s73
	v_lshlrev_b32_e32 v146, 1, v72
	v_mov_b32_e32 v147, v3
	v_lshl_add_u64 v[146:147], v[6:7], 0, v[146:147]
	v_lshrrev_b32_e32 v223, 16, v154
	ds_read_u16 v147, v103 offset:24576
	v_cndmask_b32_e64 v146, v205, v204, s[4:5]
	v_add_f32_e32 v145, v146, v145
	ds_read_u16 v146, v103 offset:8192
	s_waitcnt lgkmcnt(1)
	v_lshlrev_b32_e32 v156, 16, v147
	v_mul_f32_e32 v147, 0x3fb8aa3b, v145
	v_exp_f32_e32 v147, v147
	s_waitcnt lgkmcnt(0)
	v_lshlrev_b32_e32 v146, 16, v146
	v_mul_f32_e32 v146, 0x3db504f3, v146
	v_mul_f32_e32 v146, v147, v146
	v_bfe_u32 v147, v146, 16, 1
	v_add3_u32 v157, v146, v147, s73
	v_or_b32_e32 v146, v142, v74
	v_mov_b32_e32 v147, v143
	v_lshlrev_b64 v[146:147], 8, v[146:147]
	v_or_b32_e32 v146, v146, v144
	v_lshl_add_u64 v[154:155], s[36:37], 0, v[146:147]
	global_store_short_d16_hi v[154:155], v157, off
	v_mul_f32_e32 v154, 0xbfb8aa3b, v145
	v_exp_f32_e32 v154, v154
	v_lshl_add_u64 v[146:147], s[38:39], 0, v[146:147]
	v_mul_f32_e32 v154, v154, v156
	v_bfe_u32 v155, v154, 16, 1
	v_add3_u32 v154, v154, v155, s73
	global_store_short_d16_hi v[146:147], v154, off
	v_sub_f32_e32 v146, v141, v145
	v_mul_f32_e32 v146, 0x3fb8aa3b, v146
	v_exp_f32_e32 v146, v146
	s_nop 0
	v_mul_f32_e32 v146, v146, v156
	v_bfe_u32 v147, v146, 16, 1
	v_add3_u32 v154, v146, v147, s73
	v_lshlrev_b32_e32 v146, 1, v74
	v_mov_b32_e32 v147, v3
	v_lshl_add_u64 v[146:147], v[6:7], 0, v[146:147]
	v_and_or_b32 v223, v154, s98, v223
	v_alignbit_b32 v226, v223, v223, 16
	v_alignbit_b32 v218, v220, v220, 16
	v_cndmask_b32_e64 v220, v226, v220, s[4:5]
	v_cndmask_b32_e64 v223, v218, v223, s[4:5]
	v_alignbit_b32 v226, v222, v222, 16
	v_alignbit_b32 v218, v221, v221, 16
	v_cndmask_b32_e64 v221, v226, v221, s[4:5]
	v_cndmask_b32_e64 v222, v218, v222, s[4:5]
	v_lshl_add_u64 v[218:219], v[146:147], 0, v[224:225]
	global_store_dwordx4 v[218:219], v[220:223], off
	s_nop 1
	ds_read_u16 v147, v105 offset:24576
	v_cndmask_b32_e64 v146, v204, v205, s[4:5]
	v_add_f32_e32 v145, v146, v145
	ds_read_u16 v146, v105 offset:8192
	s_waitcnt lgkmcnt(1)
	v_lshlrev_b32_e32 v156, 16, v147
	v_mul_f32_e32 v147, 0x3fb8aa3b, v145
	v_exp_f32_e32 v147, v147
	s_waitcnt lgkmcnt(0)
	v_lshlrev_b32_e32 v146, 16, v146
	v_mul_f32_e32 v146, 0x3db504f3, v146
	v_mul_f32_e32 v146, v147, v146
	v_bfe_u32 v147, v146, 16, 1
	v_add3_u32 v157, v146, v147, s73
	v_or_b32_e32 v146, v142, v76
	v_mov_b32_e32 v147, v143
	v_lshlrev_b64 v[146:147], 8, v[146:147]
	v_or_b32_e32 v146, v146, v144
	v_lshl_add_u64 v[154:155], s[36:37], 0, v[146:147]
	global_store_short_d16_hi v[154:155], v157, off
	v_mul_f32_e32 v154, 0xbfb8aa3b, v145
	v_exp_f32_e32 v154, v154
	v_lshl_add_u64 v[146:147], s[38:39], 0, v[146:147]
	v_mul_f32_e32 v154, v154, v156
	v_bfe_u32 v155, v154, 16, 1
	v_add3_u32 v154, v154, v155, s73
	global_store_short_d16_hi v[146:147], v154, off
	v_sub_f32_e32 v146, v141, v145
	v_mul_f32_e32 v146, 0x3fb8aa3b, v146
	v_exp_f32_e32 v146, v146
	s_nop 0
	v_mul_f32_e32 v146, v146, v156
	v_bfe_u32 v147, v146, 16, 1
	v_add3_u32 v154, v146, v147, s73
	v_lshlrev_b32_e32 v146, 1, v76
	v_mov_b32_e32 v147, v3
	v_lshl_add_u64 v[146:147], v[6:7], 0, v[146:147]
	v_lshrrev_b32_e32 v220, 16, v154
	ds_read_u16 v147, v107 offset:24576
	v_cndmask_b32_e64 v146, v203, v207, s[4:5]
	v_add_f32_e32 v145, v146, v145
	ds_read_u16 v146, v107 offset:8192
	s_waitcnt lgkmcnt(1)
	v_lshlrev_b32_e32 v156, 16, v147
	v_mul_f32_e32 v147, 0x3fb8aa3b, v145
	v_exp_f32_e32 v147, v147
	s_waitcnt lgkmcnt(0)
	v_lshlrev_b32_e32 v146, 16, v146
	v_mul_f32_e32 v146, 0x3db504f3, v146
	v_mul_f32_e32 v146, v147, v146
	v_bfe_u32 v147, v146, 16, 1
	v_add3_u32 v157, v146, v147, s73
	v_or_b32_e32 v146, v142, v78
	v_mov_b32_e32 v147, v143
	v_lshlrev_b64 v[146:147], 8, v[146:147]
	v_or_b32_e32 v146, v146, v144
	v_lshl_add_u64 v[154:155], s[36:37], 0, v[146:147]
	global_store_short_d16_hi v[154:155], v157, off
	v_mul_f32_e32 v154, 0xbfb8aa3b, v145
	v_exp_f32_e32 v154, v154
	v_lshl_add_u64 v[146:147], s[38:39], 0, v[146:147]
	v_mul_f32_e32 v154, v154, v156
	v_bfe_u32 v155, v154, 16, 1
	v_add3_u32 v154, v154, v155, s73
	global_store_short_d16_hi v[146:147], v154, off
	v_sub_f32_e32 v146, v141, v145
	v_mul_f32_e32 v146, 0x3fb8aa3b, v146
	v_exp_f32_e32 v146, v146
	s_nop 0
	v_mul_f32_e32 v146, v146, v156
	v_bfe_u32 v147, v146, 16, 1
	v_add3_u32 v154, v146, v147, s73
	v_lshlrev_b32_e32 v146, 1, v78
	v_mov_b32_e32 v147, v3
	v_lshl_add_u64 v[146:147], v[6:7], 0, v[146:147]
	v_and_or_b32 v220, v154, s98, v220
	ds_read_u16 v147, v109 offset:24576
	v_cndmask_b32_e64 v146, v202, v210, s[4:5]
	v_add_f32_e32 v145, v146, v145
	ds_read_u16 v146, v109 offset:8192
	s_waitcnt lgkmcnt(1)
	v_lshlrev_b32_e32 v156, 16, v147
	v_mul_f32_e32 v147, 0x3fb8aa3b, v145
	v_exp_f32_e32 v147, v147
	s_waitcnt lgkmcnt(0)
	v_lshlrev_b32_e32 v146, 16, v146
	v_mul_f32_e32 v146, 0x3db504f3, v146
	v_mul_f32_e32 v146, v147, v146
	v_bfe_u32 v147, v146, 16, 1
	v_add3_u32 v157, v146, v147, s73
	v_or_b32_e32 v146, v142, v80
	v_mov_b32_e32 v147, v143
	v_lshlrev_b64 v[146:147], 8, v[146:147]
	v_or_b32_e32 v146, v146, v144
	v_lshl_add_u64 v[154:155], s[36:37], 0, v[146:147]
	global_store_short_d16_hi v[154:155], v157, off
	v_mul_f32_e32 v154, 0xbfb8aa3b, v145
	v_exp_f32_e32 v154, v154
	v_lshl_add_u64 v[146:147], s[38:39], 0, v[146:147]
	v_mul_f32_e32 v154, v154, v156
	v_bfe_u32 v155, v154, 16, 1
	v_add3_u32 v154, v154, v155, s73
	global_store_short_d16_hi v[146:147], v154, off
	v_sub_f32_e32 v146, v141, v145
	v_mul_f32_e32 v146, 0x3fb8aa3b, v146
	v_exp_f32_e32 v146, v146
	s_nop 0
	v_mul_f32_e32 v146, v146, v156
	v_bfe_u32 v147, v146, 16, 1
	v_add3_u32 v154, v146, v147, s73
	v_lshlrev_b32_e32 v146, 1, v80
	v_mov_b32_e32 v147, v3
	v_lshl_add_u64 v[146:147], v[6:7], 0, v[146:147]
	v_lshrrev_b32_e32 v221, 16, v154
	ds_read_u16 v147, v111 offset:24576
	v_cndmask_b32_e64 v146, v201, v212, s[4:5]
	v_add_f32_e32 v145, v146, v145
	ds_read_u16 v146, v111 offset:8192
	s_waitcnt lgkmcnt(1)
	v_lshlrev_b32_e32 v156, 16, v147
	v_mul_f32_e32 v147, 0x3fb8aa3b, v145
	v_exp_f32_e32 v147, v147
	s_waitcnt lgkmcnt(0)
	v_lshlrev_b32_e32 v146, 16, v146
	v_mul_f32_e32 v146, 0x3db504f3, v146
	v_mul_f32_e32 v146, v147, v146
	v_bfe_u32 v147, v146, 16, 1
	v_add3_u32 v157, v146, v147, s73
	v_or_b32_e32 v146, v142, v82
	v_mov_b32_e32 v147, v143
	v_lshlrev_b64 v[146:147], 8, v[146:147]
	v_or_b32_e32 v146, v146, v144
	v_lshl_add_u64 v[154:155], s[36:37], 0, v[146:147]
	global_store_short_d16_hi v[154:155], v157, off
	v_mul_f32_e32 v154, 0xbfb8aa3b, v145
	v_exp_f32_e32 v154, v154
	v_lshl_add_u64 v[146:147], s[38:39], 0, v[146:147]
	v_mul_f32_e32 v154, v154, v156
	v_bfe_u32 v155, v154, 16, 1
	v_add3_u32 v154, v154, v155, s73
	global_store_short_d16_hi v[146:147], v154, off
	v_sub_f32_e32 v146, v141, v145
	v_mul_f32_e32 v146, 0x3fb8aa3b, v146
	v_exp_f32_e32 v146, v146
	s_nop 0
	v_mul_f32_e32 v146, v146, v156
	v_bfe_u32 v147, v146, 16, 1
	v_add3_u32 v154, v146, v147, s73
	v_lshlrev_b32_e32 v146, 1, v82
	v_mov_b32_e32 v147, v3
	v_lshl_add_u64 v[146:147], v[6:7], 0, v[146:147]
	v_and_or_b32 v221, v154, s98, v221
	ds_read_u16 v147, v113 offset:24576
	v_cndmask_b32_e64 v146, v200, v206, s[4:5]
	v_add_f32_e32 v145, v146, v145
	ds_read_u16 v146, v113 offset:8192
	s_waitcnt lgkmcnt(1)
	v_lshlrev_b32_e32 v156, 16, v147
	v_mul_f32_e32 v147, 0x3fb8aa3b, v145
	v_exp_f32_e32 v147, v147
	s_waitcnt lgkmcnt(0)
	v_lshlrev_b32_e32 v146, 16, v146
	v_mul_f32_e32 v146, 0x3db504f3, v146
	v_mul_f32_e32 v146, v147, v146
	v_bfe_u32 v147, v146, 16, 1
	v_add3_u32 v157, v146, v147, s73
	v_or_b32_e32 v146, v142, v84
	v_mov_b32_e32 v147, v143
	v_lshlrev_b64 v[146:147], 8, v[146:147]
	v_or_b32_e32 v146, v146, v144
	v_lshl_add_u64 v[154:155], s[36:37], 0, v[146:147]
	global_store_short_d16_hi v[154:155], v157, off
	v_mul_f32_e32 v154, 0xbfb8aa3b, v145
	v_exp_f32_e32 v154, v154
	v_lshl_add_u64 v[146:147], s[38:39], 0, v[146:147]
	v_mul_f32_e32 v154, v154, v156
	v_bfe_u32 v155, v154, 16, 1
	v_add3_u32 v154, v154, v155, s73
	global_store_short_d16_hi v[146:147], v154, off
	v_sub_f32_e32 v146, v141, v145
	v_mul_f32_e32 v146, 0x3fb8aa3b, v146
	v_exp_f32_e32 v146, v146
	s_nop 0
	v_mul_f32_e32 v146, v146, v156
	v_bfe_u32 v147, v146, 16, 1
	v_add3_u32 v154, v146, v147, s73
	v_lshlrev_b32_e32 v146, 1, v84
	v_mov_b32_e32 v147, v3
	v_lshl_add_u64 v[146:147], v[6:7], 0, v[146:147]
	v_lshrrev_b32_e32 v222, 16, v154
	ds_read_u16 v147, v115 offset:24576
	v_cndmask_b32_e64 v146, v199, v209, s[4:5]
	v_add_f32_e32 v145, v146, v145
	ds_read_u16 v146, v115 offset:8192
	s_waitcnt lgkmcnt(1)
	v_lshlrev_b32_e32 v156, 16, v147
	v_mul_f32_e32 v147, 0x3fb8aa3b, v145
	v_exp_f32_e32 v147, v147
	s_waitcnt lgkmcnt(0)
	v_lshlrev_b32_e32 v146, 16, v146
	v_mul_f32_e32 v146, 0x3db504f3, v146
	v_mul_f32_e32 v146, v147, v146
	v_bfe_u32 v147, v146, 16, 1
	v_add3_u32 v157, v146, v147, s73
	v_or_b32_e32 v146, v142, v86
	v_mov_b32_e32 v147, v143
	v_lshlrev_b64 v[146:147], 8, v[146:147]
	v_or_b32_e32 v146, v146, v144
	v_lshl_add_u64 v[154:155], s[36:37], 0, v[146:147]
	global_store_short_d16_hi v[154:155], v157, off
	v_mul_f32_e32 v154, 0xbfb8aa3b, v145
	v_exp_f32_e32 v154, v154
	v_lshl_add_u64 v[146:147], s[38:39], 0, v[146:147]
	v_mul_f32_e32 v154, v154, v156
	v_bfe_u32 v155, v154, 16, 1
	v_add3_u32 v154, v154, v155, s73
	global_store_short_d16_hi v[146:147], v154, off
	v_sub_f32_e32 v146, v141, v145
	v_mul_f32_e32 v146, 0x3fb8aa3b, v146
	v_exp_f32_e32 v146, v146
	s_nop 0
	v_mul_f32_e32 v146, v146, v156
	v_bfe_u32 v147, v146, 16, 1
	v_add3_u32 v154, v146, v147, s73
	v_lshlrev_b32_e32 v146, 1, v86
	v_mov_b32_e32 v147, v3
	v_lshl_add_u64 v[146:147], v[6:7], 0, v[146:147]
	v_and_or_b32 v222, v154, s98, v222
	ds_read_u16 v147, v117 offset:24576
	v_cndmask_b32_e64 v146, v198, v214, s[4:5]
	v_add_f32_e32 v145, v146, v145
	ds_read_u16 v146, v117 offset:8192
	s_waitcnt lgkmcnt(1)
	v_lshlrev_b32_e32 v156, 16, v147
	v_mul_f32_e32 v147, 0x3fb8aa3b, v145
	v_exp_f32_e32 v147, v147
	s_waitcnt lgkmcnt(0)
	v_lshlrev_b32_e32 v146, 16, v146
	v_mul_f32_e32 v146, 0x3db504f3, v146
	v_mul_f32_e32 v146, v147, v146
	v_bfe_u32 v147, v146, 16, 1
	v_add3_u32 v157, v146, v147, s73
	v_or_b32_e32 v146, v142, v88
	v_mov_b32_e32 v147, v143
	v_lshlrev_b64 v[146:147], 8, v[146:147]
	v_or_b32_e32 v146, v146, v144
	v_lshl_add_u64 v[154:155], s[36:37], 0, v[146:147]
	global_store_short_d16_hi v[154:155], v157, off
	v_mul_f32_e32 v154, 0xbfb8aa3b, v145
	v_exp_f32_e32 v154, v154
	v_lshl_add_u64 v[146:147], s[38:39], 0, v[146:147]
	v_mul_f32_e32 v154, v154, v156
	v_bfe_u32 v155, v154, 16, 1
	v_add3_u32 v154, v154, v155, s73
	global_store_short_d16_hi v[146:147], v154, off
	v_sub_f32_e32 v146, v141, v145
	v_mul_f32_e32 v146, 0x3fb8aa3b, v146
	v_exp_f32_e32 v146, v146
	s_nop 0
	v_mul_f32_e32 v146, v146, v156
	v_bfe_u32 v147, v146, 16, 1
	v_add3_u32 v154, v146, v147, s73
	v_lshlrev_b32_e32 v146, 1, v88
	v_mov_b32_e32 v147, v3
	v_lshl_add_u64 v[146:147], v[6:7], 0, v[146:147]
	v_lshrrev_b32_e32 v223, 16, v154
	ds_read_u16 v147, v119 offset:24576
	v_cndmask_b32_e64 v146, v197, v216, s[4:5]
	v_add_f32_e32 v145, v146, v145
	ds_read_u16 v146, v119 offset:8192
	s_waitcnt lgkmcnt(1)
	v_lshlrev_b32_e32 v156, 16, v147
	v_mul_f32_e32 v147, 0x3fb8aa3b, v145
	v_exp_f32_e32 v147, v147
	s_waitcnt lgkmcnt(0)
	v_lshlrev_b32_e32 v146, 16, v146
	v_mul_f32_e32 v146, 0x3db504f3, v146
	v_mul_f32_e32 v146, v147, v146
	v_bfe_u32 v147, v146, 16, 1
	v_add3_u32 v157, v146, v147, s73
	v_or_b32_e32 v146, v142, v90
	v_mov_b32_e32 v147, v143
	v_lshlrev_b64 v[146:147], 8, v[146:147]
	v_or_b32_e32 v146, v146, v144
	v_lshl_add_u64 v[154:155], s[36:37], 0, v[146:147]
	global_store_short_d16_hi v[154:155], v157, off
	v_mul_f32_e32 v154, 0xbfb8aa3b, v145
	v_exp_f32_e32 v154, v154
	v_lshl_add_u64 v[146:147], s[38:39], 0, v[146:147]
	v_mul_f32_e32 v154, v154, v156
	v_bfe_u32 v155, v154, 16, 1
	v_add3_u32 v154, v154, v155, s73
	global_store_short_d16_hi v[146:147], v154, off
	v_sub_f32_e32 v146, v141, v145
	v_mul_f32_e32 v146, 0x3fb8aa3b, v146
	v_exp_f32_e32 v146, v146
	s_nop 0
	v_mul_f32_e32 v146, v146, v156
	v_bfe_u32 v147, v146, 16, 1
	v_add3_u32 v154, v146, v147, s73
	v_lshlrev_b32_e32 v146, 1, v90
	v_mov_b32_e32 v147, v3
	v_lshl_add_u64 v[146:147], v[6:7], 0, v[146:147]
	v_and_or_b32 v223, v154, s98, v223
	v_alignbit_b32 v226, v223, v223, 16
	v_alignbit_b32 v218, v220, v220, 16
	v_cndmask_b32_e64 v220, v226, v220, s[4:5]
	v_cndmask_b32_e64 v223, v218, v223, s[4:5]
	v_alignbit_b32 v226, v222, v222, 16
	v_alignbit_b32 v218, v221, v221, 16
	v_cndmask_b32_e64 v221, v226, v221, s[4:5]
	v_cndmask_b32_e64 v222, v218, v222, s[4:5]
	v_lshl_add_u64 v[218:219], v[146:147], 0, v[224:225]
	global_store_dwordx4 v[218:219], v[220:223], off
	s_nop 1
	ds_read_u16 v147, v121 offset:24576
	v_cndmask_b32_e64 v146, v196, v208, s[4:5]
	v_add_f32_e32 v145, v146, v145
	ds_read_u16 v146, v121 offset:8192
	s_waitcnt lgkmcnt(1)
	v_lshlrev_b32_e32 v156, 16, v147
	v_mul_f32_e32 v147, 0x3fb8aa3b, v145
	v_exp_f32_e32 v147, v147
	s_waitcnt lgkmcnt(0)
	v_lshlrev_b32_e32 v146, 16, v146
	v_mul_f32_e32 v146, 0x3db504f3, v146
	v_mul_f32_e32 v146, v147, v146
	v_bfe_u32 v147, v146, 16, 1
	v_add3_u32 v157, v146, v147, s73
	v_or_b32_e32 v146, v142, v92
	v_mov_b32_e32 v147, v143
	v_lshlrev_b64 v[146:147], 8, v[146:147]
	v_or_b32_e32 v146, v146, v144
	v_lshl_add_u64 v[154:155], s[36:37], 0, v[146:147]
	global_store_short_d16_hi v[154:155], v157, off
	v_mul_f32_e32 v154, 0xbfb8aa3b, v145
	v_exp_f32_e32 v154, v154
	v_lshl_add_u64 v[146:147], s[38:39], 0, v[146:147]
	v_mul_f32_e32 v154, v154, v156
	v_bfe_u32 v155, v154, 16, 1
	v_add3_u32 v154, v154, v155, s73
	global_store_short_d16_hi v[146:147], v154, off
	v_sub_f32_e32 v146, v141, v145
	v_mul_f32_e32 v146, 0x3fb8aa3b, v146
	v_exp_f32_e32 v146, v146
	s_nop 0
	v_mul_f32_e32 v146, v146, v156
	v_bfe_u32 v147, v146, 16, 1
	v_add3_u32 v154, v146, v147, s73
	v_lshlrev_b32_e32 v146, 1, v92
	v_mov_b32_e32 v147, v3
	v_lshl_add_u64 v[146:147], v[6:7], 0, v[146:147]
	v_lshrrev_b32_e32 v220, 16, v154
	ds_read_u16 v147, v123 offset:24576
	v_cndmask_b32_e64 v146, v195, v213, s[4:5]
	v_add_f32_e32 v145, v146, v145
	ds_read_u16 v146, v123 offset:8192
	s_waitcnt lgkmcnt(1)
	v_lshlrev_b32_e32 v156, 16, v147
	v_mul_f32_e32 v147, 0x3fb8aa3b, v145
	v_exp_f32_e32 v147, v147
	s_waitcnt lgkmcnt(0)
	v_lshlrev_b32_e32 v146, 16, v146
	v_mul_f32_e32 v146, 0x3db504f3, v146
	v_mul_f32_e32 v146, v147, v146
	v_bfe_u32 v147, v146, 16, 1
	v_add3_u32 v157, v146, v147, s73
	v_or_b32_e32 v146, v142, v94
	v_mov_b32_e32 v147, v143
	v_lshlrev_b64 v[146:147], 8, v[146:147]
	v_or_b32_e32 v146, v146, v144
	v_lshl_add_u64 v[154:155], s[36:37], 0, v[146:147]
	global_store_short_d16_hi v[154:155], v157, off
	v_mul_f32_e32 v154, 0xbfb8aa3b, v145
	v_exp_f32_e32 v154, v154
	v_lshl_add_u64 v[146:147], s[38:39], 0, v[146:147]
	v_mul_f32_e32 v154, v154, v156
	v_bfe_u32 v155, v154, 16, 1
	v_add3_u32 v154, v154, v155, s73
	global_store_short_d16_hi v[146:147], v154, off
	v_sub_f32_e32 v146, v141, v145
	v_mul_f32_e32 v146, 0x3fb8aa3b, v146
	v_exp_f32_e32 v146, v146
	s_nop 0
	v_mul_f32_e32 v146, v146, v156
	v_bfe_u32 v147, v146, 16, 1
	v_add3_u32 v154, v146, v147, s73
	v_lshlrev_b32_e32 v146, 1, v94
	v_mov_b32_e32 v147, v3
	v_lshl_add_u64 v[146:147], v[6:7], 0, v[146:147]
	v_and_or_b32 v220, v154, s98, v220
	ds_read_u16 v147, v125 offset:24576
	v_cndmask_b32_e64 v146, v194, v234, s[4:5]
	v_add_f32_e32 v145, v146, v145
	ds_read_u16 v146, v125 offset:8192
	s_waitcnt lgkmcnt(1)
	v_lshlrev_b32_e32 v156, 16, v147
	v_mul_f32_e32 v147, 0x3fb8aa3b, v145
	v_exp_f32_e32 v147, v147
	s_waitcnt lgkmcnt(0)
	v_lshlrev_b32_e32 v146, 16, v146
	v_mul_f32_e32 v146, 0x3db504f3, v146
	v_mul_f32_e32 v146, v147, v146
	v_bfe_u32 v147, v146, 16, 1
	v_add3_u32 v157, v146, v147, s73
	v_or_b32_e32 v146, v142, v96
	v_mov_b32_e32 v147, v143
	v_lshlrev_b64 v[146:147], 8, v[146:147]
	v_or_b32_e32 v146, v146, v144
	v_lshl_add_u64 v[154:155], s[36:37], 0, v[146:147]
	global_store_short_d16_hi v[154:155], v157, off
	v_mul_f32_e32 v154, 0xbfb8aa3b, v145
	v_exp_f32_e32 v154, v154
	v_lshl_add_u64 v[146:147], s[38:39], 0, v[146:147]
	v_mul_f32_e32 v154, v154, v156
	v_bfe_u32 v155, v154, 16, 1
	v_add3_u32 v154, v154, v155, s73
	global_store_short_d16_hi v[146:147], v154, off
	v_sub_f32_e32 v146, v141, v145
	v_mul_f32_e32 v146, 0x3fb8aa3b, v146
	v_exp_f32_e32 v146, v146
	s_nop 0
	v_mul_f32_e32 v146, v146, v156
	v_bfe_u32 v147, v146, 16, 1
	v_add3_u32 v154, v146, v147, s73
	v_lshlrev_b32_e32 v146, 1, v96
	v_mov_b32_e32 v147, v3
	v_lshl_add_u64 v[146:147], v[6:7], 0, v[146:147]
	v_lshrrev_b32_e32 v221, 16, v154
	ds_read_u16 v147, v127 offset:24576
	v_cndmask_b32_e64 v146, v193, v236, s[4:5]
	v_add_f32_e32 v145, v146, v145
	ds_read_u16 v146, v127 offset:8192
	s_waitcnt lgkmcnt(1)
	v_lshlrev_b32_e32 v156, 16, v147
	v_mul_f32_e32 v147, 0x3fb8aa3b, v145
	v_exp_f32_e32 v147, v147
	s_waitcnt lgkmcnt(0)
	v_lshlrev_b32_e32 v146, 16, v146
	v_mul_f32_e32 v146, 0x3db504f3, v146
	v_mul_f32_e32 v146, v147, v146
	v_bfe_u32 v147, v146, 16, 1
	v_add3_u32 v157, v146, v147, s73
	v_or_b32_e32 v146, v142, v98
	v_mov_b32_e32 v147, v143
	v_lshlrev_b64 v[146:147], 8, v[146:147]
	v_or_b32_e32 v146, v146, v144
	v_lshl_add_u64 v[154:155], s[36:37], 0, v[146:147]
	global_store_short_d16_hi v[154:155], v157, off
	v_mul_f32_e32 v154, 0xbfb8aa3b, v145
	v_exp_f32_e32 v154, v154
	v_lshl_add_u64 v[146:147], s[38:39], 0, v[146:147]
	v_mul_f32_e32 v154, v154, v156
	v_bfe_u32 v155, v154, 16, 1
	v_add3_u32 v154, v154, v155, s73
	global_store_short_d16_hi v[146:147], v154, off
	v_sub_f32_e32 v146, v141, v145
	v_mul_f32_e32 v146, 0x3fb8aa3b, v146
	v_exp_f32_e32 v146, v146
	s_nop 0
	v_mul_f32_e32 v146, v146, v156
	v_bfe_u32 v147, v146, 16, 1
	v_add3_u32 v154, v146, v147, s73
	v_lshlrev_b32_e32 v146, 1, v98
	v_mov_b32_e32 v147, v3
	v_lshl_add_u64 v[146:147], v[6:7], 0, v[146:147]
	v_and_or_b32 v221, v154, s98, v221
	ds_read_u16 v147, v129 offset:24576
	v_cndmask_b32_e64 v146, v192, v211, s[4:5]
	v_add_f32_e32 v145, v146, v145
	ds_read_u16 v146, v129 offset:8192
	s_waitcnt lgkmcnt(1)
	v_lshlrev_b32_e32 v156, 16, v147
	v_mul_f32_e32 v147, 0x3fb8aa3b, v145
	v_exp_f32_e32 v147, v147
	s_waitcnt lgkmcnt(0)
	v_lshlrev_b32_e32 v146, 16, v146
	v_mul_f32_e32 v146, 0x3db504f3, v146
	v_mul_f32_e32 v146, v147, v146
	v_bfe_u32 v147, v146, 16, 1
	v_add3_u32 v157, v146, v147, s73
	v_or_b32_e32 v146, v142, v100
	v_mov_b32_e32 v147, v143
	v_lshlrev_b64 v[146:147], 8, v[146:147]
	v_or_b32_e32 v146, v146, v144
	v_lshl_add_u64 v[154:155], s[36:37], 0, v[146:147]
	global_store_short_d16_hi v[154:155], v157, off
	v_mul_f32_e32 v154, 0xbfb8aa3b, v145
	v_exp_f32_e32 v154, v154
	v_lshl_add_u64 v[146:147], s[38:39], 0, v[146:147]
	v_mul_f32_e32 v154, v154, v156
	v_bfe_u32 v155, v154, 16, 1
	v_add3_u32 v154, v154, v155, s73
	global_store_short_d16_hi v[146:147], v154, off
	v_sub_f32_e32 v146, v141, v145
	v_mul_f32_e32 v146, 0x3fb8aa3b, v146
	v_exp_f32_e32 v146, v146
	s_nop 0
	v_mul_f32_e32 v146, v146, v156
	v_bfe_u32 v147, v146, 16, 1
	v_add3_u32 v154, v146, v147, s73
	v_lshlrev_b32_e32 v146, 1, v100
	v_mov_b32_e32 v147, v3
	v_lshl_add_u64 v[146:147], v[6:7], 0, v[146:147]
	v_lshrrev_b32_e32 v222, 16, v154
	ds_read_u16 v147, v131 offset:24576
	v_cndmask_b32_e64 v146, v191, v217, s[4:5]
	v_add_f32_e32 v145, v146, v145
	ds_read_u16 v146, v131 offset:8192
	s_waitcnt lgkmcnt(1)
	v_lshlrev_b32_e32 v156, 16, v147
	v_mul_f32_e32 v147, 0x3fb8aa3b, v145
	v_exp_f32_e32 v147, v147
	s_waitcnt lgkmcnt(0)
	v_lshlrev_b32_e32 v146, 16, v146
	v_mul_f32_e32 v146, 0x3db504f3, v146
	v_mul_f32_e32 v146, v147, v146
	v_bfe_u32 v147, v146, 16, 1
	v_add3_u32 v157, v146, v147, s73
	v_or_b32_e32 v146, v142, v102
	v_mov_b32_e32 v147, v143
	v_lshlrev_b64 v[146:147], 8, v[146:147]
	v_or_b32_e32 v146, v146, v144
	v_lshl_add_u64 v[154:155], s[36:37], 0, v[146:147]
	global_store_short_d16_hi v[154:155], v157, off
	v_mul_f32_e32 v154, 0xbfb8aa3b, v145
	v_exp_f32_e32 v154, v154
	v_lshl_add_u64 v[146:147], s[38:39], 0, v[146:147]
	v_mul_f32_e32 v154, v154, v156
	v_bfe_u32 v155, v154, 16, 1
	v_add3_u32 v154, v154, v155, s73
	global_store_short_d16_hi v[146:147], v154, off
	v_sub_f32_e32 v146, v141, v145
	v_mul_f32_e32 v146, 0x3fb8aa3b, v146
	v_exp_f32_e32 v146, v146
	s_nop 0
	v_mul_f32_e32 v146, v146, v156
	v_bfe_u32 v147, v146, 16, 1
	v_add3_u32 v154, v146, v147, s73
	v_lshlrev_b32_e32 v146, 1, v102
	v_mov_b32_e32 v147, v3
	v_lshl_add_u64 v[146:147], v[6:7], 0, v[146:147]
	v_and_or_b32 v222, v154, s98, v222
	ds_read_u16 v147, v133 offset:24576
	v_cndmask_b32_e64 v146, v190, v238, s[4:5]
	v_add_f32_e32 v145, v146, v145
	ds_read_u16 v146, v133 offset:8192
	s_waitcnt lgkmcnt(1)
	v_lshlrev_b32_e32 v156, 16, v147
	v_mul_f32_e32 v147, 0x3fb8aa3b, v145
	v_exp_f32_e32 v147, v147
	s_waitcnt lgkmcnt(0)
	v_lshlrev_b32_e32 v146, 16, v146
	v_mul_f32_e32 v146, 0x3db504f3, v146
	v_mul_f32_e32 v146, v147, v146
	v_bfe_u32 v147, v146, 16, 1
	v_add3_u32 v157, v146, v147, s73
	v_or_b32_e32 v146, v142, v104
	v_mov_b32_e32 v147, v143
	v_lshlrev_b64 v[146:147], 8, v[146:147]
	v_or_b32_e32 v146, v146, v144
	v_lshl_add_u64 v[154:155], s[36:37], 0, v[146:147]
	global_store_short_d16_hi v[154:155], v157, off
	v_mul_f32_e32 v154, 0xbfb8aa3b, v145
	v_exp_f32_e32 v154, v154
	v_lshl_add_u64 v[146:147], s[38:39], 0, v[146:147]
	v_mul_f32_e32 v154, v154, v156
	v_bfe_u32 v155, v154, 16, 1
	v_add3_u32 v154, v154, v155, s73
	global_store_short_d16_hi v[146:147], v154, off
	v_sub_f32_e32 v146, v141, v145
	v_mul_f32_e32 v146, 0x3fb8aa3b, v146
	v_exp_f32_e32 v146, v146
	s_nop 0
	v_mul_f32_e32 v146, v146, v156
	v_bfe_u32 v147, v146, 16, 1
	v_add3_u32 v154, v146, v147, s73
	v_lshlrev_b32_e32 v146, 1, v104
	v_mov_b32_e32 v147, v3
	v_lshl_add_u64 v[146:147], v[6:7], 0, v[146:147]
	v_lshrrev_b32_e32 v223, 16, v154
	ds_read_u16 v147, v135 offset:24576
	v_cndmask_b32_e64 v146, v189, v240, s[4:5]
	v_add_f32_e32 v145, v146, v145
	ds_read_u16 v146, v135 offset:8192
	s_waitcnt lgkmcnt(1)
	v_lshlrev_b32_e32 v156, 16, v147
	v_mul_f32_e32 v147, 0x3fb8aa3b, v145
	v_exp_f32_e32 v147, v147
	s_waitcnt lgkmcnt(0)
	v_lshlrev_b32_e32 v146, 16, v146
	v_mul_f32_e32 v146, 0x3db504f3, v146
	v_mul_f32_e32 v146, v147, v146
	v_bfe_u32 v147, v146, 16, 1
	v_add3_u32 v157, v146, v147, s73
	v_or_b32_e32 v146, v142, v106
	v_mov_b32_e32 v147, v143
	v_lshlrev_b64 v[146:147], 8, v[146:147]
	v_or_b32_e32 v146, v146, v144
	v_lshl_add_u64 v[154:155], s[36:37], 0, v[146:147]
	global_store_short_d16_hi v[154:155], v157, off
	v_mul_f32_e32 v154, 0xbfb8aa3b, v145
	v_exp_f32_e32 v154, v154
	v_lshl_add_u64 v[146:147], s[38:39], 0, v[146:147]
	v_mul_f32_e32 v154, v154, v156
	v_bfe_u32 v155, v154, 16, 1
	v_add3_u32 v154, v154, v155, s73
	global_store_short_d16_hi v[146:147], v154, off
	v_sub_f32_e32 v146, v141, v145
	v_mul_f32_e32 v146, 0x3fb8aa3b, v146
	v_exp_f32_e32 v146, v146
	s_nop 0
	v_mul_f32_e32 v146, v146, v156
	v_bfe_u32 v147, v146, 16, 1
	v_add3_u32 v154, v146, v147, s73
	v_lshlrev_b32_e32 v146, 1, v106
	v_mov_b32_e32 v147, v3
	v_lshl_add_u64 v[146:147], v[6:7], 0, v[146:147]
	v_and_or_b32 v223, v154, s98, v223
	v_alignbit_b32 v226, v223, v223, 16
	v_alignbit_b32 v218, v220, v220, 16
	v_cndmask_b32_e64 v220, v226, v220, s[4:5]
	v_cndmask_b32_e64 v223, v218, v223, s[4:5]
	v_alignbit_b32 v226, v222, v222, 16
	v_alignbit_b32 v218, v221, v221, 16
	v_cndmask_b32_e64 v221, v226, v221, s[4:5]
	v_cndmask_b32_e64 v222, v218, v222, s[4:5]
	v_lshl_add_u64 v[218:219], v[146:147], 0, v[224:225]
	global_store_dwordx4 v[218:219], v[220:223], off
	s_nop 1
	ds_read_u16 v147, v137 offset:24576
	v_cndmask_b32_e64 v146, v188, v215, s[4:5]
	v_add_f32_e32 v145, v146, v145
	ds_read_u16 v146, v137 offset:8192
	s_waitcnt lgkmcnt(1)
	v_lshlrev_b32_e32 v156, 16, v147
	v_mul_f32_e32 v147, 0x3fb8aa3b, v145
	v_exp_f32_e32 v147, v147
	s_waitcnt lgkmcnt(0)
	v_lshlrev_b32_e32 v146, 16, v146
	v_mul_f32_e32 v146, 0x3db504f3, v146
	v_mul_f32_e32 v146, v147, v146
	v_bfe_u32 v147, v146, 16, 1
	v_add3_u32 v157, v146, v147, s73
	v_or_b32_e32 v146, v142, v108
	v_mov_b32_e32 v147, v143
	v_lshlrev_b64 v[146:147], 8, v[146:147]
	v_or_b32_e32 v146, v146, v144
	v_lshl_add_u64 v[154:155], s[36:37], 0, v[146:147]
	global_store_short_d16_hi v[154:155], v157, off
	v_mul_f32_e32 v154, 0xbfb8aa3b, v145
	v_exp_f32_e32 v154, v154
	v_lshl_add_u64 v[146:147], s[38:39], 0, v[146:147]
	v_mul_f32_e32 v154, v154, v156
	v_bfe_u32 v155, v154, 16, 1
	v_add3_u32 v154, v154, v155, s73
	global_store_short_d16_hi v[146:147], v154, off
	v_sub_f32_e32 v146, v141, v145
	v_mul_f32_e32 v146, 0x3fb8aa3b, v146
	v_exp_f32_e32 v146, v146
	s_nop 0
	v_mul_f32_e32 v146, v146, v156
	v_bfe_u32 v147, v146, 16, 1
	v_add3_u32 v154, v146, v147, s73
	v_lshlrev_b32_e32 v146, 1, v108
	v_mov_b32_e32 v147, v3
	v_lshl_add_u64 v[146:147], v[6:7], 0, v[146:147]
	v_lshrrev_b32_e32 v220, 16, v154
	ds_read_u16 v147, v139 offset:24576
	v_cndmask_b32_e64 v146, v187, v237, s[4:5]
	v_add_f32_e32 v145, v146, v145
	ds_read_u16 v146, v139 offset:8192
	s_waitcnt lgkmcnt(1)
	v_lshlrev_b32_e32 v156, 16, v147
	v_mul_f32_e32 v147, 0x3fb8aa3b, v145
	v_exp_f32_e32 v147, v147
	s_waitcnt lgkmcnt(0)
	v_lshlrev_b32_e32 v146, 16, v146
	v_mul_f32_e32 v146, 0x3db504f3, v146
	v_mul_f32_e32 v146, v147, v146
	v_bfe_u32 v147, v146, 16, 1
	v_add3_u32 v157, v146, v147, s73
	v_or_b32_e32 v146, v142, v110
	v_mov_b32_e32 v147, v143
	v_lshlrev_b64 v[146:147], 8, v[146:147]
	v_or_b32_e32 v146, v146, v144
	v_lshl_add_u64 v[154:155], s[36:37], 0, v[146:147]
	global_store_short_d16_hi v[154:155], v157, off
	v_mul_f32_e32 v154, 0xbfb8aa3b, v145
	v_exp_f32_e32 v154, v154
	v_lshl_add_u64 v[146:147], s[38:39], 0, v[146:147]
	v_mul_f32_e32 v154, v154, v156
	v_bfe_u32 v155, v154, 16, 1
	v_add3_u32 v154, v154, v155, s73
	global_store_short_d16_hi v[146:147], v154, off
	v_sub_f32_e32 v146, v141, v145
	v_mul_f32_e32 v146, 0x3fb8aa3b, v146
	v_exp_f32_e32 v146, v146
	s_nop 0
	v_mul_f32_e32 v146, v146, v156
	v_bfe_u32 v147, v146, 16, 1
	v_add3_u32 v154, v146, v147, s73
	v_lshlrev_b32_e32 v146, 1, v110
	v_mov_b32_e32 v147, v3
	v_lshl_add_u64 v[146:147], v[6:7], 0, v[146:147]
	v_and_or_b32 v220, v154, s98, v220
	ds_read_u16 v147, v148 offset:24576
	v_cndmask_b32_e64 v146, v186, v242, s[4:5]
	v_add_f32_e32 v145, v146, v145
	ds_read_u16 v146, v148 offset:8192
	s_waitcnt lgkmcnt(1)
	v_lshlrev_b32_e32 v156, 16, v147
	v_mul_f32_e32 v147, 0x3fb8aa3b, v145
	v_exp_f32_e32 v147, v147
	s_waitcnt lgkmcnt(0)
	v_lshlrev_b32_e32 v146, 16, v146
	v_mul_f32_e32 v146, 0x3db504f3, v146
	v_mul_f32_e32 v146, v147, v146
	v_bfe_u32 v147, v146, 16, 1
	v_add3_u32 v157, v146, v147, s73
	v_or_b32_e32 v146, v142, v112
	v_mov_b32_e32 v147, v143
	v_lshlrev_b64 v[146:147], 8, v[146:147]
	v_or_b32_e32 v146, v146, v144
	v_lshl_add_u64 v[154:155], s[36:37], 0, v[146:147]
	global_store_short_d16_hi v[154:155], v157, off
	v_mul_f32_e32 v154, 0xbfb8aa3b, v145
	v_exp_f32_e32 v154, v154
	v_lshl_add_u64 v[146:147], s[38:39], 0, v[146:147]
	v_mul_f32_e32 v154, v154, v156
	v_bfe_u32 v155, v154, 16, 1
	v_add3_u32 v154, v154, v155, s73
	global_store_short_d16_hi v[146:147], v154, off
	v_sub_f32_e32 v146, v141, v145
	v_mul_f32_e32 v146, 0x3fb8aa3b, v146
	v_exp_f32_e32 v146, v146
	s_nop 0
	v_mul_f32_e32 v146, v146, v156
	v_bfe_u32 v147, v146, 16, 1
	v_add3_u32 v154, v146, v147, s73
	v_lshlrev_b32_e32 v146, 1, v112
	v_mov_b32_e32 v147, v3
	v_lshl_add_u64 v[146:147], v[6:7], 0, v[146:147]
	v_lshrrev_b32_e32 v221, 16, v154
	ds_read_u16 v147, v149 offset:24576
	v_cndmask_b32_e64 v146, v185, v244, s[4:5]
	v_add_f32_e32 v145, v146, v145
	ds_read_u16 v146, v149 offset:8192
	s_waitcnt lgkmcnt(1)
	v_lshlrev_b32_e32 v156, 16, v147
	v_mul_f32_e32 v147, 0x3fb8aa3b, v145
	v_exp_f32_e32 v147, v147
	s_waitcnt lgkmcnt(0)
	v_lshlrev_b32_e32 v146, 16, v146
	v_mul_f32_e32 v146, 0x3db504f3, v146
	v_mul_f32_e32 v146, v147, v146
	v_bfe_u32 v147, v146, 16, 1
	v_add3_u32 v157, v146, v147, s73
	v_or_b32_e32 v146, v142, v114
	v_mov_b32_e32 v147, v143
	v_lshlrev_b64 v[146:147], 8, v[146:147]
	v_or_b32_e32 v146, v146, v144
	v_lshl_add_u64 v[154:155], s[36:37], 0, v[146:147]
	global_store_short_d16_hi v[154:155], v157, off
	v_mul_f32_e32 v154, 0xbfb8aa3b, v145
	v_exp_f32_e32 v154, v154
	v_lshl_add_u64 v[146:147], s[38:39], 0, v[146:147]
	v_mul_f32_e32 v154, v154, v156
	v_bfe_u32 v155, v154, 16, 1
	v_add3_u32 v154, v154, v155, s73
	global_store_short_d16_hi v[146:147], v154, off
	v_sub_f32_e32 v146, v141, v145
	v_mul_f32_e32 v146, 0x3fb8aa3b, v146
	v_exp_f32_e32 v146, v146
	s_nop 0
	v_mul_f32_e32 v146, v146, v156
	v_bfe_u32 v147, v146, 16, 1
	v_add3_u32 v154, v146, v147, s73
	v_lshlrev_b32_e32 v146, 1, v114
	v_mov_b32_e32 v147, v3
	v_lshl_add_u64 v[146:147], v[6:7], 0, v[146:147]
	v_and_or_b32 v221, v154, s98, v221
	ds_read_u16 v147, v150 offset:24576
	v_cndmask_b32_e64 v146, v184, v235, s[4:5]
	v_add_f32_e32 v145, v146, v145
	ds_read_u16 v146, v150 offset:8192
	s_waitcnt lgkmcnt(1)
	v_lshlrev_b32_e32 v156, 16, v147
	v_mul_f32_e32 v147, 0x3fb8aa3b, v145
	v_exp_f32_e32 v147, v147
	s_waitcnt lgkmcnt(0)
	v_lshlrev_b32_e32 v146, 16, v146
	v_mul_f32_e32 v146, 0x3db504f3, v146
	v_mul_f32_e32 v146, v147, v146
	v_bfe_u32 v147, v146, 16, 1
	v_add3_u32 v157, v146, v147, s73
	v_or_b32_e32 v146, v142, v116
	v_mov_b32_e32 v147, v143
	v_lshlrev_b64 v[146:147], 8, v[146:147]
	v_or_b32_e32 v146, v146, v144
	v_lshl_add_u64 v[154:155], s[36:37], 0, v[146:147]
	global_store_short_d16_hi v[154:155], v157, off
	v_mul_f32_e32 v154, 0xbfb8aa3b, v145
	v_exp_f32_e32 v154, v154
	v_lshl_add_u64 v[146:147], s[38:39], 0, v[146:147]
	v_mul_f32_e32 v154, v154, v156
	v_bfe_u32 v155, v154, 16, 1
	v_add3_u32 v154, v154, v155, s73
	global_store_short_d16_hi v[146:147], v154, off
	v_sub_f32_e32 v146, v141, v145
	v_mul_f32_e32 v146, 0x3fb8aa3b, v146
	v_exp_f32_e32 v146, v146
	s_nop 0
	v_mul_f32_e32 v146, v146, v156
	v_bfe_u32 v147, v146, 16, 1
	v_add3_u32 v154, v146, v147, s73
	v_lshlrev_b32_e32 v146, 1, v116
	v_mov_b32_e32 v147, v3
	v_lshl_add_u64 v[146:147], v[6:7], 0, v[146:147]
	v_lshrrev_b32_e32 v222, 16, v154
	ds_read_u16 v147, v151 offset:24576
	v_cndmask_b32_e64 v146, v183, v241, s[4:5]
	v_add_f32_e32 v145, v146, v145
	ds_read_u16 v146, v151 offset:8192
	s_waitcnt lgkmcnt(1)
	v_lshlrev_b32_e32 v156, 16, v147
	v_mul_f32_e32 v147, 0x3fb8aa3b, v145
	v_exp_f32_e32 v147, v147
	s_waitcnt lgkmcnt(0)
	v_lshlrev_b32_e32 v146, 16, v146
	v_mul_f32_e32 v146, 0x3db504f3, v146
	v_mul_f32_e32 v146, v147, v146
	v_bfe_u32 v147, v146, 16, 1
	v_add3_u32 v157, v146, v147, s73
	v_or_b32_e32 v146, v142, v118
	v_mov_b32_e32 v147, v143
	v_lshlrev_b64 v[146:147], 8, v[146:147]
	v_or_b32_e32 v146, v146, v144
	v_lshl_add_u64 v[154:155], s[36:37], 0, v[146:147]
	global_store_short_d16_hi v[154:155], v157, off
	v_mul_f32_e32 v154, 0xbfb8aa3b, v145
	v_exp_f32_e32 v154, v154
	v_lshl_add_u64 v[146:147], s[38:39], 0, v[146:147]
	v_mul_f32_e32 v154, v154, v156
	v_bfe_u32 v155, v154, 16, 1
	v_add3_u32 v154, v154, v155, s73
	global_store_short_d16_hi v[146:147], v154, off
	v_sub_f32_e32 v146, v141, v145
	v_mul_f32_e32 v146, 0x3fb8aa3b, v146
	v_exp_f32_e32 v146, v146
	s_nop 0
	v_mul_f32_e32 v146, v146, v156
	v_bfe_u32 v147, v146, 16, 1
	v_add3_u32 v154, v146, v147, s73
	v_lshlrev_b32_e32 v146, 1, v118
	v_mov_b32_e32 v147, v3
	v_lshl_add_u64 v[146:147], v[6:7], 0, v[146:147]
	v_and_or_b32 v222, v154, s98, v222
	ds_read_u16 v147, v152 offset:24576
	v_cndmask_b32_e64 v146, v182, v246, s[4:5]
	v_add_f32_e32 v145, v146, v145
	ds_read_u16 v146, v152 offset:8192
	s_waitcnt lgkmcnt(1)
	v_lshlrev_b32_e32 v156, 16, v147
	v_mul_f32_e32 v147, 0x3fb8aa3b, v145
	v_exp_f32_e32 v147, v147
	s_waitcnt lgkmcnt(0)
	v_lshlrev_b32_e32 v146, 16, v146
	v_mul_f32_e32 v146, 0x3db504f3, v146
	v_mul_f32_e32 v146, v147, v146
	v_bfe_u32 v147, v146, 16, 1
	v_add3_u32 v157, v146, v147, s73
	v_or_b32_e32 v146, v142, v120
	v_mov_b32_e32 v147, v143
	v_lshlrev_b64 v[146:147], 8, v[146:147]
	v_or_b32_e32 v146, v146, v144
	v_lshl_add_u64 v[154:155], s[36:37], 0, v[146:147]
	global_store_short_d16_hi v[154:155], v157, off
	v_mul_f32_e32 v154, 0xbfb8aa3b, v145
	v_exp_f32_e32 v154, v154
	v_lshl_add_u64 v[146:147], s[38:39], 0, v[146:147]
	v_mul_f32_e32 v154, v154, v156
	v_bfe_u32 v155, v154, 16, 1
	v_add3_u32 v154, v154, v155, s73
	global_store_short_d16_hi v[146:147], v154, off
	v_sub_f32_e32 v146, v141, v145
	v_mul_f32_e32 v146, 0x3fb8aa3b, v146
	v_exp_f32_e32 v146, v146
	s_nop 0
	v_mul_f32_e32 v146, v146, v156
	v_bfe_u32 v147, v146, 16, 1
	v_add3_u32 v154, v146, v147, s73
	v_lshlrev_b32_e32 v146, 1, v120
	v_mov_b32_e32 v147, v3
	v_lshl_add_u64 v[146:147], v[6:7], 0, v[146:147]
	v_lshrrev_b32_e32 v223, 16, v154
	ds_read_u16 v147, v153 offset:24576
	v_cndmask_b32_e64 v146, v181, v247, s[4:5]
	v_add_f32_e32 v145, v146, v145
	ds_read_u16 v146, v153 offset:8192
	s_waitcnt lgkmcnt(1)
	v_lshlrev_b32_e32 v156, 16, v147
	v_mul_f32_e32 v147, 0x3fb8aa3b, v145
	v_exp_f32_e32 v147, v147
	s_waitcnt lgkmcnt(0)
	v_lshlrev_b32_e32 v146, 16, v146
	v_mul_f32_e32 v146, 0x3db504f3, v146
	v_mul_f32_e32 v146, v147, v146
	v_bfe_u32 v147, v146, 16, 1
	v_add3_u32 v157, v146, v147, s73
	v_or_b32_e32 v146, v142, v122
	v_mov_b32_e32 v147, v143
	v_lshlrev_b64 v[146:147], 8, v[146:147]
	v_or_b32_e32 v146, v146, v144
	v_lshl_add_u64 v[154:155], s[36:37], 0, v[146:147]
	global_store_short_d16_hi v[154:155], v157, off
	v_mul_f32_e32 v154, 0xbfb8aa3b, v145
	v_exp_f32_e32 v154, v154
	v_lshl_add_u64 v[146:147], s[38:39], 0, v[146:147]
	v_mul_f32_e32 v154, v154, v156
	v_bfe_u32 v155, v154, 16, 1
	v_add3_u32 v154, v154, v155, s73
	global_store_short_d16_hi v[146:147], v154, off
	v_sub_f32_e32 v146, v141, v145
	v_mul_f32_e32 v146, 0x3fb8aa3b, v146
	v_exp_f32_e32 v146, v146
	s_nop 0
	v_mul_f32_e32 v146, v146, v156
	v_bfe_u32 v147, v146, 16, 1
	v_add3_u32 v154, v146, v147, s73
	v_lshlrev_b32_e32 v146, 1, v122
	v_mov_b32_e32 v147, v3
	v_lshl_add_u64 v[146:147], v[6:7], 0, v[146:147]
	v_and_or_b32 v223, v154, s98, v223
	v_alignbit_b32 v226, v223, v223, 16
	v_alignbit_b32 v218, v220, v220, 16
	v_cndmask_b32_e64 v220, v226, v220, s[4:5]
	v_cndmask_b32_e64 v223, v218, v223, s[4:5]
	v_alignbit_b32 v226, v222, v222, 16
	v_alignbit_b32 v218, v221, v221, 16
	v_cndmask_b32_e64 v221, v226, v221, s[4:5]
	v_cndmask_b32_e64 v222, v218, v222, s[4:5]
	v_lshl_add_u64 v[218:219], v[146:147], 0, v[224:225]
	global_store_dwordx4 v[218:219], v[220:223], off
	s_nop 1
	ds_read_u16 v147, v162 offset:24576
	v_cndmask_b32_e64 v146, v180, v239, s[4:5]
	v_add_f32_e32 v145, v146, v145
	ds_read_u16 v146, v162 offset:8192
	s_waitcnt lgkmcnt(1)
	v_lshlrev_b32_e32 v156, 16, v147
	v_mul_f32_e32 v147, 0x3fb8aa3b, v145
	v_exp_f32_e32 v147, v147
	s_waitcnt lgkmcnt(0)
	v_lshlrev_b32_e32 v146, 16, v146
	v_mul_f32_e32 v146, 0x3db504f3, v146
	v_mul_f32_e32 v146, v147, v146
	v_bfe_u32 v147, v146, 16, 1
	v_add3_u32 v157, v146, v147, s73
	v_or_b32_e32 v146, v142, v124
	v_mov_b32_e32 v147, v143
	v_lshlrev_b64 v[146:147], 8, v[146:147]
	v_or_b32_e32 v146, v146, v144
	v_lshl_add_u64 v[154:155], s[36:37], 0, v[146:147]
	global_store_short_d16_hi v[154:155], v157, off
	v_mul_f32_e32 v154, 0xbfb8aa3b, v145
	v_exp_f32_e32 v154, v154
	v_lshl_add_u64 v[146:147], s[38:39], 0, v[146:147]
	v_mul_f32_e32 v154, v154, v156
	v_bfe_u32 v155, v154, 16, 1
	v_add3_u32 v154, v154, v155, s73
	global_store_short_d16_hi v[146:147], v154, off
	v_sub_f32_e32 v146, v141, v145
	v_mul_f32_e32 v146, 0x3fb8aa3b, v146
	v_exp_f32_e32 v146, v146
	s_nop 0
	v_mul_f32_e32 v146, v146, v156
	v_bfe_u32 v147, v146, 16, 1
	v_add3_u32 v154, v146, v147, s73
	v_lshlrev_b32_e32 v146, 1, v124
	v_mov_b32_e32 v147, v3
	v_lshl_add_u64 v[146:147], v[6:7], 0, v[146:147]
	v_lshrrev_b32_e32 v220, 16, v154
	ds_read_u16 v147, v163 offset:24576
	v_cndmask_b32_e64 v146, v179, v245, s[4:5]
	v_add_f32_e32 v145, v146, v145
	ds_read_u16 v146, v163 offset:8192
	s_waitcnt lgkmcnt(1)
	v_lshlrev_b32_e32 v156, 16, v147
	v_mul_f32_e32 v147, 0x3fb8aa3b, v145
	v_exp_f32_e32 v147, v147
	s_waitcnt lgkmcnt(0)
	v_lshlrev_b32_e32 v146, 16, v146
	v_mul_f32_e32 v146, 0x3db504f3, v146
	v_mul_f32_e32 v146, v147, v146
	v_bfe_u32 v147, v146, 16, 1
	v_add3_u32 v157, v146, v147, s73
	v_or_b32_e32 v146, v142, v126
	v_mov_b32_e32 v147, v143
	v_lshlrev_b64 v[146:147], 8, v[146:147]
	v_or_b32_e32 v146, v146, v144
	v_lshl_add_u64 v[154:155], s[36:37], 0, v[146:147]
	global_store_short_d16_hi v[154:155], v157, off
	v_mul_f32_e32 v154, 0xbfb8aa3b, v145
	v_exp_f32_e32 v154, v154
	v_lshl_add_u64 v[146:147], s[38:39], 0, v[146:147]
	v_mul_f32_e32 v154, v154, v156
	v_bfe_u32 v155, v154, 16, 1
	v_add3_u32 v154, v154, v155, s73
	global_store_short_d16_hi v[146:147], v154, off
	v_sub_f32_e32 v146, v141, v145
	v_mul_f32_e32 v146, 0x3fb8aa3b, v146
	v_exp_f32_e32 v146, v146
	s_nop 0
	v_mul_f32_e32 v146, v146, v156
	v_bfe_u32 v147, v146, 16, 1
	v_add3_u32 v154, v146, v147, s73
	v_lshlrev_b32_e32 v146, 1, v126
	v_mov_b32_e32 v147, v3
	v_lshl_add_u64 v[146:147], v[6:7], 0, v[146:147]
	v_and_or_b32 v220, v154, s98, v220
	ds_read_u16 v147, v164 offset:24576
	v_cndmask_b32_e64 v146, v178, v249, s[4:5]
	v_add_f32_e32 v145, v146, v145
	ds_read_u16 v146, v164 offset:8192
	s_waitcnt lgkmcnt(1)
	v_lshlrev_b32_e32 v156, 16, v147
	v_mul_f32_e32 v147, 0x3fb8aa3b, v145
	v_exp_f32_e32 v147, v147
	s_waitcnt lgkmcnt(0)
	v_lshlrev_b32_e32 v146, 16, v146
	v_mul_f32_e32 v146, 0x3db504f3, v146
	v_mul_f32_e32 v146, v147, v146
	v_bfe_u32 v147, v146, 16, 1
	v_add3_u32 v157, v146, v147, s73
	v_or_b32_e32 v146, v142, v128
	v_mov_b32_e32 v147, v143
	v_lshlrev_b64 v[146:147], 8, v[146:147]
	v_or_b32_e32 v146, v146, v144
	v_lshl_add_u64 v[154:155], s[36:37], 0, v[146:147]
	global_store_short_d16_hi v[154:155], v157, off
	v_mul_f32_e32 v154, 0xbfb8aa3b, v145
	v_exp_f32_e32 v154, v154
	v_lshl_add_u64 v[146:147], s[38:39], 0, v[146:147]
	v_mul_f32_e32 v154, v154, v156
	v_bfe_u32 v155, v154, 16, 1
	v_add3_u32 v154, v154, v155, s73
	global_store_short_d16_hi v[146:147], v154, off
	v_sub_f32_e32 v146, v141, v145
	v_mul_f32_e32 v146, 0x3fb8aa3b, v146
	v_exp_f32_e32 v146, v146
	s_nop 0
	v_mul_f32_e32 v146, v146, v156
	v_bfe_u32 v147, v146, 16, 1
	v_add3_u32 v154, v146, v147, s73
	v_lshlrev_b32_e32 v146, 1, v128
	v_mov_b32_e32 v147, v3
	v_lshl_add_u64 v[146:147], v[6:7], 0, v[146:147]
	v_lshrrev_b32_e32 v221, 16, v154
	ds_read_u16 v147, v165 offset:24576
	v_cndmask_b32_e64 v146, v177, v250, s[4:5]
	v_add_f32_e32 v145, v146, v145
	ds_read_u16 v146, v165 offset:8192
	s_waitcnt lgkmcnt(1)
	v_lshlrev_b32_e32 v156, 16, v147
	v_mul_f32_e32 v147, 0x3fb8aa3b, v145
	v_exp_f32_e32 v147, v147
	s_waitcnt lgkmcnt(0)
	v_lshlrev_b32_e32 v146, 16, v146
	v_mul_f32_e32 v146, 0x3db504f3, v146
	v_mul_f32_e32 v146, v147, v146
	v_bfe_u32 v147, v146, 16, 1
	v_add3_u32 v157, v146, v147, s73
	v_or_b32_e32 v146, v142, v130
	v_mov_b32_e32 v147, v143
	v_lshlrev_b64 v[146:147], 8, v[146:147]
	v_or_b32_e32 v146, v146, v144
	v_lshl_add_u64 v[154:155], s[36:37], 0, v[146:147]
	global_store_short_d16_hi v[154:155], v157, off
	v_mul_f32_e32 v154, 0xbfb8aa3b, v145
	v_exp_f32_e32 v154, v154
	v_lshl_add_u64 v[146:147], s[38:39], 0, v[146:147]
	v_mul_f32_e32 v154, v154, v156
	v_bfe_u32 v155, v154, 16, 1
	v_add3_u32 v154, v154, v155, s73
	global_store_short_d16_hi v[146:147], v154, off
	v_sub_f32_e32 v146, v141, v145
	v_mul_f32_e32 v146, 0x3fb8aa3b, v146
	v_exp_f32_e32 v146, v146
	s_nop 0
	v_mul_f32_e32 v146, v146, v156
	v_bfe_u32 v147, v146, 16, 1
	v_add3_u32 v154, v146, v147, s73
	v_lshlrev_b32_e32 v146, 1, v130
	v_mov_b32_e32 v147, v3
	v_lshl_add_u64 v[146:147], v[6:7], 0, v[146:147]
	v_and_or_b32 v221, v154, s98, v221
	ds_read_u16 v147, v166 offset:24576
	v_cndmask_b32_e64 v146, v176, v243, s[4:5]
	v_add_f32_e32 v145, v146, v145
	ds_read_u16 v146, v166 offset:8192
	s_waitcnt lgkmcnt(1)
	v_lshlrev_b32_e32 v156, 16, v147
	v_mul_f32_e32 v147, 0x3fb8aa3b, v145
	v_exp_f32_e32 v147, v147
	s_waitcnt lgkmcnt(0)
	v_lshlrev_b32_e32 v146, 16, v146
	v_mul_f32_e32 v146, 0x3db504f3, v146
	v_mul_f32_e32 v146, v147, v146
	v_bfe_u32 v147, v146, 16, 1
	v_add3_u32 v157, v146, v147, s73
	v_or_b32_e32 v146, v142, v132
	v_mov_b32_e32 v147, v143
	v_lshlrev_b64 v[146:147], 8, v[146:147]
	v_or_b32_e32 v146, v146, v144
	v_lshl_add_u64 v[154:155], s[36:37], 0, v[146:147]
	global_store_short_d16_hi v[154:155], v157, off
	v_mul_f32_e32 v154, 0xbfb8aa3b, v145
	v_exp_f32_e32 v154, v154
	v_lshl_add_u64 v[146:147], s[38:39], 0, v[146:147]
	v_mul_f32_e32 v154, v154, v156
	v_bfe_u32 v155, v154, 16, 1
	v_add3_u32 v154, v154, v155, s73
	global_store_short_d16_hi v[146:147], v154, off
	v_sub_f32_e32 v146, v141, v145
	v_mul_f32_e32 v146, 0x3fb8aa3b, v146
	v_exp_f32_e32 v146, v146
	s_nop 0
	v_mul_f32_e32 v146, v146, v156
	v_bfe_u32 v147, v146, 16, 1
	v_add3_u32 v154, v146, v147, s73
	v_lshlrev_b32_e32 v146, 1, v132
	v_mov_b32_e32 v147, v3
	v_lshl_add_u64 v[146:147], v[6:7], 0, v[146:147]
	v_lshrrev_b32_e32 v222, 16, v154
	ds_read_u16 v147, v167 offset:24576
	v_cndmask_b32_e64 v146, v175, v248, s[4:5]
	v_add_f32_e32 v145, v146, v145
	ds_read_u16 v146, v167 offset:8192
	s_waitcnt lgkmcnt(1)
	v_lshlrev_b32_e32 v156, 16, v147
	v_mul_f32_e32 v147, 0x3fb8aa3b, v145
	v_exp_f32_e32 v147, v147
	s_waitcnt lgkmcnt(0)
	v_lshlrev_b32_e32 v146, 16, v146
	v_mul_f32_e32 v146, 0x3db504f3, v146
	v_mul_f32_e32 v146, v147, v146
	v_bfe_u32 v147, v146, 16, 1
	v_add3_u32 v157, v146, v147, s73
	v_or_b32_e32 v146, v142, v134
	v_mov_b32_e32 v147, v143
	v_lshlrev_b64 v[146:147], 8, v[146:147]
	v_or_b32_e32 v146, v146, v144
	v_lshl_add_u64 v[154:155], s[36:37], 0, v[146:147]
	global_store_short_d16_hi v[154:155], v157, off
	v_mul_f32_e32 v154, 0xbfb8aa3b, v145
	v_exp_f32_e32 v154, v154
	v_lshl_add_u64 v[146:147], s[38:39], 0, v[146:147]
	v_mul_f32_e32 v154, v154, v156
	v_bfe_u32 v155, v154, 16, 1
	v_add3_u32 v154, v154, v155, s73
	global_store_short_d16_hi v[146:147], v154, off
	v_sub_f32_e32 v146, v141, v145
	v_mul_f32_e32 v146, 0x3fb8aa3b, v146
	v_exp_f32_e32 v146, v146
	s_nop 0
	v_mul_f32_e32 v146, v146, v156
	v_bfe_u32 v147, v146, 16, 1
	v_add3_u32 v154, v146, v147, s73
	v_lshlrev_b32_e32 v146, 1, v134
	v_mov_b32_e32 v147, v3
	v_lshl_add_u64 v[146:147], v[6:7], 0, v[146:147]
	v_and_or_b32 v222, v154, s98, v222
	ds_read_u16 v147, v168 offset:24576
	v_cndmask_b32_e64 v146, v174, v251, s[4:5]
	v_add_f32_e32 v145, v146, v145
	ds_read_u16 v146, v168 offset:8192
	s_waitcnt lgkmcnt(1)
	v_lshlrev_b32_e32 v156, 16, v147
	v_mul_f32_e32 v147, 0x3fb8aa3b, v145
	v_exp_f32_e32 v147, v147
	s_waitcnt lgkmcnt(0)
	v_lshlrev_b32_e32 v146, 16, v146
	v_mul_f32_e32 v146, 0x3db504f3, v146
	v_mul_f32_e32 v146, v147, v146
	v_bfe_u32 v147, v146, 16, 1
	v_add3_u32 v157, v146, v147, s73
	v_or_b32_e32 v146, v142, v136
	v_mov_b32_e32 v147, v143
	v_lshlrev_b64 v[146:147], 8, v[146:147]
	v_or_b32_e32 v146, v146, v144
	v_lshl_add_u64 v[154:155], s[36:37], 0, v[146:147]
	global_store_short_d16_hi v[154:155], v157, off
	v_mul_f32_e32 v154, 0xbfb8aa3b, v145
	v_exp_f32_e32 v154, v154
	v_lshl_add_u64 v[146:147], s[38:39], 0, v[146:147]
	v_or_b32_e32 v142, v142, v138
	v_lshlrev_b64 v[142:143], 8, v[142:143]
	v_mul_f32_e32 v154, v154, v156
	v_bfe_u32 v155, v154, 16, 1
	v_add3_u32 v154, v154, v155, s73
	global_store_short_d16_hi v[146:147], v154, off
	v_sub_f32_e32 v146, v141, v145
	v_mul_f32_e32 v146, 0x3fb8aa3b, v146
	v_exp_f32_e32 v146, v146
	v_or_b32_e32 v142, v142, v144
	v_mul_f32_e32 v146, v146, v156
	v_bfe_u32 v147, v146, 16, 1
	v_add3_u32 v154, v146, v147, s73
	v_lshlrev_b32_e32 v146, 1, v136
	v_mov_b32_e32 v147, v3
	v_lshl_add_u64 v[146:147], v[6:7], 0, v[146:147]
	v_lshrrev_b32_e32 v223, 16, v154
	v_cndmask_b32_e64 v146, v173, v252, s[4:5]
	v_add_f32_e32 v146, v146, v145
	ds_read_u16 v145, v169 offset:8192
	v_mul_f32_e32 v154, 0x3fb8aa3b, v146
	v_exp_f32_e32 v154, v154
	ds_read_u16 v147, v169 offset:24576
	s_waitcnt lgkmcnt(1)
	v_lshlrev_b32_e32 v145, 16, v145
	v_mul_f32_e32 v145, 0x3db504f3, v145
	v_mul_f32_e32 v145, v154, v145
	v_bfe_u32 v154, v145, 16, 1
	v_add3_u32 v154, v145, v154, s73
	v_lshl_add_u64 v[144:145], s[36:37], 0, v[142:143]
	global_store_short_d16_hi v[144:145], v154, off
	v_mul_f32_e32 v144, 0xbfb8aa3b, v146
	v_exp_f32_e32 v144, v144
	s_waitcnt lgkmcnt(0)
	v_lshlrev_b32_e32 v147, 16, v147
	v_lshl_add_u64 v[142:143], s[38:39], 0, v[142:143]
	v_mul_f32_e32 v144, v144, v147
	v_bfe_u32 v145, v144, 16, 1
	v_add3_u32 v144, v144, v145, s73
	global_store_short_d16_hi v[142:143], v144, off
	v_sub_f32_e32 v142, v141, v146
	v_mul_f32_e32 v142, 0x3fb8aa3b, v142
	v_exp_f32_e32 v142, v142
	s_nop 0
	v_mul_f32_e32 v142, v142, v147
	v_bfe_u32 v143, v142, 16, 1
	v_add3_u32 v144, v142, v143, s73
	v_lshlrev_b32_e32 v142, 1, v138
	v_mov_b32_e32 v143, v3
	v_lshl_add_u64 v[6:7], v[6:7], 0, v[142:143]
	v_and_or_b32 v223, v144, s98, v223
	v_alignbit_b32 v226, v223, v223, 16
	v_alignbit_b32 v218, v220, v220, 16
	v_cndmask_b32_e64 v220, v226, v220, s[4:5]
	v_cndmask_b32_e64 v223, v218, v223, s[4:5]
	v_alignbit_b32 v226, v222, v222, 16
	v_alignbit_b32 v218, v221, v221, 16
	v_cndmask_b32_e64 v221, v226, v221, s[4:5]
	v_cndmask_b32_e64 v222, v218, v222, s[4:5]
	v_lshl_add_u64 v[218:219], v[6:7], 0, v[224:225]
	global_store_dwordx4 v[218:219], v[220:223], off
	s_nop 1
	v_and_b32_e32 v227, 0xff, v0
	v_lshrrev_b32_e32 v228, 8, v0
	v_lshlrev_b32_e32 v227, 2, v227
	v_lshl_add_u32 v227, v228, 16, v227
	ds_read_b32 v218, v227 offset:40960
	ds_read_b32 v219, v227 offset:41984
	ds_read_b32 v220, v227 offset:43008
	ds_read_b32 v221, v227 offset:44032
	ds_read_b32 v222, v227 offset:45056
	ds_read_b32 v223, v227 offset:46080
	ds_read_b32 v224, v227 offset:47104
	ds_read_b32 v225, v227 offset:48128
	ds_read_b32 v226, v227 offset:49152
	s_waitcnt lgkmcnt(0)
	v_mul_f32_e32 v6, 0x3fb8aa3b, v141
	v_exp_f32_e32 v6, v6
	global_store_dword v[4:5], v6, off
	s_andn2_b64 exec, exec, s[12:13]
	s_cbranch_execnz .LBB0_759
